# K-loop burst head: s_setprio 1 moved before the pre-MMA barrier and the redundant lgkmcnt(0) after it removed (60 sites)
# speedup vs baseline: 1.0603x; 1.0024x over previous
.LBB0_197:
	ds_read_b128 v[104:107], v171
	ds_read_b128 v[108:111], v171 offset:1024
	ds_read_b128 v[120:123], v171 offset:2048
	ds_read_b128 v[124:127], v171 offset:3072
	ds_read_b128 v[160:163], v172
	ds_read_b128 v[176:179], v172 offset:1024
	ds_read_b128 v[180:183], v172 offset:2048
	ds_read_b128 v[184:187], v172 offset:3072
	s_add_u32 s54, s52, 0xfffc0080
	s_addc_u32 s55, s53, -1
	s_cmp_eq_u32 s88, 12
	s_cselect_b32 s57, s9, s55
	s_cselect_b32 s56, s45, s54
	s_cselect_b32 s55, s43, s87
	s_cselect_b32 s54, s51, s86
	v_lshl_add_u64 v[164:165], s[52:53], 0, v[152:153]
	s_add_i32 m0, s64, 0xc000
	ds_read_b128 v[188:191], v173
	ds_read_b128 v[192:195], v173 offset:1024
	ds_read_b128 v[196:199], v173 offset:2048
	ds_read_b128 v[200:203], v173 offset:3072
	ds_read_b128 v[204:207], v173 offset:4096
	ds_read_b128 v[212:215], v173 offset:5120
	ds_read_b128 v[216:219], v173 offset:6144
	ds_read_b128 v[220:223], v173 offset:7168
	global_load_lds_dwordx4 v[164:165], off
	v_lshl_add_u64 v[164:165], s[52:53], 0, v[154:155]
	s_add_i32 m0, s64, 0xe000
	s_nop 0
	global_load_lds_dwordx4 v[164:165], off
	s_waitcnt vmcnt(8)
	s_waitcnt lgkmcnt(0)
	s_setprio 1
	s_barrier
	v_mfma_f32_16x16x32_bf16 v[140:143], v[104:107], v[188:191], v[140:143]
	v_mfma_f32_16x16x32_bf16 v[136:139], v[120:123], v[188:191], v[136:139]
	v_mfma_f32_16x16x32_bf16 v[116:119], v[104:107], v[196:199], v[116:119]
	v_mfma_f32_16x16x32_bf16 v[112:115], v[120:123], v[196:199], v[112:115]
	v_mfma_f32_16x16x32_bf16 v[92:95], v[104:107], v[204:207], v[92:95]
	v_mfma_f32_16x16x32_bf16 v[88:91], v[120:123], v[204:207], v[88:91]
	v_mfma_f32_16x16x32_bf16 v[76:79], v[104:107], v[216:219], v[76:79]
	v_mfma_f32_16x16x32_bf16 v[72:75], v[120:123], v[216:219], v[72:75]
	v_mfma_f32_16x16x32_bf16 v[140:143], v[108:111], v[192:195], v[140:143]
	v_mfma_f32_16x16x32_bf16 v[136:139], v[124:127], v[192:195], v[136:139]
	v_mfma_f32_16x16x32_bf16 v[116:119], v[108:111], v[200:203], v[116:119]
	v_mfma_f32_16x16x32_bf16 v[112:115], v[124:127], v[200:203], v[112:115]
	v_mfma_f32_16x16x32_bf16 v[92:95], v[108:111], v[212:215], v[92:95]
	v_mfma_f32_16x16x32_bf16 v[88:91], v[124:127], v[212:215], v[88:91]
	v_mfma_f32_16x16x32_bf16 v[76:79], v[108:111], v[220:223], v[76:79]
	v_mfma_f32_16x16x32_bf16 v[72:75], v[124:127], v[220:223], v[72:75]
	s_setprio 0
	s_setprio 1
	v_mfma_f32_16x16x32_bf16 v[132:135], v[160:163], v[188:191], v[132:135]
	v_mfma_f32_16x16x32_bf16 v[128:131], v[180:183], v[188:191], v[128:131]
	v_mfma_f32_16x16x32_bf16 v[100:103], v[160:163], v[196:199], v[100:103]
	v_mfma_f32_16x16x32_bf16 v[96:99], v[180:183], v[196:199], v[96:99]
	v_mfma_f32_16x16x32_bf16 v[84:87], v[160:163], v[204:207], v[84:87]
	v_mfma_f32_16x16x32_bf16 v[80:83], v[180:183], v[204:207], v[80:83]
	v_mfma_f32_16x16x32_bf16 v[68:71], v[160:163], v[216:219], v[68:71]
	v_mfma_f32_16x16x32_bf16 v[64:67], v[180:183], v[216:219], v[64:67]
	v_mfma_f32_16x16x32_bf16 v[132:135], v[176:179], v[192:195], v[132:135]
	v_mfma_f32_16x16x32_bf16 v[128:131], v[184:187], v[192:195], v[128:131]
	v_mfma_f32_16x16x32_bf16 v[100:103], v[176:179], v[200:203], v[100:103]
	v_mfma_f32_16x16x32_bf16 v[96:99], v[184:187], v[200:203], v[96:99]
	v_mfma_f32_16x16x32_bf16 v[84:87], v[176:179], v[212:215], v[84:87]
	v_mfma_f32_16x16x32_bf16 v[80:83], v[184:187], v[212:215], v[80:83]
	v_mfma_f32_16x16x32_bf16 v[68:71], v[176:179], v[220:223], v[68:71]
	v_mfma_f32_16x16x32_bf16 v[64:67], v[184:187], v[220:223], v[64:67]
	s_setprio 0
	s_barrier
	s_add_i32 s91, s80, s58
	v_lshl_add_u64 v[164:165], s[54:55], 0, v[146:147]
	s_mov_b32 m0, s91
	ds_read_b128 v[188:191], v173 offset:16384
	ds_read_b128 v[192:195], v173 offset:17408
	ds_read_b128 v[196:199], v173 offset:18432
	ds_read_b128 v[200:203], v173 offset:19456
	ds_read_b128 v[204:207], v173 offset:20480
	ds_read_b128 v[212:215], v173 offset:21504
	ds_read_b128 v[216:219], v173 offset:22528
	ds_read_b128 v[220:223], v173 offset:23552
	global_load_lds_dwordx4 v[164:165], off
	s_add_i32 m0, s91, 0x2000
	s_add_u32 s94, s54, 0x40000
	v_lshl_add_u64 v[224:225], s[54:55], 0, v[150:151]
	s_addc_u32 s95, s55, 0
	s_add_i32 s91, s81, s58
	global_load_lds_dwordx4 v[224:225], off
	v_lshl_add_u64 v[226:227], s[94:95], 0, v[146:147]
	s_mov_b32 m0, s91
	v_lshl_add_u64 v[228:229], s[56:57], 0, v[148:149]
	global_load_lds_dwordx4 v[226:227], off
	v_lshl_add_u64 v[226:227], s[94:95], 0, v[150:151]
	s_add_i32 m0, s91, 0x2000
	s_nop 0
	global_load_lds_dwordx4 v[226:227], off
	v_lshl_add_u64 v[226:227], s[56:57], 0, v[144:145]
	s_mov_b32 m0, s64
	s_nop 0
	global_load_lds_dwordx4 v[226:227], off
	s_mov_b32 m0, s65
	s_nop 0
	global_load_lds_dwordx4 v[228:229], off
	s_waitcnt vmcnt(8)
	s_waitcnt lgkmcnt(0)
	s_setprio 1
	s_barrier
	v_mfma_f32_16x16x32_bf16 v[60:63], v[104:107], v[188:191], v[60:63]
	v_mfma_f32_16x16x32_bf16 v[56:59], v[120:123], v[188:191], v[56:59]
	v_mfma_f32_16x16x32_bf16 v[44:47], v[104:107], v[196:199], v[44:47]
	v_mfma_f32_16x16x32_bf16 v[40:43], v[120:123], v[196:199], v[40:43]
	v_mfma_f32_16x16x32_bf16 v[28:31], v[104:107], v[204:207], v[28:31]
	v_mfma_f32_16x16x32_bf16 v[24:27], v[120:123], v[204:207], v[24:27]
	v_mfma_f32_16x16x32_bf16 v[12:15], v[104:107], v[216:219], v[12:15]
	v_mfma_f32_16x16x32_bf16 v[8:11], v[120:123], v[216:219], v[8:11]
	v_mfma_f32_16x16x32_bf16 v[60:63], v[108:111], v[192:195], v[60:63]
	v_mfma_f32_16x16x32_bf16 v[56:59], v[124:127], v[192:195], v[56:59]
	v_mfma_f32_16x16x32_bf16 v[44:47], v[108:111], v[200:203], v[44:47]
	v_mfma_f32_16x16x32_bf16 v[40:43], v[124:127], v[200:203], v[40:43]
	v_mfma_f32_16x16x32_bf16 v[28:31], v[108:111], v[212:215], v[28:31]
	v_mfma_f32_16x16x32_bf16 v[24:27], v[124:127], v[212:215], v[24:27]
	v_mfma_f32_16x16x32_bf16 v[12:15], v[108:111], v[220:223], v[12:15]
	v_mfma_f32_16x16x32_bf16 v[8:11], v[124:127], v[220:223], v[8:11]
	s_setprio 0
	s_setprio 1
	v_mfma_f32_16x16x32_bf16 v[52:55], v[160:163], v[188:191], v[52:55]
	v_mfma_f32_16x16x32_bf16 v[48:51], v[180:183], v[188:191], v[48:51]
	v_mfma_f32_16x16x32_bf16 v[36:39], v[160:163], v[196:199], v[36:39]
	v_mfma_f32_16x16x32_bf16 v[32:35], v[180:183], v[196:199], v[32:35]
	v_mfma_f32_16x16x32_bf16 v[20:23], v[160:163], v[204:207], v[20:23]
	v_mfma_f32_16x16x32_bf16 v[16:19], v[180:183], v[204:207], v[16:19]
	v_mfma_f32_16x16x32_bf16 v[4:7], v[160:163], v[216:219], v[4:7]
	v_mfma_f32_16x16x32_bf16 v[0:3], v[180:183], v[216:219], v[0:3]
	v_mfma_f32_16x16x32_bf16 v[52:55], v[176:179], v[192:195], v[52:55]
	v_mfma_f32_16x16x32_bf16 v[48:51], v[184:187], v[192:195], v[48:51]
	v_mfma_f32_16x16x32_bf16 v[36:39], v[176:179], v[200:203], v[36:39]
	v_mfma_f32_16x16x32_bf16 v[32:35], v[184:187], v[200:203], v[32:35]
	v_mfma_f32_16x16x32_bf16 v[20:23], v[176:179], v[212:215], v[20:23]
	v_mfma_f32_16x16x32_bf16 v[16:19], v[184:187], v[212:215], v[16:19]
	v_mfma_f32_16x16x32_bf16 v[4:7], v[176:179], v[220:223], v[4:7]
	v_mfma_f32_16x16x32_bf16 v[0:3], v[184:187], v[220:223], v[0:3]
	s_setprio 0
	s_barrier
	s_add_i32 s91, 0, 0x18000
	s_add_i32 s92, 0, 0x1c000
	v_add_u32_e32 v124, s91, v168
	v_add_u32_e32 v166, s92, v168
	ds_read_b128 v[104:107], v124
	ds_read_b128 v[108:111], v124 offset:1024
	ds_read_b128 v[120:123], v124 offset:2048
	ds_read_b128 v[124:127], v124 offset:3072
	ds_read_b128 v[160:163], v166
	ds_read_b128 v[176:179], v166 offset:1024
	ds_read_b128 v[180:183], v166 offset:2048
	ds_read_b128 v[184:187], v166 offset:3072
	s_add_u32 s56, s56, 0x40000
	s_addc_u32 s57, s57, 0
	s_mov_b32 m0, s66
	v_lshl_add_u64 v[230:231], s[56:57], 0, v[144:145]
	ds_read_b128 v[188:191], v173 offset:32768
	ds_read_b128 v[192:195], v173 offset:33792
	ds_read_b128 v[196:199], v173 offset:34816
	ds_read_b128 v[200:203], v173 offset:35840
	ds_read_b128 v[204:207], v173 offset:36864
	ds_read_b128 v[212:215], v173 offset:37888
	ds_read_b128 v[216:219], v173 offset:38912
	ds_read_b128 v[220:223], v173 offset:39936
	global_load_lds_dwordx4 v[230:231], off
	v_lshl_add_u64 v[230:231], s[56:57], 0, v[148:149]
	s_mov_b32 m0, s67
	s_nop 0
	global_load_lds_dwordx4 v[230:231], off
	s_waitcnt vmcnt(8)
	s_waitcnt lgkmcnt(0)
	s_setprio 1
	s_barrier
	v_mfma_f32_16x16x32_bf16 v[140:143], v[104:107], v[188:191], v[140:143]
	v_mfma_f32_16x16x32_bf16 v[136:139], v[120:123], v[188:191], v[136:139]
	v_mfma_f32_16x16x32_bf16 v[116:119], v[104:107], v[196:199], v[116:119]
	v_mfma_f32_16x16x32_bf16 v[112:115], v[120:123], v[196:199], v[112:115]
	v_mfma_f32_16x16x32_bf16 v[92:95], v[104:107], v[204:207], v[92:95]
	v_mfma_f32_16x16x32_bf16 v[88:91], v[120:123], v[204:207], v[88:91]
	v_mfma_f32_16x16x32_bf16 v[76:79], v[104:107], v[216:219], v[76:79]
	v_mfma_f32_16x16x32_bf16 v[72:75], v[120:123], v[216:219], v[72:75]
	v_mfma_f32_16x16x32_bf16 v[140:143], v[108:111], v[192:195], v[140:143]
	v_mfma_f32_16x16x32_bf16 v[136:139], v[124:127], v[192:195], v[136:139]
	v_mfma_f32_16x16x32_bf16 v[116:119], v[108:111], v[200:203], v[116:119]
	v_mfma_f32_16x16x32_bf16 v[112:115], v[124:127], v[200:203], v[112:115]
	v_mfma_f32_16x16x32_bf16 v[92:95], v[108:111], v[212:215], v[92:95]
	v_mfma_f32_16x16x32_bf16 v[88:91], v[124:127], v[212:215], v[88:91]
	v_mfma_f32_16x16x32_bf16 v[76:79], v[108:111], v[220:223], v[76:79]
	v_mfma_f32_16x16x32_bf16 v[72:75], v[124:127], v[220:223], v[72:75]
	s_setprio 0
	s_setprio 1
	v_mfma_f32_16x16x32_bf16 v[132:135], v[160:163], v[188:191], v[132:135]
	v_mfma_f32_16x16x32_bf16 v[128:131], v[180:183], v[188:191], v[128:131]
	v_mfma_f32_16x16x32_bf16 v[100:103], v[160:163], v[196:199], v[100:103]
	v_mfma_f32_16x16x32_bf16 v[96:99], v[180:183], v[196:199], v[96:99]
	v_mfma_f32_16x16x32_bf16 v[84:87], v[160:163], v[204:207], v[84:87]
	v_mfma_f32_16x16x32_bf16 v[80:83], v[180:183], v[204:207], v[80:83]
	v_mfma_f32_16x16x32_bf16 v[68:71], v[160:163], v[216:219], v[68:71]
	v_mfma_f32_16x16x32_bf16 v[64:67], v[180:183], v[216:219], v[64:67]
	v_mfma_f32_16x16x32_bf16 v[132:135], v[176:179], v[192:195], v[132:135]
	v_mfma_f32_16x16x32_bf16 v[128:131], v[184:187], v[192:195], v[128:131]
	v_mfma_f32_16x16x32_bf16 v[100:103], v[176:179], v[200:203], v[100:103]
	v_mfma_f32_16x16x32_bf16 v[96:99], v[184:187], v[200:203], v[96:99]
	v_mfma_f32_16x16x32_bf16 v[84:87], v[176:179], v[212:215], v[84:87]
	v_mfma_f32_16x16x32_bf16 v[80:83], v[184:187], v[212:215], v[80:83]
	v_mfma_f32_16x16x32_bf16 v[68:71], v[176:179], v[220:223], v[68:71]
	v_mfma_f32_16x16x32_bf16 v[64:67], v[184:187], v[220:223], v[64:67]
	s_setprio 0
	s_barrier
	s_add_i32 s56, s91, s58
	v_lshl_add_u64 v[164:165], v[164:165], 0, s[14:15]
	s_mov_b32 m0, s56
	ds_read_b128 v[188:191], v173 offset:49152
	ds_read_b128 v[192:195], v173 offset:50176
	ds_read_b128 v[196:199], v173 offset:51200
	ds_read_b128 v[200:203], v173 offset:52224
	ds_read_b128 v[204:207], v173 offset:53248
	ds_read_b128 v[212:215], v173 offset:54272
	ds_read_b128 v[216:219], v173 offset:55296
	ds_read_b128 v[220:223], v173 offset:56320
	global_load_lds_dwordx4 v[164:165], off
	s_add_i32 m0, s56, 0x2000
	s_add_u32 s54, s54, 0x40080
	v_lshl_add_u64 v[164:165], v[224:225], 0, s[14:15]
	s_addc_u32 s55, s55, 0
	s_add_i32 s56, s92, s58
	global_load_lds_dwordx4 v[164:165], off
	v_lshl_add_u64 v[164:165], s[54:55], 0, v[146:147]
	s_mov_b32 m0, s56
	s_nop 0
	global_load_lds_dwordx4 v[164:165], off
	v_lshl_add_u64 v[164:165], s[54:55], 0, v[150:151]
	s_add_i32 m0, s56, 0x2000
	s_nop 0
	global_load_lds_dwordx4 v[164:165], off
	v_lshl_add_u64 v[164:165], v[226:227], 0, s[14:15]
	s_mov_b32 m0, s72
	s_nop 0
	global_load_lds_dwordx4 v[164:165], off
	v_lshl_add_u64 v[164:165], v[228:229], 0, s[14:15]
	s_mov_b32 m0, s73
	s_nop 0
	global_load_lds_dwordx4 v[164:165], off
	s_waitcnt vmcnt(8)
	s_waitcnt lgkmcnt(0)
	s_setprio 1
	s_barrier
	v_mfma_f32_16x16x32_bf16 v[60:63], v[104:107], v[188:191], v[60:63]
	v_mfma_f32_16x16x32_bf16 v[56:59], v[120:123], v[188:191], v[56:59]
	v_mfma_f32_16x16x32_bf16 v[44:47], v[104:107], v[196:199], v[44:47]
	v_mfma_f32_16x16x32_bf16 v[40:43], v[120:123], v[196:199], v[40:43]
	v_mfma_f32_16x16x32_bf16 v[28:31], v[104:107], v[204:207], v[28:31]
	v_mfma_f32_16x16x32_bf16 v[24:27], v[120:123], v[204:207], v[24:27]
	v_mfma_f32_16x16x32_bf16 v[12:15], v[104:107], v[216:219], v[12:15]
	v_mfma_f32_16x16x32_bf16 v[8:11], v[120:123], v[216:219], v[8:11]
	v_mfma_f32_16x16x32_bf16 v[60:63], v[108:111], v[192:195], v[60:63]
	v_mfma_f32_16x16x32_bf16 v[56:59], v[124:127], v[192:195], v[56:59]
	v_mfma_f32_16x16x32_bf16 v[44:47], v[108:111], v[200:203], v[44:47]
	v_mfma_f32_16x16x32_bf16 v[40:43], v[124:127], v[200:203], v[40:43]
	v_mfma_f32_16x16x32_bf16 v[28:31], v[108:111], v[212:215], v[28:31]
	v_mfma_f32_16x16x32_bf16 v[24:27], v[124:127], v[212:215], v[24:27]
	v_mfma_f32_16x16x32_bf16 v[12:15], v[108:111], v[220:223], v[12:15]
	v_mfma_f32_16x16x32_bf16 v[8:11], v[124:127], v[220:223], v[8:11]
	s_setprio 0
	s_setprio 1
	v_mfma_f32_16x16x32_bf16 v[52:55], v[160:163], v[188:191], v[52:55]
	v_mfma_f32_16x16x32_bf16 v[48:51], v[180:183], v[188:191], v[48:51]
	v_mfma_f32_16x16x32_bf16 v[36:39], v[160:163], v[196:199], v[36:39]
	v_mfma_f32_16x16x32_bf16 v[32:35], v[180:183], v[196:199], v[32:35]
	v_mfma_f32_16x16x32_bf16 v[20:23], v[160:163], v[204:207], v[20:23]
	v_mfma_f32_16x16x32_bf16 v[16:19], v[180:183], v[204:207], v[16:19]
	v_mfma_f32_16x16x32_bf16 v[4:7], v[160:163], v[216:219], v[4:7]
	v_mfma_f32_16x16x32_bf16 v[0:3], v[180:183], v[216:219], v[0:3]
	v_mfma_f32_16x16x32_bf16 v[52:55], v[176:179], v[192:195], v[52:55]
	v_mfma_f32_16x16x32_bf16 v[48:51], v[184:187], v[192:195], v[48:51]
	v_mfma_f32_16x16x32_bf16 v[36:39], v[176:179], v[200:203], v[36:39]
	v_mfma_f32_16x16x32_bf16 v[32:35], v[184:187], v[200:203], v[32:35]
	v_mfma_f32_16x16x32_bf16 v[20:23], v[176:179], v[212:215], v[20:23]
	v_mfma_f32_16x16x32_bf16 v[16:19], v[184:187], v[212:215], v[16:19]
	v_mfma_f32_16x16x32_bf16 v[4:7], v[176:179], v[220:223], v[4:7]
	v_mfma_f32_16x16x32_bf16 v[0:3], v[184:187], v[220:223], v[0:3]
	s_setprio 0
	s_barrier
	s_add_i32 s88, s88, 2
	s_add_u32 s52, s52, 0x100
	s_addc_u32 s53, s53, 0
	s_add_u32 s86, s86, 0x100
	s_addc_u32 s87, s87, 0
	s_cmp_gt_u32 s88, 13
	s_cbranch_scc0 .LBB0_197
	s_and_b64 vcc, exec, s[16:17]
	s_cbranch_vccz .LBB0_200
	s_barrier

.LBB0_591:
	ds_read_b128 v[152:155], v179
	ds_read_b128 v[156:159], v179 offset:1024
	ds_read_b128 v[160:163], v179 offset:2048
	ds_read_b128 v[164:167], v179 offset:3072
	ds_read_b128 v[168:171], v180
	ds_read_b128 v[172:175], v180 offset:1024
	ds_read_b128 v[184:187], v180 offset:2048
	ds_read_b128 v[188:191], v180 offset:3072
	s_add_u32 s52, s50, 0xfffc0080
	s_addc_u32 s53, s51, -1
	s_cmp_eq_u32 s75, 12
	s_cselect_b32 s55, s9, s53
	s_cselect_b32 s54, s43, s52
	s_cselect_b32 s53, s41, s74
	s_cselect_b32 s52, s49, s73
	v_lshl_add_u64 v[228:229], s[50:51], 0, v[136:137]
	s_add_i32 m0, s61, 0xc000
	ds_read_b128 v[192:195], v181
	ds_read_b128 v[196:199], v181 offset:1024
	ds_read_b128 v[200:203], v181 offset:2048
	ds_read_b128 v[204:207], v181 offset:3072
	ds_read_b128 v[212:215], v181 offset:4096
	ds_read_b128 v[216:219], v181 offset:5120
	ds_read_b128 v[220:223], v181 offset:6144
	ds_read_b128 v[224:227], v181 offset:7168
	global_load_lds_dwordx4 v[228:229], off
	v_lshl_add_u64 v[228:229], s[50:51], 0, v[138:139]
	s_add_i32 m0, s61, 0xe000
	s_nop 0
	global_load_lds_dwordx4 v[228:229], off
	s_waitcnt vmcnt(8)
	s_waitcnt lgkmcnt(0)
	s_setprio 1
	s_barrier
	v_mfma_f32_16x16x32_bf16 v[124:127], v[152:155], v[192:195], v[124:127]
	v_mfma_f32_16x16x32_bf16 v[120:123], v[160:163], v[192:195], v[120:123]
	v_mfma_f32_16x16x32_bf16 v[108:111], v[152:155], v[200:203], v[108:111]
	v_mfma_f32_16x16x32_bf16 v[104:107], v[160:163], v[200:203], v[104:107]
	v_mfma_f32_16x16x32_bf16 v[92:95], v[152:155], v[212:215], v[92:95]
	v_mfma_f32_16x16x32_bf16 v[88:91], v[160:163], v[212:215], v[88:91]
	v_mfma_f32_16x16x32_bf16 v[76:79], v[152:155], v[220:223], v[76:79]
	v_mfma_f32_16x16x32_bf16 v[72:75], v[160:163], v[220:223], v[72:75]
	v_mfma_f32_16x16x32_bf16 v[124:127], v[156:159], v[196:199], v[124:127]
	v_mfma_f32_16x16x32_bf16 v[120:123], v[164:167], v[196:199], v[120:123]
	v_mfma_f32_16x16x32_bf16 v[108:111], v[156:159], v[204:207], v[108:111]
	v_mfma_f32_16x16x32_bf16 v[104:107], v[164:167], v[204:207], v[104:107]
	v_mfma_f32_16x16x32_bf16 v[92:95], v[156:159], v[216:219], v[92:95]
	v_mfma_f32_16x16x32_bf16 v[88:91], v[164:167], v[216:219], v[88:91]
	v_mfma_f32_16x16x32_bf16 v[76:79], v[156:159], v[224:227], v[76:79]
	v_mfma_f32_16x16x32_bf16 v[72:75], v[164:167], v[224:227], v[72:75]
	s_setprio 0
	s_setprio 1
	v_mfma_f32_16x16x32_bf16 v[116:119], v[168:171], v[192:195], v[116:119]
	v_mfma_f32_16x16x32_bf16 v[112:115], v[184:187], v[192:195], v[112:115]
	v_mfma_f32_16x16x32_bf16 v[100:103], v[168:171], v[200:203], v[100:103]
	v_mfma_f32_16x16x32_bf16 v[96:99], v[184:187], v[200:203], v[96:99]
	v_mfma_f32_16x16x32_bf16 v[84:87], v[168:171], v[212:215], v[84:87]
	v_mfma_f32_16x16x32_bf16 v[80:83], v[184:187], v[212:215], v[80:83]
	v_mfma_f32_16x16x32_bf16 v[68:71], v[168:171], v[220:223], v[68:71]
	v_mfma_f32_16x16x32_bf16 v[64:67], v[184:187], v[220:223], v[64:67]
	v_mfma_f32_16x16x32_bf16 v[116:119], v[172:175], v[196:199], v[116:119]
	v_mfma_f32_16x16x32_bf16 v[112:115], v[188:191], v[196:199], v[112:115]
	v_mfma_f32_16x16x32_bf16 v[100:103], v[172:175], v[204:207], v[100:103]
	v_mfma_f32_16x16x32_bf16 v[96:99], v[188:191], v[204:207], v[96:99]
	v_mfma_f32_16x16x32_bf16 v[84:87], v[172:175], v[216:219], v[84:87]
	v_mfma_f32_16x16x32_bf16 v[80:83], v[188:191], v[216:219], v[80:83]
	v_mfma_f32_16x16x32_bf16 v[68:71], v[172:175], v[224:227], v[68:71]
	v_mfma_f32_16x16x32_bf16 v[64:67], v[188:191], v[224:227], v[64:67]
	s_setprio 0
	s_barrier
	s_add_i32 s76, s71, s60
	v_lshl_add_u64 v[228:229], s[52:53], 0, v[130:131]
	s_mov_b32 m0, s76
	ds_read_b128 v[192:195], v181 offset:16384
	ds_read_b128 v[196:199], v181 offset:17408
	ds_read_b128 v[200:203], v181 offset:18432
	ds_read_b128 v[204:207], v181 offset:19456
	ds_read_b128 v[212:215], v181 offset:20480
	ds_read_b128 v[216:219], v181 offset:21504
	ds_read_b128 v[220:223], v181 offset:22528
	ds_read_b128 v[224:227], v181 offset:23552
	global_load_lds_dwordx4 v[228:229], off
	s_add_i32 m0, s76, 0x2000
	s_add_u32 s76, s52, 0x40000
	v_lshl_add_u64 v[230:231], s[52:53], 0, v[134:135]
	s_addc_u32 s77, s53, 0
	s_add_i32 s78, s72, s60
	global_load_lds_dwordx4 v[230:231], off
	v_lshl_add_u64 v[232:233], s[76:77], 0, v[130:131]
	s_mov_b32 m0, s78
	v_lshl_add_u64 v[234:235], s[54:55], 0, v[132:133]
	global_load_lds_dwordx4 v[232:233], off
	v_lshl_add_u64 v[232:233], s[76:77], 0, v[134:135]
	s_add_i32 m0, s78, 0x2000
	s_nop 0
	global_load_lds_dwordx4 v[232:233], off
	v_lshl_add_u64 v[232:233], s[54:55], 0, v[128:129]
	s_mov_b32 m0, s61
	s_nop 0
	global_load_lds_dwordx4 v[232:233], off
	s_mov_b32 m0, s62
	s_nop 0
	global_load_lds_dwordx4 v[234:235], off
	s_waitcnt vmcnt(8)
	s_waitcnt lgkmcnt(0)
	s_setprio 1
	s_barrier
	v_mfma_f32_16x16x32_bf16 v[60:63], v[152:155], v[192:195], v[60:63]
	v_mfma_f32_16x16x32_bf16 v[56:59], v[160:163], v[192:195], v[56:59]
	v_mfma_f32_16x16x32_bf16 v[44:47], v[152:155], v[200:203], v[44:47]
	v_mfma_f32_16x16x32_bf16 v[40:43], v[160:163], v[200:203], v[40:43]
	v_mfma_f32_16x16x32_bf16 v[28:31], v[152:155], v[212:215], v[28:31]
	v_mfma_f32_16x16x32_bf16 v[24:27], v[160:163], v[212:215], v[24:27]
	v_mfma_f32_16x16x32_bf16 v[12:15], v[152:155], v[220:223], v[12:15]
	v_mfma_f32_16x16x32_bf16 v[8:11], v[160:163], v[220:223], v[8:11]
	v_mfma_f32_16x16x32_bf16 v[60:63], v[156:159], v[196:199], v[60:63]
	v_mfma_f32_16x16x32_bf16 v[56:59], v[164:167], v[196:199], v[56:59]
	v_mfma_f32_16x16x32_bf16 v[44:47], v[156:159], v[204:207], v[44:47]
	v_mfma_f32_16x16x32_bf16 v[40:43], v[164:167], v[204:207], v[40:43]
	v_mfma_f32_16x16x32_bf16 v[28:31], v[156:159], v[216:219], v[28:31]
	v_mfma_f32_16x16x32_bf16 v[24:27], v[164:167], v[216:219], v[24:27]
	v_mfma_f32_16x16x32_bf16 v[12:15], v[156:159], v[224:227], v[12:15]
	v_mfma_f32_16x16x32_bf16 v[8:11], v[164:167], v[224:227], v[8:11]
	s_setprio 0
	s_setprio 1
	v_mfma_f32_16x16x32_bf16 v[52:55], v[168:171], v[192:195], v[52:55]
	v_mfma_f32_16x16x32_bf16 v[48:51], v[184:187], v[192:195], v[48:51]
	v_mfma_f32_16x16x32_bf16 v[36:39], v[168:171], v[200:203], v[36:39]
	v_mfma_f32_16x16x32_bf16 v[32:35], v[184:187], v[200:203], v[32:35]
	v_mfma_f32_16x16x32_bf16 v[20:23], v[168:171], v[212:215], v[20:23]
	v_mfma_f32_16x16x32_bf16 v[16:19], v[184:187], v[212:215], v[16:19]
	v_mfma_f32_16x16x32_bf16 v[4:7], v[168:171], v[220:223], v[4:7]
	v_mfma_f32_16x16x32_bf16 v[0:3], v[184:187], v[220:223], v[0:3]
	v_mfma_f32_16x16x32_bf16 v[52:55], v[172:175], v[196:199], v[52:55]
	v_mfma_f32_16x16x32_bf16 v[48:51], v[188:191], v[196:199], v[48:51]
	v_mfma_f32_16x16x32_bf16 v[36:39], v[172:175], v[204:207], v[36:39]
	v_mfma_f32_16x16x32_bf16 v[32:35], v[188:191], v[204:207], v[32:35]
	v_mfma_f32_16x16x32_bf16 v[20:23], v[172:175], v[216:219], v[20:23]
	v_mfma_f32_16x16x32_bf16 v[16:19], v[188:191], v[216:219], v[16:19]
	v_mfma_f32_16x16x32_bf16 v[4:7], v[172:175], v[224:227], v[4:7]
	v_mfma_f32_16x16x32_bf16 v[0:3], v[188:191], v[224:227], v[0:3]
	s_setprio 0
	s_barrier
	s_add_i32 s76, 0, 0x18000
	s_add_i32 s77, 0, 0x1c000
	v_add_u32_e32 v164, s76, v177
	v_add_u32_e32 v183, s77, v177
	ds_read_b128 v[152:155], v164
	ds_read_b128 v[156:159], v164 offset:1024
	ds_read_b128 v[160:163], v164 offset:2048
	ds_read_b128 v[164:167], v164 offset:3072
	ds_read_b128 v[168:171], v183
	ds_read_b128 v[172:175], v183 offset:1024
	ds_read_b128 v[184:187], v183 offset:2048
	ds_read_b128 v[188:191], v183 offset:3072
	s_add_u32 s54, s54, 0x40000
	s_addc_u32 s55, s55, 0
	s_mov_b32 m0, s63
	v_lshl_add_u64 v[236:237], s[54:55], 0, v[128:129]
	ds_read_b128 v[192:195], v181 offset:32768
	ds_read_b128 v[196:199], v181 offset:33792
	ds_read_b128 v[200:203], v181 offset:34816
	ds_read_b128 v[204:207], v181 offset:35840
	ds_read_b128 v[212:215], v181 offset:36864
	ds_read_b128 v[216:219], v181 offset:37888
	ds_read_b128 v[220:223], v181 offset:38912
	ds_read_b128 v[224:227], v181 offset:39936
	global_load_lds_dwordx4 v[236:237], off
	v_lshl_add_u64 v[236:237], s[54:55], 0, v[132:133]
	s_mov_b32 m0, s64
	s_nop 0
	global_load_lds_dwordx4 v[236:237], off
	s_waitcnt vmcnt(8)
	s_waitcnt lgkmcnt(0)
	s_setprio 1
	s_barrier
	v_mfma_f32_16x16x32_bf16 v[124:127], v[152:155], v[192:195], v[124:127]
	v_mfma_f32_16x16x32_bf16 v[120:123], v[160:163], v[192:195], v[120:123]
	v_mfma_f32_16x16x32_bf16 v[108:111], v[152:155], v[200:203], v[108:111]
	v_mfma_f32_16x16x32_bf16 v[104:107], v[160:163], v[200:203], v[104:107]
	v_mfma_f32_16x16x32_bf16 v[92:95], v[152:155], v[212:215], v[92:95]
	v_mfma_f32_16x16x32_bf16 v[88:91], v[160:163], v[212:215], v[88:91]
	v_mfma_f32_16x16x32_bf16 v[76:79], v[152:155], v[220:223], v[76:79]
	v_mfma_f32_16x16x32_bf16 v[72:75], v[160:163], v[220:223], v[72:75]
	v_mfma_f32_16x16x32_bf16 v[124:127], v[156:159], v[196:199], v[124:127]
	v_mfma_f32_16x16x32_bf16 v[120:123], v[164:167], v[196:199], v[120:123]
	v_mfma_f32_16x16x32_bf16 v[108:111], v[156:159], v[204:207], v[108:111]
	v_mfma_f32_16x16x32_bf16 v[104:107], v[164:167], v[204:207], v[104:107]
	v_mfma_f32_16x16x32_bf16 v[92:95], v[156:159], v[216:219], v[92:95]
	v_mfma_f32_16x16x32_bf16 v[88:91], v[164:167], v[216:219], v[88:91]
	v_mfma_f32_16x16x32_bf16 v[76:79], v[156:159], v[224:227], v[76:79]
	v_mfma_f32_16x16x32_bf16 v[72:75], v[164:167], v[224:227], v[72:75]
	s_setprio 0
	s_setprio 1
	v_mfma_f32_16x16x32_bf16 v[116:119], v[168:171], v[192:195], v[116:119]
	v_mfma_f32_16x16x32_bf16 v[112:115], v[184:187], v[192:195], v[112:115]
	v_mfma_f32_16x16x32_bf16 v[100:103], v[168:171], v[200:203], v[100:103]
	v_mfma_f32_16x16x32_bf16 v[96:99], v[184:187], v[200:203], v[96:99]
	v_mfma_f32_16x16x32_bf16 v[84:87], v[168:171], v[212:215], v[84:87]
	v_mfma_f32_16x16x32_bf16 v[80:83], v[184:187], v[212:215], v[80:83]
	v_mfma_f32_16x16x32_bf16 v[68:71], v[168:171], v[220:223], v[68:71]
	v_mfma_f32_16x16x32_bf16 v[64:67], v[184:187], v[220:223], v[64:67]
	v_mfma_f32_16x16x32_bf16 v[116:119], v[172:175], v[196:199], v[116:119]
	v_mfma_f32_16x16x32_bf16 v[112:115], v[188:191], v[196:199], v[112:115]
	v_mfma_f32_16x16x32_bf16 v[100:103], v[172:175], v[204:207], v[100:103]
	v_mfma_f32_16x16x32_bf16 v[96:99], v[188:191], v[204:207], v[96:99]
	v_mfma_f32_16x16x32_bf16 v[84:87], v[172:175], v[216:219], v[84:87]
	v_mfma_f32_16x16x32_bf16 v[80:83], v[188:191], v[216:219], v[80:83]
	v_mfma_f32_16x16x32_bf16 v[68:71], v[172:175], v[224:227], v[68:71]
	v_mfma_f32_16x16x32_bf16 v[64:67], v[188:191], v[224:227], v[64:67]
	s_setprio 0
	s_barrier
	s_add_i32 s54, s76, s60
	v_lshl_add_u64 v[228:229], v[228:229], 0, s[24:25]
	s_mov_b32 m0, s54
	ds_read_b128 v[192:195], v181 offset:49152
	ds_read_b128 v[196:199], v181 offset:50176
	ds_read_b128 v[200:203], v181 offset:51200
	ds_read_b128 v[204:207], v181 offset:52224
	ds_read_b128 v[212:215], v181 offset:53248
	ds_read_b128 v[216:219], v181 offset:54272
	ds_read_b128 v[220:223], v181 offset:55296
	ds_read_b128 v[224:227], v181 offset:56320
	global_load_lds_dwordx4 v[228:229], off
	s_add_i32 m0, s54, 0x2000
	s_add_u32 s52, s52, 0x40080
	v_lshl_add_u64 v[228:229], v[230:231], 0, s[24:25]
	s_addc_u32 s53, s53, 0
	s_add_i32 s54, s77, s60
	global_load_lds_dwordx4 v[228:229], off
	v_lshl_add_u64 v[228:229], s[52:53], 0, v[130:131]
	s_mov_b32 m0, s54
	s_nop 0
	global_load_lds_dwordx4 v[228:229], off
	v_lshl_add_u64 v[228:229], s[52:53], 0, v[134:135]
	s_add_i32 m0, s54, 0x2000
	s_nop 0
	global_load_lds_dwordx4 v[228:229], off
	v_lshl_add_u64 v[228:229], v[232:233], 0, s[24:25]
	s_mov_b32 m0, s66
	s_nop 0
	global_load_lds_dwordx4 v[228:229], off
	v_lshl_add_u64 v[228:229], v[234:235], 0, s[24:25]
	s_mov_b32 m0, s67
	s_nop 0
	global_load_lds_dwordx4 v[228:229], off
	s_waitcnt vmcnt(8)
	s_waitcnt lgkmcnt(0)
	s_setprio 1
	s_barrier
	v_mfma_f32_16x16x32_bf16 v[60:63], v[152:155], v[192:195], v[60:63]
	v_mfma_f32_16x16x32_bf16 v[56:59], v[160:163], v[192:195], v[56:59]
	v_mfma_f32_16x16x32_bf16 v[44:47], v[152:155], v[200:203], v[44:47]
	v_mfma_f32_16x16x32_bf16 v[40:43], v[160:163], v[200:203], v[40:43]
	v_mfma_f32_16x16x32_bf16 v[28:31], v[152:155], v[212:215], v[28:31]
	v_mfma_f32_16x16x32_bf16 v[24:27], v[160:163], v[212:215], v[24:27]
	v_mfma_f32_16x16x32_bf16 v[12:15], v[152:155], v[220:223], v[12:15]
	v_mfma_f32_16x16x32_bf16 v[8:11], v[160:163], v[220:223], v[8:11]
	v_mfma_f32_16x16x32_bf16 v[60:63], v[156:159], v[196:199], v[60:63]
	v_mfma_f32_16x16x32_bf16 v[56:59], v[164:167], v[196:199], v[56:59]
	v_mfma_f32_16x16x32_bf16 v[44:47], v[156:159], v[204:207], v[44:47]
	v_mfma_f32_16x16x32_bf16 v[40:43], v[164:167], v[204:207], v[40:43]
	v_mfma_f32_16x16x32_bf16 v[28:31], v[156:159], v[216:219], v[28:31]
	v_mfma_f32_16x16x32_bf16 v[24:27], v[164:167], v[216:219], v[24:27]
	v_mfma_f32_16x16x32_bf16 v[12:15], v[156:159], v[224:227], v[12:15]
	v_mfma_f32_16x16x32_bf16 v[8:11], v[164:167], v[224:227], v[8:11]
	s_setprio 0
	s_setprio 1
	v_mfma_f32_16x16x32_bf16 v[52:55], v[168:171], v[192:195], v[52:55]
	v_mfma_f32_16x16x32_bf16 v[48:51], v[184:187], v[192:195], v[48:51]
	v_mfma_f32_16x16x32_bf16 v[36:39], v[168:171], v[200:203], v[36:39]
	v_mfma_f32_16x16x32_bf16 v[32:35], v[184:187], v[200:203], v[32:35]
	v_mfma_f32_16x16x32_bf16 v[20:23], v[168:171], v[212:215], v[20:23]
	v_mfma_f32_16x16x32_bf16 v[16:19], v[184:187], v[212:215], v[16:19]
	v_mfma_f32_16x16x32_bf16 v[4:7], v[168:171], v[220:223], v[4:7]
	v_mfma_f32_16x16x32_bf16 v[0:3], v[184:187], v[220:223], v[0:3]
	v_mfma_f32_16x16x32_bf16 v[52:55], v[172:175], v[196:199], v[52:55]
	v_mfma_f32_16x16x32_bf16 v[48:51], v[188:191], v[196:199], v[48:51]
	v_mfma_f32_16x16x32_bf16 v[36:39], v[172:175], v[204:207], v[36:39]
	v_mfma_f32_16x16x32_bf16 v[32:35], v[188:191], v[204:207], v[32:35]
	v_mfma_f32_16x16x32_bf16 v[20:23], v[172:175], v[216:219], v[20:23]
	v_mfma_f32_16x16x32_bf16 v[16:19], v[188:191], v[216:219], v[16:19]
	v_mfma_f32_16x16x32_bf16 v[4:7], v[172:175], v[224:227], v[4:7]
	v_mfma_f32_16x16x32_bf16 v[0:3], v[188:191], v[224:227], v[0:3]
	s_setprio 0
	s_barrier
	s_add_i32 s75, s75, 2
	s_add_u32 s50, s50, 0x100
	s_addc_u32 s51, s51, 0
	s_add_u32 s73, s73, 0x100
	s_addc_u32 s74, s74, 0
	s_cmp_gt_u32 s75, 13
	s_cbranch_scc0 .LBB0_591
	s_and_b64 vcc, exec, s[36:37]
	s_cbranch_vccz .LBB0_594
	s_barrier

.LBB0_702:
	ds_read_b128 v[152:155], v149
	ds_read_b128 v[156:159], v149 offset:1024
	ds_read_b128 v[160:163], v149 offset:2048
	ds_read_b128 v[164:167], v149 offset:3072
	ds_read_b128 v[168:171], v150
	ds_read_b128 v[172:175], v150 offset:1024
	ds_read_b128 v[176:179], v150 offset:2048
	ds_read_b128 v[180:183], v150 offset:3072
	s_add_u32 s46, s44, 0xfffc0080
	s_addc_u32 s47, s45, -1
	s_cmp_eq_u32 s75, 12
	s_cselect_b32 s49, s37, s47
	s_cselect_b32 s48, s71, s46
	s_cselect_b32 s47, s25, s74
	s_cselect_b32 s46, s72, s73
	v_lshl_add_u64 v[144:145], s[44:45], 0, v[136:137]
	s_add_i32 m0, s43, 0xc000
	ds_read_b128 v[184:187], v151
	ds_read_b128 v[188:191], v151 offset:1024
	ds_read_b128 v[192:195], v151 offset:2048
	ds_read_b128 v[196:199], v151 offset:3072
	ds_read_b128 v[200:203], v151 offset:4096
	ds_read_b128 v[204:207], v151 offset:5120
	ds_read_b128 v[212:215], v151 offset:6144
	ds_read_b128 v[216:219], v151 offset:7168
	global_load_lds_dwordx4 v[144:145], off
	v_lshl_add_u64 v[144:145], s[44:45], 0, v[138:139]
	s_add_i32 m0, s43, 0xe000
	s_nop 0
	global_load_lds_dwordx4 v[144:145], off
	s_waitcnt vmcnt(8)
	s_waitcnt lgkmcnt(0)
	s_setprio 1
	s_barrier
	v_mfma_f32_16x16x32_bf16 v[124:127], v[152:155], v[184:187], v[124:127]
	v_mfma_f32_16x16x32_bf16 v[120:123], v[160:163], v[184:187], v[120:123]
	v_mfma_f32_16x16x32_bf16 v[108:111], v[152:155], v[192:195], v[108:111]
	v_mfma_f32_16x16x32_bf16 v[104:107], v[160:163], v[192:195], v[104:107]
	v_mfma_f32_16x16x32_bf16 v[92:95], v[152:155], v[200:203], v[92:95]
	v_mfma_f32_16x16x32_bf16 v[88:91], v[160:163], v[200:203], v[88:91]
	v_mfma_f32_16x16x32_bf16 v[76:79], v[152:155], v[212:215], v[76:79]
	v_mfma_f32_16x16x32_bf16 v[72:75], v[160:163], v[212:215], v[72:75]
	v_mfma_f32_16x16x32_bf16 v[124:127], v[156:159], v[188:191], v[124:127]
	v_mfma_f32_16x16x32_bf16 v[120:123], v[164:167], v[188:191], v[120:123]
	v_mfma_f32_16x16x32_bf16 v[108:111], v[156:159], v[196:199], v[108:111]
	v_mfma_f32_16x16x32_bf16 v[104:107], v[164:167], v[196:199], v[104:107]
	v_mfma_f32_16x16x32_bf16 v[92:95], v[156:159], v[204:207], v[92:95]
	v_mfma_f32_16x16x32_bf16 v[88:91], v[164:167], v[204:207], v[88:91]
	v_mfma_f32_16x16x32_bf16 v[76:79], v[156:159], v[216:219], v[76:79]
	v_mfma_f32_16x16x32_bf16 v[72:75], v[164:167], v[216:219], v[72:75]
	s_setprio 0
	s_setprio 1
	v_mfma_f32_16x16x32_bf16 v[116:119], v[168:171], v[184:187], v[116:119]
	v_mfma_f32_16x16x32_bf16 v[112:115], v[176:179], v[184:187], v[112:115]
	v_mfma_f32_16x16x32_bf16 v[100:103], v[168:171], v[192:195], v[100:103]
	v_mfma_f32_16x16x32_bf16 v[96:99], v[176:179], v[192:195], v[96:99]
	v_mfma_f32_16x16x32_bf16 v[84:87], v[168:171], v[200:203], v[84:87]
	v_mfma_f32_16x16x32_bf16 v[80:83], v[176:179], v[200:203], v[80:83]
	v_mfma_f32_16x16x32_bf16 v[68:71], v[168:171], v[212:215], v[68:71]
	v_mfma_f32_16x16x32_bf16 v[64:67], v[176:179], v[212:215], v[64:67]
	v_mfma_f32_16x16x32_bf16 v[116:119], v[172:175], v[188:191], v[116:119]
	v_mfma_f32_16x16x32_bf16 v[112:115], v[180:183], v[188:191], v[112:115]
	v_mfma_f32_16x16x32_bf16 v[100:103], v[172:175], v[196:199], v[100:103]
	v_mfma_f32_16x16x32_bf16 v[96:99], v[180:183], v[196:199], v[96:99]
	v_mfma_f32_16x16x32_bf16 v[84:87], v[172:175], v[204:207], v[84:87]
	v_mfma_f32_16x16x32_bf16 v[80:83], v[180:183], v[204:207], v[80:83]
	v_mfma_f32_16x16x32_bf16 v[68:71], v[172:175], v[216:219], v[68:71]
	v_mfma_f32_16x16x32_bf16 v[64:67], v[180:183], v[216:219], v[64:67]
	s_setprio 0
	s_barrier
	s_add_i32 s76, s64, s55
	v_lshl_add_u64 v[144:145], s[46:47], 0, v[130:131]
	s_mov_b32 m0, s76
	ds_read_b128 v[184:187], v151 offset:16384
	ds_read_b128 v[188:191], v151 offset:17408
	ds_read_b128 v[192:195], v151 offset:18432
	ds_read_b128 v[196:199], v151 offset:19456
	ds_read_b128 v[200:203], v151 offset:20480
	ds_read_b128 v[204:207], v151 offset:21504
	ds_read_b128 v[212:215], v151 offset:22528
	ds_read_b128 v[216:219], v151 offset:23552
	global_load_lds_dwordx4 v[144:145], off
	s_add_i32 m0, s76, 0x2000
	s_add_u32 s76, s46, 0x40000
	v_lshl_add_u64 v[220:221], s[46:47], 0, v[134:135]
	s_addc_u32 s77, s47, 0
	s_add_i32 s78, s65, s55
	global_load_lds_dwordx4 v[220:221], off
	v_lshl_add_u64 v[222:223], s[76:77], 0, v[130:131]
	s_mov_b32 m0, s78
	v_lshl_add_u64 v[224:225], s[48:49], 0, v[132:133]
	global_load_lds_dwordx4 v[222:223], off
	v_lshl_add_u64 v[222:223], s[76:77], 0, v[134:135]
	s_add_i32 m0, s78, 0x2000
	s_nop 0
	global_load_lds_dwordx4 v[222:223], off
	v_lshl_add_u64 v[222:223], s[48:49], 0, v[128:129]
	s_mov_b32 m0, s43
	s_nop 0
	global_load_lds_dwordx4 v[222:223], off
	s_mov_b32 m0, s56
	s_nop 0
	global_load_lds_dwordx4 v[224:225], off
	s_waitcnt vmcnt(8)
	s_waitcnt lgkmcnt(0)
	s_setprio 1
	s_barrier
	v_mfma_f32_16x16x32_bf16 v[60:63], v[152:155], v[184:187], v[60:63]
	v_mfma_f32_16x16x32_bf16 v[56:59], v[160:163], v[184:187], v[56:59]
	v_mfma_f32_16x16x32_bf16 v[44:47], v[152:155], v[192:195], v[44:47]
	v_mfma_f32_16x16x32_bf16 v[40:43], v[160:163], v[192:195], v[40:43]
	v_mfma_f32_16x16x32_bf16 v[28:31], v[152:155], v[200:203], v[28:31]
	v_mfma_f32_16x16x32_bf16 v[24:27], v[160:163], v[200:203], v[24:27]
	v_mfma_f32_16x16x32_bf16 v[12:15], v[152:155], v[212:215], v[12:15]
	v_mfma_f32_16x16x32_bf16 v[8:11], v[160:163], v[212:215], v[8:11]
	v_mfma_f32_16x16x32_bf16 v[60:63], v[156:159], v[188:191], v[60:63]
	v_mfma_f32_16x16x32_bf16 v[56:59], v[164:167], v[188:191], v[56:59]
	v_mfma_f32_16x16x32_bf16 v[44:47], v[156:159], v[196:199], v[44:47]
	v_mfma_f32_16x16x32_bf16 v[40:43], v[164:167], v[196:199], v[40:43]
	v_mfma_f32_16x16x32_bf16 v[28:31], v[156:159], v[204:207], v[28:31]
	v_mfma_f32_16x16x32_bf16 v[24:27], v[164:167], v[204:207], v[24:27]
	v_mfma_f32_16x16x32_bf16 v[12:15], v[156:159], v[216:219], v[12:15]
	v_mfma_f32_16x16x32_bf16 v[8:11], v[164:167], v[216:219], v[8:11]
	s_setprio 0
	s_setprio 1
	v_mfma_f32_16x16x32_bf16 v[52:55], v[168:171], v[184:187], v[52:55]
	v_mfma_f32_16x16x32_bf16 v[48:51], v[176:179], v[184:187], v[48:51]
	v_mfma_f32_16x16x32_bf16 v[36:39], v[168:171], v[192:195], v[36:39]
	v_mfma_f32_16x16x32_bf16 v[32:35], v[176:179], v[192:195], v[32:35]
	v_mfma_f32_16x16x32_bf16 v[20:23], v[168:171], v[200:203], v[20:23]
	v_mfma_f32_16x16x32_bf16 v[16:19], v[176:179], v[200:203], v[16:19]
	v_mfma_f32_16x16x32_bf16 v[4:7], v[168:171], v[212:215], v[4:7]
	v_mfma_f32_16x16x32_bf16 v[0:3], v[176:179], v[212:215], v[0:3]
	v_mfma_f32_16x16x32_bf16 v[52:55], v[172:175], v[188:191], v[52:55]
	v_mfma_f32_16x16x32_bf16 v[48:51], v[180:183], v[188:191], v[48:51]
	v_mfma_f32_16x16x32_bf16 v[36:39], v[172:175], v[196:199], v[36:39]
	v_mfma_f32_16x16x32_bf16 v[32:35], v[180:183], v[196:199], v[32:35]
	v_mfma_f32_16x16x32_bf16 v[20:23], v[172:175], v[204:207], v[20:23]
	v_mfma_f32_16x16x32_bf16 v[16:19], v[180:183], v[204:207], v[16:19]
	v_mfma_f32_16x16x32_bf16 v[4:7], v[172:175], v[216:219], v[4:7]
	v_mfma_f32_16x16x32_bf16 v[0:3], v[180:183], v[216:219], v[0:3]
	s_setprio 0
	s_barrier
	s_add_i32 s76, 0, 0x18000
	s_add_i32 s77, 0, 0x1c000
	v_add_u32_e32 v164, s76, v147
	v_add_u32_e32 v180, s77, v147
	ds_read_b128 v[152:155], v164
	ds_read_b128 v[156:159], v164 offset:1024
	ds_read_b128 v[160:163], v164 offset:2048
	ds_read_b128 v[164:167], v164 offset:3072
	ds_read_b128 v[168:171], v180
	ds_read_b128 v[172:175], v180 offset:1024
	ds_read_b128 v[176:179], v180 offset:2048
	ds_read_b128 v[180:183], v180 offset:3072
	s_add_u32 s48, s48, 0x40000
	s_addc_u32 s49, s49, 0
	s_mov_b32 m0, s57
	v_lshl_add_u64 v[226:227], s[48:49], 0, v[128:129]
	ds_read_b128 v[184:187], v151 offset:32768
	ds_read_b128 v[188:191], v151 offset:33792
	ds_read_b128 v[192:195], v151 offset:34816
	ds_read_b128 v[196:199], v151 offset:35840
	ds_read_b128 v[200:203], v151 offset:36864
	ds_read_b128 v[204:207], v151 offset:37888
	ds_read_b128 v[212:215], v151 offset:38912
	ds_read_b128 v[216:219], v151 offset:39936
	global_load_lds_dwordx4 v[226:227], off
	v_lshl_add_u64 v[226:227], s[48:49], 0, v[132:133]
	s_mov_b32 m0, s58
	s_nop 0
	global_load_lds_dwordx4 v[226:227], off
	s_waitcnt vmcnt(8)
	s_waitcnt lgkmcnt(0)
	s_setprio 1
	s_barrier
	v_mfma_f32_16x16x32_bf16 v[124:127], v[152:155], v[184:187], v[124:127]
	v_mfma_f32_16x16x32_bf16 v[120:123], v[160:163], v[184:187], v[120:123]
	v_mfma_f32_16x16x32_bf16 v[108:111], v[152:155], v[192:195], v[108:111]
	v_mfma_f32_16x16x32_bf16 v[104:107], v[160:163], v[192:195], v[104:107]
	v_mfma_f32_16x16x32_bf16 v[92:95], v[152:155], v[200:203], v[92:95]
	v_mfma_f32_16x16x32_bf16 v[88:91], v[160:163], v[200:203], v[88:91]
	v_mfma_f32_16x16x32_bf16 v[76:79], v[152:155], v[212:215], v[76:79]
	v_mfma_f32_16x16x32_bf16 v[72:75], v[160:163], v[212:215], v[72:75]
	v_mfma_f32_16x16x32_bf16 v[124:127], v[156:159], v[188:191], v[124:127]
	v_mfma_f32_16x16x32_bf16 v[120:123], v[164:167], v[188:191], v[120:123]
	v_mfma_f32_16x16x32_bf16 v[108:111], v[156:159], v[196:199], v[108:111]
	v_mfma_f32_16x16x32_bf16 v[104:107], v[164:167], v[196:199], v[104:107]
	v_mfma_f32_16x16x32_bf16 v[92:95], v[156:159], v[204:207], v[92:95]
	v_mfma_f32_16x16x32_bf16 v[88:91], v[164:167], v[204:207], v[88:91]
	v_mfma_f32_16x16x32_bf16 v[76:79], v[156:159], v[216:219], v[76:79]
	v_mfma_f32_16x16x32_bf16 v[72:75], v[164:167], v[216:219], v[72:75]
	s_setprio 0
	s_setprio 1
	v_mfma_f32_16x16x32_bf16 v[116:119], v[168:171], v[184:187], v[116:119]
	v_mfma_f32_16x16x32_bf16 v[112:115], v[176:179], v[184:187], v[112:115]
	v_mfma_f32_16x16x32_bf16 v[100:103], v[168:171], v[192:195], v[100:103]
	v_mfma_f32_16x16x32_bf16 v[96:99], v[176:179], v[192:195], v[96:99]
	v_mfma_f32_16x16x32_bf16 v[84:87], v[168:171], v[200:203], v[84:87]
	v_mfma_f32_16x16x32_bf16 v[80:83], v[176:179], v[200:203], v[80:83]
	v_mfma_f32_16x16x32_bf16 v[68:71], v[168:171], v[212:215], v[68:71]
	v_mfma_f32_16x16x32_bf16 v[64:67], v[176:179], v[212:215], v[64:67]
	v_mfma_f32_16x16x32_bf16 v[116:119], v[172:175], v[188:191], v[116:119]
	v_mfma_f32_16x16x32_bf16 v[112:115], v[180:183], v[188:191], v[112:115]
	v_mfma_f32_16x16x32_bf16 v[100:103], v[172:175], v[196:199], v[100:103]
	v_mfma_f32_16x16x32_bf16 v[96:99], v[180:183], v[196:199], v[96:99]
	v_mfma_f32_16x16x32_bf16 v[84:87], v[172:175], v[204:207], v[84:87]
	v_mfma_f32_16x16x32_bf16 v[80:83], v[180:183], v[204:207], v[80:83]
	v_mfma_f32_16x16x32_bf16 v[68:71], v[172:175], v[216:219], v[68:71]
	v_mfma_f32_16x16x32_bf16 v[64:67], v[180:183], v[216:219], v[64:67]
	s_setprio 0
	s_barrier
	s_add_i32 s48, s76, s55
	v_lshl_add_u64 v[144:145], v[144:145], 0, s[12:13]
	s_mov_b32 m0, s48
	ds_read_b128 v[184:187], v151 offset:49152
	ds_read_b128 v[188:191], v151 offset:50176
	ds_read_b128 v[192:195], v151 offset:51200
	ds_read_b128 v[196:199], v151 offset:52224
	ds_read_b128 v[200:203], v151 offset:53248
	ds_read_b128 v[204:207], v151 offset:54272
	ds_read_b128 v[212:215], v151 offset:55296
	ds_read_b128 v[216:219], v151 offset:56320
	global_load_lds_dwordx4 v[144:145], off
	s_add_i32 m0, s48, 0x2000
	s_add_u32 s46, s46, 0x40080
	v_lshl_add_u64 v[144:145], v[220:221], 0, s[12:13]
	s_addc_u32 s47, s47, 0
	s_add_i32 s48, s77, s55
	global_load_lds_dwordx4 v[144:145], off
	v_lshl_add_u64 v[144:145], s[46:47], 0, v[130:131]
	s_mov_b32 m0, s48
	s_nop 0
	global_load_lds_dwordx4 v[144:145], off
	v_lshl_add_u64 v[144:145], s[46:47], 0, v[134:135]
	s_add_i32 m0, s48, 0x2000
	s_nop 0
	global_load_lds_dwordx4 v[144:145], off
	v_lshl_add_u64 v[144:145], v[222:223], 0, s[12:13]
	s_mov_b32 m0, s60
	s_nop 0
	global_load_lds_dwordx4 v[144:145], off
	v_lshl_add_u64 v[144:145], v[224:225], 0, s[12:13]
	s_mov_b32 m0, s61
	s_nop 0
	global_load_lds_dwordx4 v[144:145], off
	s_waitcnt vmcnt(8)
	s_waitcnt lgkmcnt(0)
	s_setprio 1
	s_barrier
	v_mfma_f32_16x16x32_bf16 v[60:63], v[152:155], v[184:187], v[60:63]
	v_mfma_f32_16x16x32_bf16 v[56:59], v[160:163], v[184:187], v[56:59]
	v_mfma_f32_16x16x32_bf16 v[44:47], v[152:155], v[192:195], v[44:47]
	v_mfma_f32_16x16x32_bf16 v[40:43], v[160:163], v[192:195], v[40:43]
	v_mfma_f32_16x16x32_bf16 v[28:31], v[152:155], v[200:203], v[28:31]
	v_mfma_f32_16x16x32_bf16 v[24:27], v[160:163], v[200:203], v[24:27]
	v_mfma_f32_16x16x32_bf16 v[12:15], v[152:155], v[212:215], v[12:15]
	v_mfma_f32_16x16x32_bf16 v[8:11], v[160:163], v[212:215], v[8:11]
	v_mfma_f32_16x16x32_bf16 v[60:63], v[156:159], v[188:191], v[60:63]
	v_mfma_f32_16x16x32_bf16 v[56:59], v[164:167], v[188:191], v[56:59]
	v_mfma_f32_16x16x32_bf16 v[44:47], v[156:159], v[196:199], v[44:47]
	v_mfma_f32_16x16x32_bf16 v[40:43], v[164:167], v[196:199], v[40:43]
	v_mfma_f32_16x16x32_bf16 v[28:31], v[156:159], v[204:207], v[28:31]
	v_mfma_f32_16x16x32_bf16 v[24:27], v[164:167], v[204:207], v[24:27]
	v_mfma_f32_16x16x32_bf16 v[12:15], v[156:159], v[216:219], v[12:15]
	v_mfma_f32_16x16x32_bf16 v[8:11], v[164:167], v[216:219], v[8:11]
	s_setprio 0
	s_setprio 1
	v_mfma_f32_16x16x32_bf16 v[52:55], v[168:171], v[184:187], v[52:55]
	v_mfma_f32_16x16x32_bf16 v[48:51], v[176:179], v[184:187], v[48:51]
	v_mfma_f32_16x16x32_bf16 v[36:39], v[168:171], v[192:195], v[36:39]
	v_mfma_f32_16x16x32_bf16 v[32:35], v[176:179], v[192:195], v[32:35]
	v_mfma_f32_16x16x32_bf16 v[20:23], v[168:171], v[200:203], v[20:23]
	v_mfma_f32_16x16x32_bf16 v[16:19], v[176:179], v[200:203], v[16:19]
	v_mfma_f32_16x16x32_bf16 v[4:7], v[168:171], v[212:215], v[4:7]
	v_mfma_f32_16x16x32_bf16 v[0:3], v[176:179], v[212:215], v[0:3]
	v_mfma_f32_16x16x32_bf16 v[52:55], v[172:175], v[188:191], v[52:55]
	v_mfma_f32_16x16x32_bf16 v[48:51], v[180:183], v[188:191], v[48:51]
	v_mfma_f32_16x16x32_bf16 v[36:39], v[172:175], v[196:199], v[36:39]
	v_mfma_f32_16x16x32_bf16 v[32:35], v[180:183], v[196:199], v[32:35]
	v_mfma_f32_16x16x32_bf16 v[20:23], v[172:175], v[204:207], v[20:23]
	v_mfma_f32_16x16x32_bf16 v[16:19], v[180:183], v[204:207], v[16:19]
	v_mfma_f32_16x16x32_bf16 v[4:7], v[172:175], v[216:219], v[4:7]
	v_mfma_f32_16x16x32_bf16 v[0:3], v[180:183], v[216:219], v[0:3]
	s_setprio 0
	s_barrier
	s_add_i32 s75, s75, 2
	s_add_u32 s44, s44, 0x100
	s_addc_u32 s45, s45, 0
	s_add_u32 s73, s73, 0x100
	s_addc_u32 s74, s74, 0
	s_cmp_gt_u32 s75, 13
	s_cbranch_scc0 .LBB0_702
	s_and_b64 vcc, exec, s[14:15]
	s_cbranch_vccz .LBB0_705
	s_barrier

.LBB0_783:
	ds_read_b128 v[144:147], v154
	ds_read_b128 v[158:161], v154 offset:1024
	ds_read_b128 v[162:165], v154 offset:2048
	ds_read_b128 v[166:169], v154 offset:3072
	ds_read_b128 v[170:173], v155
	ds_read_b128 v[174:177], v155 offset:1024
	ds_read_b128 v[178:181], v155 offset:2048
	ds_read_b128 v[182:185], v155 offset:3072
	s_add_u32 s50, s48, 0xfff00080
	s_addc_u32 s51, s49, -1
	s_cmp_eq_u32 s73, 60
	s_cselect_b32 s53, s9, s51
	s_cselect_b32 s52, s41, s50
	s_cselect_b32 s51, s39, s72
	s_cselect_b32 s50, s47, s71
	v_lshl_add_u64 v[148:149], s[48:49], 0, v[136:137]
	s_add_i32 m0, s59, 0xc000
	ds_read_b128 v[186:189], v156
	ds_read_b128 v[190:193], v156 offset:1024
	ds_read_b128 v[194:197], v156 offset:2048
	ds_read_b128 v[198:201], v156 offset:3072
	ds_read_b128 v[202:205], v156 offset:4096
	ds_read_b128 v[212:215], v156 offset:5120
	ds_read_b128 v[216:219], v156 offset:6144
	ds_read_b128 v[220:223], v156 offset:7168
	global_load_lds_dwordx4 v[148:149], off
	v_lshl_add_u64 v[148:149], s[48:49], 0, v[138:139]
	s_add_i32 m0, s59, 0xe000
	s_nop 0
	global_load_lds_dwordx4 v[148:149], off
	s_waitcnt vmcnt(8)
	s_waitcnt lgkmcnt(0)
	s_setprio 1
	s_barrier
	v_mfma_f32_16x16x32_bf16 v[124:127], v[144:147], v[186:189], v[124:127]
	v_mfma_f32_16x16x32_bf16 v[120:123], v[162:165], v[186:189], v[120:123]
	v_mfma_f32_16x16x32_bf16 v[108:111], v[144:147], v[194:197], v[108:111]
	v_mfma_f32_16x16x32_bf16 v[104:107], v[162:165], v[194:197], v[104:107]
	v_mfma_f32_16x16x32_bf16 v[92:95], v[144:147], v[202:205], v[92:95]
	v_mfma_f32_16x16x32_bf16 v[88:91], v[162:165], v[202:205], v[88:91]
	v_mfma_f32_16x16x32_bf16 v[76:79], v[144:147], v[216:219], v[76:79]
	v_mfma_f32_16x16x32_bf16 v[72:75], v[162:165], v[216:219], v[72:75]
	v_mfma_f32_16x16x32_bf16 v[124:127], v[158:161], v[190:193], v[124:127]
	v_mfma_f32_16x16x32_bf16 v[120:123], v[166:169], v[190:193], v[120:123]
	v_mfma_f32_16x16x32_bf16 v[108:111], v[158:161], v[198:201], v[108:111]
	v_mfma_f32_16x16x32_bf16 v[104:107], v[166:169], v[198:201], v[104:107]
	v_mfma_f32_16x16x32_bf16 v[92:95], v[158:161], v[212:215], v[92:95]
	v_mfma_f32_16x16x32_bf16 v[88:91], v[166:169], v[212:215], v[88:91]
	v_mfma_f32_16x16x32_bf16 v[76:79], v[158:161], v[220:223], v[76:79]
	v_mfma_f32_16x16x32_bf16 v[72:75], v[166:169], v[220:223], v[72:75]
	s_setprio 0
	s_setprio 1
	v_mfma_f32_16x16x32_bf16 v[116:119], v[170:173], v[186:189], v[116:119]
	v_mfma_f32_16x16x32_bf16 v[112:115], v[178:181], v[186:189], v[112:115]
	v_mfma_f32_16x16x32_bf16 v[100:103], v[170:173], v[194:197], v[100:103]
	v_mfma_f32_16x16x32_bf16 v[96:99], v[178:181], v[194:197], v[96:99]
	v_mfma_f32_16x16x32_bf16 v[84:87], v[170:173], v[202:205], v[84:87]
	v_mfma_f32_16x16x32_bf16 v[80:83], v[178:181], v[202:205], v[80:83]
	v_mfma_f32_16x16x32_bf16 v[68:71], v[170:173], v[216:219], v[68:71]
	v_mfma_f32_16x16x32_bf16 v[64:67], v[178:181], v[216:219], v[64:67]
	v_mfma_f32_16x16x32_bf16 v[116:119], v[174:177], v[190:193], v[116:119]
	v_mfma_f32_16x16x32_bf16 v[112:115], v[182:185], v[190:193], v[112:115]
	v_mfma_f32_16x16x32_bf16 v[100:103], v[174:177], v[198:201], v[100:103]
	v_mfma_f32_16x16x32_bf16 v[96:99], v[182:185], v[198:201], v[96:99]
	v_mfma_f32_16x16x32_bf16 v[84:87], v[174:177], v[212:215], v[84:87]
	v_mfma_f32_16x16x32_bf16 v[80:83], v[182:185], v[212:215], v[80:83]
	v_mfma_f32_16x16x32_bf16 v[68:71], v[174:177], v[220:223], v[68:71]
	v_mfma_f32_16x16x32_bf16 v[64:67], v[182:185], v[220:223], v[64:67]
	s_setprio 0
	s_barrier
	s_add_i32 s74, s69, s58
	v_lshl_add_u64 v[148:149], s[50:51], 0, v[130:131]
	s_mov_b32 m0, s74
	ds_read_b128 v[186:189], v156 offset:16384
	ds_read_b128 v[190:193], v156 offset:17408
	ds_read_b128 v[194:197], v156 offset:18432
	ds_read_b128 v[198:201], v156 offset:19456
	ds_read_b128 v[202:205], v156 offset:20480
	ds_read_b128 v[212:215], v156 offset:21504
	ds_read_b128 v[216:219], v156 offset:22528
	ds_read_b128 v[220:223], v156 offset:23552
	global_load_lds_dwordx4 v[148:149], off
	s_add_i32 m0, s74, 0x2000
	s_add_u32 s74, s50, 0x100000
	v_lshl_add_u64 v[206:207], s[50:51], 0, v[134:135]
	s_addc_u32 s75, s51, 0
	s_add_i32 s76, s70, s58
	global_load_lds_dwordx4 v[206:207], off
	v_lshl_add_u64 v[224:225], s[74:75], 0, v[130:131]
	s_mov_b32 m0, s76
	v_lshl_add_u64 v[226:227], s[52:53], 0, v[132:133]
	global_load_lds_dwordx4 v[224:225], off
	v_lshl_add_u64 v[224:225], s[74:75], 0, v[134:135]
	s_add_i32 m0, s76, 0x2000
	s_nop 0
	global_load_lds_dwordx4 v[224:225], off
	v_lshl_add_u64 v[224:225], s[52:53], 0, v[128:129]
	s_mov_b32 m0, s59
	s_nop 0
	global_load_lds_dwordx4 v[224:225], off
	s_mov_b32 m0, s60
	s_nop 0
	global_load_lds_dwordx4 v[226:227], off
	s_waitcnt vmcnt(8)
	s_waitcnt lgkmcnt(0)
	s_setprio 1
	s_barrier
	v_mfma_f32_16x16x32_bf16 v[60:63], v[144:147], v[186:189], v[60:63]
	v_mfma_f32_16x16x32_bf16 v[56:59], v[162:165], v[186:189], v[56:59]
	v_mfma_f32_16x16x32_bf16 v[44:47], v[144:147], v[194:197], v[44:47]
	v_mfma_f32_16x16x32_bf16 v[40:43], v[162:165], v[194:197], v[40:43]
	v_mfma_f32_16x16x32_bf16 v[28:31], v[144:147], v[202:205], v[28:31]
	v_mfma_f32_16x16x32_bf16 v[24:27], v[162:165], v[202:205], v[24:27]
	v_mfma_f32_16x16x32_bf16 v[12:15], v[144:147], v[216:219], v[12:15]
	v_mfma_f32_16x16x32_bf16 v[8:11], v[162:165], v[216:219], v[8:11]
	v_mfma_f32_16x16x32_bf16 v[60:63], v[158:161], v[190:193], v[60:63]
	v_mfma_f32_16x16x32_bf16 v[56:59], v[166:169], v[190:193], v[56:59]
	v_mfma_f32_16x16x32_bf16 v[44:47], v[158:161], v[198:201], v[44:47]
	v_mfma_f32_16x16x32_bf16 v[40:43], v[166:169], v[198:201], v[40:43]
	v_mfma_f32_16x16x32_bf16 v[28:31], v[158:161], v[212:215], v[28:31]
	v_mfma_f32_16x16x32_bf16 v[24:27], v[166:169], v[212:215], v[24:27]
	v_mfma_f32_16x16x32_bf16 v[12:15], v[158:161], v[220:223], v[12:15]
	v_mfma_f32_16x16x32_bf16 v[8:11], v[166:169], v[220:223], v[8:11]
	s_setprio 0
	s_setprio 1
	v_mfma_f32_16x16x32_bf16 v[52:55], v[170:173], v[186:189], v[52:55]
	v_mfma_f32_16x16x32_bf16 v[48:51], v[178:181], v[186:189], v[48:51]
	v_mfma_f32_16x16x32_bf16 v[36:39], v[170:173], v[194:197], v[36:39]
	v_mfma_f32_16x16x32_bf16 v[32:35], v[178:181], v[194:197], v[32:35]
	v_mfma_f32_16x16x32_bf16 v[20:23], v[170:173], v[202:205], v[20:23]
	v_mfma_f32_16x16x32_bf16 v[16:19], v[178:181], v[202:205], v[16:19]
	v_mfma_f32_16x16x32_bf16 v[4:7], v[170:173], v[216:219], v[4:7]
	v_mfma_f32_16x16x32_bf16 v[0:3], v[178:181], v[216:219], v[0:3]
	v_mfma_f32_16x16x32_bf16 v[52:55], v[174:177], v[190:193], v[52:55]
	v_mfma_f32_16x16x32_bf16 v[48:51], v[182:185], v[190:193], v[48:51]
	v_mfma_f32_16x16x32_bf16 v[36:39], v[174:177], v[198:201], v[36:39]
	v_mfma_f32_16x16x32_bf16 v[32:35], v[182:185], v[198:201], v[32:35]
	v_mfma_f32_16x16x32_bf16 v[20:23], v[174:177], v[212:215], v[20:23]
	v_mfma_f32_16x16x32_bf16 v[16:19], v[182:185], v[212:215], v[16:19]
	v_mfma_f32_16x16x32_bf16 v[4:7], v[174:177], v[220:223], v[4:7]
	v_mfma_f32_16x16x32_bf16 v[0:3], v[182:185], v[220:223], v[0:3]
	s_setprio 0
	s_barrier
	s_add_i32 s74, 0, 0x18000
	v_add_u32_e32 v150, s74, v152
	s_add_i32 s75, 0, 0x1c000
	ds_read_b128 v[144:147], v150
	ds_read_b128 v[158:161], v150 offset:1024
	ds_read_b128 v[162:165], v150 offset:2048
	ds_read_b128 v[166:169], v150 offset:3072
	v_add_u32_e32 v150, s75, v152
	ds_read_b128 v[170:173], v150
	ds_read_b128 v[174:177], v150 offset:1024
	ds_read_b128 v[178:181], v150 offset:2048
	ds_read_b128 v[182:185], v150 offset:3072
	s_add_u32 s52, s52, 0x100000
	s_addc_u32 s53, s53, 0
	s_mov_b32 m0, s61
	v_lshl_add_u64 v[228:229], s[52:53], 0, v[128:129]
	ds_read_b128 v[186:189], v156 offset:32768
	ds_read_b128 v[190:193], v156 offset:33792
	ds_read_b128 v[194:197], v156 offset:34816
	ds_read_b128 v[198:201], v156 offset:35840
	ds_read_b128 v[202:205], v156 offset:36864
	ds_read_b128 v[212:215], v156 offset:37888
	ds_read_b128 v[216:219], v156 offset:38912
	ds_read_b128 v[220:223], v156 offset:39936
	global_load_lds_dwordx4 v[228:229], off
	v_lshl_add_u64 v[228:229], s[52:53], 0, v[132:133]
	s_mov_b32 m0, s62
	s_nop 0
	global_load_lds_dwordx4 v[228:229], off
	s_waitcnt vmcnt(8)
	s_waitcnt lgkmcnt(0)
	s_setprio 1
	s_barrier
	v_mfma_f32_16x16x32_bf16 v[124:127], v[144:147], v[186:189], v[124:127]
	v_mfma_f32_16x16x32_bf16 v[120:123], v[162:165], v[186:189], v[120:123]
	v_mfma_f32_16x16x32_bf16 v[108:111], v[144:147], v[194:197], v[108:111]
	v_mfma_f32_16x16x32_bf16 v[104:107], v[162:165], v[194:197], v[104:107]
	v_mfma_f32_16x16x32_bf16 v[92:95], v[144:147], v[202:205], v[92:95]
	v_mfma_f32_16x16x32_bf16 v[88:91], v[162:165], v[202:205], v[88:91]
	v_mfma_f32_16x16x32_bf16 v[76:79], v[144:147], v[216:219], v[76:79]
	v_mfma_f32_16x16x32_bf16 v[72:75], v[162:165], v[216:219], v[72:75]
	v_mfma_f32_16x16x32_bf16 v[124:127], v[158:161], v[190:193], v[124:127]
	v_mfma_f32_16x16x32_bf16 v[120:123], v[166:169], v[190:193], v[120:123]
	v_mfma_f32_16x16x32_bf16 v[108:111], v[158:161], v[198:201], v[108:111]
	v_mfma_f32_16x16x32_bf16 v[104:107], v[166:169], v[198:201], v[104:107]
	v_mfma_f32_16x16x32_bf16 v[92:95], v[158:161], v[212:215], v[92:95]
	v_mfma_f32_16x16x32_bf16 v[88:91], v[166:169], v[212:215], v[88:91]
	v_mfma_f32_16x16x32_bf16 v[76:79], v[158:161], v[220:223], v[76:79]
	v_mfma_f32_16x16x32_bf16 v[72:75], v[166:169], v[220:223], v[72:75]
	s_setprio 0
	s_setprio 1
	v_mfma_f32_16x16x32_bf16 v[116:119], v[170:173], v[186:189], v[116:119]
	v_mfma_f32_16x16x32_bf16 v[112:115], v[178:181], v[186:189], v[112:115]
	v_mfma_f32_16x16x32_bf16 v[100:103], v[170:173], v[194:197], v[100:103]
	v_mfma_f32_16x16x32_bf16 v[96:99], v[178:181], v[194:197], v[96:99]
	v_mfma_f32_16x16x32_bf16 v[84:87], v[170:173], v[202:205], v[84:87]
	v_mfma_f32_16x16x32_bf16 v[80:83], v[178:181], v[202:205], v[80:83]
	v_mfma_f32_16x16x32_bf16 v[68:71], v[170:173], v[216:219], v[68:71]
	v_mfma_f32_16x16x32_bf16 v[64:67], v[178:181], v[216:219], v[64:67]
	v_mfma_f32_16x16x32_bf16 v[116:119], v[174:177], v[190:193], v[116:119]
	v_mfma_f32_16x16x32_bf16 v[112:115], v[182:185], v[190:193], v[112:115]
	v_mfma_f32_16x16x32_bf16 v[100:103], v[174:177], v[198:201], v[100:103]
	v_mfma_f32_16x16x32_bf16 v[96:99], v[182:185], v[198:201], v[96:99]
	v_mfma_f32_16x16x32_bf16 v[84:87], v[174:177], v[212:215], v[84:87]
	v_mfma_f32_16x16x32_bf16 v[80:83], v[182:185], v[212:215], v[80:83]
	v_mfma_f32_16x16x32_bf16 v[68:71], v[174:177], v[220:223], v[68:71]
	v_mfma_f32_16x16x32_bf16 v[64:67], v[182:185], v[220:223], v[64:67]
	s_setprio 0
	s_barrier
	s_add_i32 s52, s74, s58
	v_lshl_add_u64 v[148:149], v[148:149], 0, s[22:23]
	s_mov_b32 m0, s52
	ds_read_b128 v[186:189], v156 offset:49152
	ds_read_b128 v[190:193], v156 offset:50176
	ds_read_b128 v[194:197], v156 offset:51200
	ds_read_b128 v[198:201], v156 offset:52224
	ds_read_b128 v[202:205], v156 offset:53248
	ds_read_b128 v[212:215], v156 offset:54272
	ds_read_b128 v[216:219], v156 offset:55296
	ds_read_b128 v[220:223], v156 offset:56320
	global_load_lds_dwordx4 v[148:149], off
	s_add_i32 m0, s52, 0x2000
	s_add_u32 s50, s50, 0x100080
	v_lshl_add_u64 v[148:149], v[206:207], 0, s[22:23]
	s_addc_u32 s51, s51, 0
	s_add_i32 s52, s75, s58
	global_load_lds_dwordx4 v[148:149], off
	v_lshl_add_u64 v[148:149], s[50:51], 0, v[130:131]
	s_mov_b32 m0, s52
	s_nop 0
	global_load_lds_dwordx4 v[148:149], off
	v_lshl_add_u64 v[148:149], s[50:51], 0, v[134:135]
	s_add_i32 m0, s52, 0x2000
	s_nop 0
	global_load_lds_dwordx4 v[148:149], off
	v_lshl_add_u64 v[148:149], v[224:225], 0, s[22:23]
	s_mov_b32 m0, s64
	s_nop 0
	global_load_lds_dwordx4 v[148:149], off
	v_lshl_add_u64 v[148:149], v[226:227], 0, s[22:23]
	s_mov_b32 m0, s65
	s_nop 0
	global_load_lds_dwordx4 v[148:149], off
	s_waitcnt vmcnt(8)
	s_waitcnt lgkmcnt(0)
	s_setprio 1
	s_barrier
	v_mfma_f32_16x16x32_bf16 v[60:63], v[144:147], v[186:189], v[60:63]
	v_mfma_f32_16x16x32_bf16 v[56:59], v[162:165], v[186:189], v[56:59]
	v_mfma_f32_16x16x32_bf16 v[44:47], v[144:147], v[194:197], v[44:47]
	v_mfma_f32_16x16x32_bf16 v[40:43], v[162:165], v[194:197], v[40:43]
	v_mfma_f32_16x16x32_bf16 v[28:31], v[144:147], v[202:205], v[28:31]
	v_mfma_f32_16x16x32_bf16 v[24:27], v[162:165], v[202:205], v[24:27]
	v_mfma_f32_16x16x32_bf16 v[12:15], v[144:147], v[216:219], v[12:15]
	v_mfma_f32_16x16x32_bf16 v[8:11], v[162:165], v[216:219], v[8:11]
	v_mfma_f32_16x16x32_bf16 v[60:63], v[158:161], v[190:193], v[60:63]
	v_mfma_f32_16x16x32_bf16 v[56:59], v[166:169], v[190:193], v[56:59]
	v_mfma_f32_16x16x32_bf16 v[44:47], v[158:161], v[198:201], v[44:47]
	v_mfma_f32_16x16x32_bf16 v[40:43], v[166:169], v[198:201], v[40:43]
	v_mfma_f32_16x16x32_bf16 v[28:31], v[158:161], v[212:215], v[28:31]
	v_mfma_f32_16x16x32_bf16 v[24:27], v[166:169], v[212:215], v[24:27]
	v_mfma_f32_16x16x32_bf16 v[12:15], v[158:161], v[220:223], v[12:15]
	v_mfma_f32_16x16x32_bf16 v[8:11], v[166:169], v[220:223], v[8:11]
	s_setprio 0
	s_setprio 1
	v_mfma_f32_16x16x32_bf16 v[52:55], v[170:173], v[186:189], v[52:55]
	v_mfma_f32_16x16x32_bf16 v[48:51], v[178:181], v[186:189], v[48:51]
	v_mfma_f32_16x16x32_bf16 v[36:39], v[170:173], v[194:197], v[36:39]
	v_mfma_f32_16x16x32_bf16 v[32:35], v[178:181], v[194:197], v[32:35]
	v_mfma_f32_16x16x32_bf16 v[20:23], v[170:173], v[202:205], v[20:23]
	v_mfma_f32_16x16x32_bf16 v[16:19], v[178:181], v[202:205], v[16:19]
	v_mfma_f32_16x16x32_bf16 v[4:7], v[170:173], v[216:219], v[4:7]
	v_mfma_f32_16x16x32_bf16 v[0:3], v[178:181], v[216:219], v[0:3]
	v_mfma_f32_16x16x32_bf16 v[52:55], v[174:177], v[190:193], v[52:55]
	v_mfma_f32_16x16x32_bf16 v[48:51], v[182:185], v[190:193], v[48:51]
	v_mfma_f32_16x16x32_bf16 v[36:39], v[174:177], v[198:201], v[36:39]
	v_mfma_f32_16x16x32_bf16 v[32:35], v[182:185], v[198:201], v[32:35]
	v_mfma_f32_16x16x32_bf16 v[20:23], v[174:177], v[212:215], v[20:23]
	v_mfma_f32_16x16x32_bf16 v[16:19], v[182:185], v[212:215], v[16:19]
	v_mfma_f32_16x16x32_bf16 v[4:7], v[174:177], v[220:223], v[4:7]
	v_mfma_f32_16x16x32_bf16 v[0:3], v[182:185], v[220:223], v[0:3]
	s_setprio 0
	s_barrier
	s_add_i32 s73, s73, 2
	s_add_u32 s48, s48, 0x100
	s_addc_u32 s49, s49, 0
	s_add_u32 s71, s71, 0x100
	s_addc_u32 s72, s72, 0
	s_cmp_gt_u32 s73, 61
	s_cbranch_scc0 .LBB0_783
	s_and_b64 vcc, exec, s[24:25]
	s_cbranch_vccz .LBB0_786
	s_barrier

.LBB0_902:
	ds_read_b128 v[146:149], v152
	ds_read_b128 v[158:161], v152 offset:1024
	ds_read_b128 v[162:165], v152 offset:2048
	ds_read_b128 v[166:169], v152 offset:3072
	ds_read_b128 v[170:173], v153
	ds_read_b128 v[174:177], v153 offset:1024
	ds_read_b128 v[178:181], v153 offset:2048
	ds_read_b128 v[182:185], v153 offset:3072
	s_add_u32 s38, s36, 0xfffc0080
	s_addc_u32 s39, s37, -1
	s_cmp_eq_u32 s65, 12
	s_cselect_b32 s41, s19, s39
	s_cselect_b32 s40, s61, s38
	s_cselect_b32 s39, s17, s64
	s_cselect_b32 s38, s62, s63
	v_lshl_add_u64 v[206:207], s[36:37], 0, v[138:139]
	s_add_i32 m0, s25, 0xc000
	ds_read_b128 v[186:189], v154
	ds_read_b128 v[190:193], v154 offset:1024
	ds_read_b128 v[194:197], v154 offset:2048
	ds_read_b128 v[198:201], v154 offset:3072
	ds_read_b128 v[202:205], v154 offset:4096
	ds_read_b128 v[212:215], v154 offset:5120
	ds_read_b128 v[216:219], v154 offset:6144
	ds_read_b128 v[220:223], v154 offset:7168
	global_load_lds_dwordx4 v[206:207], off
	v_lshl_add_u64 v[206:207], s[36:37], 0, v[140:141]
	s_add_i32 m0, s25, 0xe000
	s_nop 0
	global_load_lds_dwordx4 v[206:207], off
	s_waitcnt vmcnt(8)
	s_waitcnt lgkmcnt(0)
	s_setprio 1
	s_barrier
	v_mfma_f32_16x16x32_bf16 v[124:127], v[146:149], v[186:189], v[124:127]
	v_mfma_f32_16x16x32_bf16 v[120:123], v[162:165], v[186:189], v[120:123]
	v_mfma_f32_16x16x32_bf16 v[108:111], v[146:149], v[194:197], v[108:111]
	v_mfma_f32_16x16x32_bf16 v[104:107], v[162:165], v[194:197], v[104:107]
	v_mfma_f32_16x16x32_bf16 v[92:95], v[146:149], v[202:205], v[92:95]
	v_mfma_f32_16x16x32_bf16 v[88:91], v[162:165], v[202:205], v[88:91]
	v_mfma_f32_16x16x32_bf16 v[76:79], v[146:149], v[216:219], v[76:79]
	v_mfma_f32_16x16x32_bf16 v[72:75], v[162:165], v[216:219], v[72:75]
	v_mfma_f32_16x16x32_bf16 v[124:127], v[158:161], v[190:193], v[124:127]
	v_mfma_f32_16x16x32_bf16 v[120:123], v[166:169], v[190:193], v[120:123]
	v_mfma_f32_16x16x32_bf16 v[108:111], v[158:161], v[198:201], v[108:111]
	v_mfma_f32_16x16x32_bf16 v[104:107], v[166:169], v[198:201], v[104:107]
	v_mfma_f32_16x16x32_bf16 v[92:95], v[158:161], v[212:215], v[92:95]
	v_mfma_f32_16x16x32_bf16 v[88:91], v[166:169], v[212:215], v[88:91]
	v_mfma_f32_16x16x32_bf16 v[76:79], v[158:161], v[220:223], v[76:79]
	v_mfma_f32_16x16x32_bf16 v[72:75], v[166:169], v[220:223], v[72:75]
	s_setprio 0
	s_setprio 1
	v_mfma_f32_16x16x32_bf16 v[116:119], v[170:173], v[186:189], v[116:119]
	v_mfma_f32_16x16x32_bf16 v[112:115], v[178:181], v[186:189], v[112:115]
	v_mfma_f32_16x16x32_bf16 v[100:103], v[170:173], v[194:197], v[100:103]
	v_mfma_f32_16x16x32_bf16 v[96:99], v[178:181], v[194:197], v[96:99]
	v_mfma_f32_16x16x32_bf16 v[84:87], v[170:173], v[202:205], v[84:87]
	v_mfma_f32_16x16x32_bf16 v[80:83], v[178:181], v[202:205], v[80:83]
	v_mfma_f32_16x16x32_bf16 v[68:71], v[170:173], v[216:219], v[68:71]
	v_mfma_f32_16x16x32_bf16 v[64:67], v[178:181], v[216:219], v[64:67]
	v_mfma_f32_16x16x32_bf16 v[116:119], v[174:177], v[190:193], v[116:119]
	v_mfma_f32_16x16x32_bf16 v[112:115], v[182:185], v[190:193], v[112:115]
	v_mfma_f32_16x16x32_bf16 v[100:103], v[174:177], v[198:201], v[100:103]
	v_mfma_f32_16x16x32_bf16 v[96:99], v[182:185], v[198:201], v[96:99]
	v_mfma_f32_16x16x32_bf16 v[84:87], v[174:177], v[212:215], v[84:87]
	v_mfma_f32_16x16x32_bf16 v[80:83], v[182:185], v[212:215], v[80:83]
	v_mfma_f32_16x16x32_bf16 v[68:71], v[174:177], v[220:223], v[68:71]
	v_mfma_f32_16x16x32_bf16 v[64:67], v[182:185], v[220:223], v[64:67]
	s_setprio 0
	s_barrier
	s_add_i32 s66, s57, s47
	v_lshl_add_u64 v[206:207], s[38:39], 0, v[130:131]
	s_mov_b32 m0, s66
	ds_read_b128 v[186:189], v154 offset:16384
	ds_read_b128 v[190:193], v154 offset:17408
	ds_read_b128 v[194:197], v154 offset:18432
	ds_read_b128 v[198:201], v154 offset:19456
	ds_read_b128 v[202:205], v154 offset:20480
	ds_read_b128 v[212:215], v154 offset:21504
	ds_read_b128 v[216:219], v154 offset:22528
	ds_read_b128 v[220:223], v154 offset:23552
	global_load_lds_dwordx4 v[206:207], off
	s_add_i32 m0, s66, 0x2000
	s_add_u32 s66, s38, 0x40000
	v_lshl_add_u64 v[224:225], s[38:39], 0, v[134:135]
	s_addc_u32 s67, s39, 0
	s_add_i32 s68, s58, s47
	global_load_lds_dwordx4 v[224:225], off
	v_lshl_add_u64 v[226:227], s[66:67], 0, v[130:131]
	s_mov_b32 m0, s68
	v_lshl_add_u64 v[228:229], s[40:41], 0, v[132:133]
	global_load_lds_dwordx4 v[226:227], off
	v_lshl_add_u64 v[226:227], s[66:67], 0, v[134:135]
	s_add_i32 m0, s68, 0x2000
	s_nop 0
	global_load_lds_dwordx4 v[226:227], off
	v_lshl_add_u64 v[226:227], s[40:41], 0, v[128:129]
	s_mov_b32 m0, s25
	s_nop 0
	global_load_lds_dwordx4 v[226:227], off
	s_mov_b32 m0, s48
	s_nop 0
	global_load_lds_dwordx4 v[228:229], off
	s_waitcnt vmcnt(8)
	s_waitcnt lgkmcnt(0)
	s_setprio 1
	s_barrier
	v_mfma_f32_16x16x32_bf16 v[60:63], v[146:149], v[186:189], v[60:63]
	v_mfma_f32_16x16x32_bf16 v[56:59], v[162:165], v[186:189], v[56:59]
	v_mfma_f32_16x16x32_bf16 v[44:47], v[146:149], v[194:197], v[44:47]
	v_mfma_f32_16x16x32_bf16 v[40:43], v[162:165], v[194:197], v[40:43]
	v_mfma_f32_16x16x32_bf16 v[28:31], v[146:149], v[202:205], v[28:31]
	v_mfma_f32_16x16x32_bf16 v[24:27], v[162:165], v[202:205], v[24:27]
	v_mfma_f32_16x16x32_bf16 v[12:15], v[146:149], v[216:219], v[12:15]
	v_mfma_f32_16x16x32_bf16 v[8:11], v[162:165], v[216:219], v[8:11]
	v_mfma_f32_16x16x32_bf16 v[60:63], v[158:161], v[190:193], v[60:63]
	v_mfma_f32_16x16x32_bf16 v[56:59], v[166:169], v[190:193], v[56:59]
	v_mfma_f32_16x16x32_bf16 v[44:47], v[158:161], v[198:201], v[44:47]
	v_mfma_f32_16x16x32_bf16 v[40:43], v[166:169], v[198:201], v[40:43]
	v_mfma_f32_16x16x32_bf16 v[28:31], v[158:161], v[212:215], v[28:31]
	v_mfma_f32_16x16x32_bf16 v[24:27], v[166:169], v[212:215], v[24:27]
	v_mfma_f32_16x16x32_bf16 v[12:15], v[158:161], v[220:223], v[12:15]
	v_mfma_f32_16x16x32_bf16 v[8:11], v[166:169], v[220:223], v[8:11]
	s_setprio 0
	s_setprio 1
	v_mfma_f32_16x16x32_bf16 v[52:55], v[170:173], v[186:189], v[52:55]
	v_mfma_f32_16x16x32_bf16 v[48:51], v[178:181], v[186:189], v[48:51]
	v_mfma_f32_16x16x32_bf16 v[36:39], v[170:173], v[194:197], v[36:39]
	v_mfma_f32_16x16x32_bf16 v[32:35], v[178:181], v[194:197], v[32:35]
	v_mfma_f32_16x16x32_bf16 v[20:23], v[170:173], v[202:205], v[20:23]
	v_mfma_f32_16x16x32_bf16 v[16:19], v[178:181], v[202:205], v[16:19]
	v_mfma_f32_16x16x32_bf16 v[4:7], v[170:173], v[216:219], v[4:7]
	v_mfma_f32_16x16x32_bf16 v[0:3], v[178:181], v[216:219], v[0:3]
	v_mfma_f32_16x16x32_bf16 v[52:55], v[174:177], v[190:193], v[52:55]
	v_mfma_f32_16x16x32_bf16 v[48:51], v[182:185], v[190:193], v[48:51]
	v_mfma_f32_16x16x32_bf16 v[36:39], v[174:177], v[198:201], v[36:39]
	v_mfma_f32_16x16x32_bf16 v[32:35], v[182:185], v[198:201], v[32:35]
	v_mfma_f32_16x16x32_bf16 v[20:23], v[174:177], v[212:215], v[20:23]
	v_mfma_f32_16x16x32_bf16 v[16:19], v[182:185], v[212:215], v[16:19]
	v_mfma_f32_16x16x32_bf16 v[4:7], v[174:177], v[220:223], v[4:7]
	v_mfma_f32_16x16x32_bf16 v[0:3], v[182:185], v[220:223], v[0:3]
	s_setprio 0
	s_barrier
	s_add_i32 s66, 0, 0x18000
	s_add_i32 s67, 0, 0x1c000
	v_add_u32_e32 v166, s66, v151
	v_add_u32_e32 v182, s67, v151
	ds_read_b128 v[146:149], v166
	ds_read_b128 v[158:161], v166 offset:1024
	ds_read_b128 v[162:165], v166 offset:2048
	ds_read_b128 v[166:169], v166 offset:3072
	ds_read_b128 v[170:173], v182
	ds_read_b128 v[174:177], v182 offset:1024
	ds_read_b128 v[178:181], v182 offset:2048
	ds_read_b128 v[182:185], v182 offset:3072
	s_add_u32 s40, s40, 0x40000
	s_addc_u32 s41, s41, 0
	s_mov_b32 m0, s49
	v_lshl_add_u64 v[230:231], s[40:41], 0, v[128:129]
	ds_read_b128 v[186:189], v154 offset:32768
	ds_read_b128 v[190:193], v154 offset:33792
	ds_read_b128 v[194:197], v154 offset:34816
	ds_read_b128 v[198:201], v154 offset:35840
	ds_read_b128 v[202:205], v154 offset:36864
	ds_read_b128 v[212:215], v154 offset:37888
	ds_read_b128 v[216:219], v154 offset:38912
	ds_read_b128 v[220:223], v154 offset:39936
	global_load_lds_dwordx4 v[230:231], off
	v_lshl_add_u64 v[230:231], s[40:41], 0, v[132:133]
	s_mov_b32 m0, s50
	s_nop 0
	global_load_lds_dwordx4 v[230:231], off
	s_waitcnt vmcnt(8)
	s_waitcnt lgkmcnt(0)
	s_setprio 1
	s_barrier
	v_mfma_f32_16x16x32_bf16 v[124:127], v[146:149], v[186:189], v[124:127]
	v_mfma_f32_16x16x32_bf16 v[120:123], v[162:165], v[186:189], v[120:123]
	v_mfma_f32_16x16x32_bf16 v[108:111], v[146:149], v[194:197], v[108:111]
	v_mfma_f32_16x16x32_bf16 v[104:107], v[162:165], v[194:197], v[104:107]
	v_mfma_f32_16x16x32_bf16 v[92:95], v[146:149], v[202:205], v[92:95]
	v_mfma_f32_16x16x32_bf16 v[88:91], v[162:165], v[202:205], v[88:91]
	v_mfma_f32_16x16x32_bf16 v[76:79], v[146:149], v[216:219], v[76:79]
	v_mfma_f32_16x16x32_bf16 v[72:75], v[162:165], v[216:219], v[72:75]
	v_mfma_f32_16x16x32_bf16 v[124:127], v[158:161], v[190:193], v[124:127]
	v_mfma_f32_16x16x32_bf16 v[120:123], v[166:169], v[190:193], v[120:123]
	v_mfma_f32_16x16x32_bf16 v[108:111], v[158:161], v[198:201], v[108:111]
	v_mfma_f32_16x16x32_bf16 v[104:107], v[166:169], v[198:201], v[104:107]
	v_mfma_f32_16x16x32_bf16 v[92:95], v[158:161], v[212:215], v[92:95]
	v_mfma_f32_16x16x32_bf16 v[88:91], v[166:169], v[212:215], v[88:91]
	v_mfma_f32_16x16x32_bf16 v[76:79], v[158:161], v[220:223], v[76:79]
	v_mfma_f32_16x16x32_bf16 v[72:75], v[166:169], v[220:223], v[72:75]
	s_setprio 0
	s_setprio 1
	v_mfma_f32_16x16x32_bf16 v[116:119], v[170:173], v[186:189], v[116:119]
	v_mfma_f32_16x16x32_bf16 v[112:115], v[178:181], v[186:189], v[112:115]
	v_mfma_f32_16x16x32_bf16 v[100:103], v[170:173], v[194:197], v[100:103]
	v_mfma_f32_16x16x32_bf16 v[96:99], v[178:181], v[194:197], v[96:99]
	v_mfma_f32_16x16x32_bf16 v[84:87], v[170:173], v[202:205], v[84:87]
	v_mfma_f32_16x16x32_bf16 v[80:83], v[178:181], v[202:205], v[80:83]
	v_mfma_f32_16x16x32_bf16 v[68:71], v[170:173], v[216:219], v[68:71]
	v_mfma_f32_16x16x32_bf16 v[64:67], v[178:181], v[216:219], v[64:67]
	v_mfma_f32_16x16x32_bf16 v[116:119], v[174:177], v[190:193], v[116:119]
	v_mfma_f32_16x16x32_bf16 v[112:115], v[182:185], v[190:193], v[112:115]
	v_mfma_f32_16x16x32_bf16 v[100:103], v[174:177], v[198:201], v[100:103]
	v_mfma_f32_16x16x32_bf16 v[96:99], v[182:185], v[198:201], v[96:99]
	v_mfma_f32_16x16x32_bf16 v[84:87], v[174:177], v[212:215], v[84:87]
	v_mfma_f32_16x16x32_bf16 v[80:83], v[182:185], v[212:215], v[80:83]
	v_mfma_f32_16x16x32_bf16 v[68:71], v[174:177], v[220:223], v[68:71]
	v_mfma_f32_16x16x32_bf16 v[64:67], v[182:185], v[220:223], v[64:67]
	s_setprio 0
	s_barrier
	s_add_i32 s40, s66, s47
	v_lshl_add_u64 v[206:207], v[206:207], 0, s[12:13]
	s_mov_b32 m0, s40
	ds_read_b128 v[186:189], v154 offset:49152
	ds_read_b128 v[190:193], v154 offset:50176
	ds_read_b128 v[194:197], v154 offset:51200
	ds_read_b128 v[198:201], v154 offset:52224
	ds_read_b128 v[202:205], v154 offset:53248
	ds_read_b128 v[212:215], v154 offset:54272
	ds_read_b128 v[216:219], v154 offset:55296
	ds_read_b128 v[220:223], v154 offset:56320
	global_load_lds_dwordx4 v[206:207], off
	s_add_i32 m0, s40, 0x2000
	s_add_u32 s38, s38, 0x40080
	v_lshl_add_u64 v[206:207], v[224:225], 0, s[12:13]
	s_addc_u32 s39, s39, 0
	s_add_i32 s40, s67, s47
	global_load_lds_dwordx4 v[206:207], off
	v_lshl_add_u64 v[206:207], s[38:39], 0, v[130:131]
	s_mov_b32 m0, s40
	s_nop 0
	global_load_lds_dwordx4 v[206:207], off
	v_lshl_add_u64 v[206:207], s[38:39], 0, v[134:135]
	s_add_i32 m0, s40, 0x2000
	s_nop 0
	global_load_lds_dwordx4 v[206:207], off
	v_lshl_add_u64 v[206:207], v[226:227], 0, s[12:13]
	s_mov_b32 m0, s53
	s_nop 0
	global_load_lds_dwordx4 v[206:207], off
	v_lshl_add_u64 v[206:207], v[228:229], 0, s[12:13]
	s_mov_b32 m0, s54
	s_nop 0
	global_load_lds_dwordx4 v[206:207], off
	s_waitcnt vmcnt(8)
	s_waitcnt lgkmcnt(0)
	s_setprio 1
	s_barrier
	v_mfma_f32_16x16x32_bf16 v[60:63], v[146:149], v[186:189], v[60:63]
	v_mfma_f32_16x16x32_bf16 v[56:59], v[162:165], v[186:189], v[56:59]
	v_mfma_f32_16x16x32_bf16 v[44:47], v[146:149], v[194:197], v[44:47]
	v_mfma_f32_16x16x32_bf16 v[40:43], v[162:165], v[194:197], v[40:43]
	v_mfma_f32_16x16x32_bf16 v[28:31], v[146:149], v[202:205], v[28:31]
	v_mfma_f32_16x16x32_bf16 v[24:27], v[162:165], v[202:205], v[24:27]
	v_mfma_f32_16x16x32_bf16 v[12:15], v[146:149], v[216:219], v[12:15]
	v_mfma_f32_16x16x32_bf16 v[8:11], v[162:165], v[216:219], v[8:11]
	v_mfma_f32_16x16x32_bf16 v[60:63], v[158:161], v[190:193], v[60:63]
	v_mfma_f32_16x16x32_bf16 v[56:59], v[166:169], v[190:193], v[56:59]
	v_mfma_f32_16x16x32_bf16 v[44:47], v[158:161], v[198:201], v[44:47]
	v_mfma_f32_16x16x32_bf16 v[40:43], v[166:169], v[198:201], v[40:43]
	v_mfma_f32_16x16x32_bf16 v[28:31], v[158:161], v[212:215], v[28:31]
	v_mfma_f32_16x16x32_bf16 v[24:27], v[166:169], v[212:215], v[24:27]
	v_mfma_f32_16x16x32_bf16 v[12:15], v[158:161], v[220:223], v[12:15]
	v_mfma_f32_16x16x32_bf16 v[8:11], v[166:169], v[220:223], v[8:11]
	s_setprio 0
	s_setprio 1
	v_mfma_f32_16x16x32_bf16 v[52:55], v[170:173], v[186:189], v[52:55]
	v_mfma_f32_16x16x32_bf16 v[48:51], v[178:181], v[186:189], v[48:51]
	v_mfma_f32_16x16x32_bf16 v[36:39], v[170:173], v[194:197], v[36:39]
	v_mfma_f32_16x16x32_bf16 v[32:35], v[178:181], v[194:197], v[32:35]
	v_mfma_f32_16x16x32_bf16 v[20:23], v[170:173], v[202:205], v[20:23]
	v_mfma_f32_16x16x32_bf16 v[16:19], v[178:181], v[202:205], v[16:19]
	v_mfma_f32_16x16x32_bf16 v[4:7], v[170:173], v[216:219], v[4:7]
	v_mfma_f32_16x16x32_bf16 v[0:3], v[178:181], v[216:219], v[0:3]
	v_mfma_f32_16x16x32_bf16 v[52:55], v[174:177], v[190:193], v[52:55]
	v_mfma_f32_16x16x32_bf16 v[48:51], v[182:185], v[190:193], v[48:51]
	v_mfma_f32_16x16x32_bf16 v[36:39], v[174:177], v[198:201], v[36:39]
	v_mfma_f32_16x16x32_bf16 v[32:35], v[182:185], v[198:201], v[32:35]
	v_mfma_f32_16x16x32_bf16 v[20:23], v[174:177], v[212:215], v[20:23]
	v_mfma_f32_16x16x32_bf16 v[16:19], v[182:185], v[212:215], v[16:19]
	v_mfma_f32_16x16x32_bf16 v[4:7], v[174:177], v[220:223], v[4:7]
	v_mfma_f32_16x16x32_bf16 v[0:3], v[182:185], v[220:223], v[0:3]
	s_setprio 0
	s_barrier
	s_add_i32 s65, s65, 2
	s_add_u32 s36, s36, 0x100
	s_addc_u32 s37, s37, 0
	s_add_u32 s63, s63, 0x100
	s_addc_u32 s64, s64, 0
	s_cmp_gt_u32 s65, 13
	s_cbranch_scc0 .LBB0_902
	s_and_b64 vcc, exec, s[14:15]
	s_cbranch_vccz .LBB0_905
	s_barrier

.LBB0_973:
	s_lshr_b64 s[38:39], s[18:19], 2
	ds_read_b128 v[0:3], v80
	ds_read_b128 v[4:7], v80 offset:1024
	ds_read_b128 v[8:11], v80 offset:2048
	ds_read_b128 v[12:15], v80 offset:3072
	s_and_b64 s[40:41], s[8:9], exec
	s_cselect_b32 s13, s38, s46
	s_ashr_i64 s[40:41], s[12:13], 15
	s_add_u32 s40, s50, s40
	s_addc_u32 s41, s51, s41
	s_and_b64 s[46:47], s[8:9], exec
	s_cselect_b32 s47, s41, s45
	s_cselect_b32 s46, s40, s44
	s_add_u32 s72, s42, 0x18080
	s_addc_u32 s73, s43, 0
	s_mov_b32 m0, s65
	v_lshl_add_u64 v[48:49], s[72:73], 0, v[70:71]
	ds_read_b128 v[16:19], v81
	ds_read_b128 v[20:23], v81 offset:1024
	ds_read_b128 v[24:27], v81 offset:2048
	ds_read_b128 v[28:31], v81 offset:3072
	ds_read_b128 v[32:35], v81 offset:4096
	ds_read_b128 v[36:39], v81 offset:5120
	ds_read_b128 v[40:43], v81 offset:6144
	ds_read_b128 v[44:47], v81 offset:7168
	global_load_lds_dwordx4 v[48:49], off
	v_lshl_add_u64 v[48:49], s[72:73], 0, v[66:67]
	s_mov_b32 m0, s66
	s_nop 0
	global_load_lds_dwordx4 v[48:49], off
	s_waitcnt vmcnt(8)
	s_waitcnt lgkmcnt(0)
	s_setprio 1
	s_barrier
	v_mfma_f32_16x16x32_bf16 v[48:51], v[0:3], v[16:19], 0
	v_mfma_f32_16x16x32_bf16 v[16:19], v[8:11], v[16:19], 0
	v_mfma_f32_16x16x32_bf16 v[48:51], v[4:7], v[20:23], v[48:51]
	v_mfma_f32_16x16x32_bf16 v[16:19], v[12:15], v[20:23], v[16:19]
	v_mfma_f32_16x16x32_bf16 v[20:23], v[0:3], v[24:27], 0
	v_mfma_f32_16x16x32_bf16 v[24:27], v[8:11], v[24:27], 0
	v_mfma_f32_16x16x32_bf16 v[20:23], v[4:7], v[28:31], v[20:23]
	v_mfma_f32_16x16x32_bf16 v[24:27], v[12:15], v[28:31], v[24:27]
	v_mfma_f32_16x16x32_bf16 v[28:31], v[0:3], v[32:35], 0
	v_mfma_f32_16x16x32_bf16 v[32:35], v[8:11], v[32:35], 0
	v_mfma_f32_16x16x32_bf16 v[28:31], v[4:7], v[36:39], v[28:31]
	v_mfma_f32_16x16x32_bf16 v[32:35], v[12:15], v[36:39], v[32:35]
	v_mfma_f32_16x16x32_bf16 v[36:39], v[0:3], v[40:43], 0
	v_mfma_f32_16x16x32_bf16 v[40:43], v[8:11], v[40:43], 0
	v_mfma_f32_16x16x32_bf16 v[36:39], v[4:7], v[44:47], v[36:39]
	v_mfma_f32_16x16x32_bf16 v[40:43], v[12:15], v[44:47], v[40:43]
	s_setprio 0
	s_setprio 1
	s_setprio 0
	s_barrier
	v_lshl_add_u64 v[132:133], s[44:45], 0, v[68:69]
	s_mov_b32 m0, s67
	v_lshl_add_u64 v[100:101], v[132:133], 0, s[20:21]
	v_lshl_add_u64 v[134:135], s[44:45], 0, v[64:65]
	s_add_u32 s72, s44, 0x10100
	ds_read_b128 v[44:47], v81 offset:16384
	ds_read_b128 v[52:55], v81 offset:17408
	ds_read_b128 v[56:59], v81 offset:18432
	ds_read_b128 v[60:63], v81 offset:19456
	ds_read_b128 v[84:87], v81 offset:20480
	ds_read_b128 v[88:91], v81 offset:21504
	ds_read_b128 v[92:95], v81 offset:22528
	ds_read_b128 v[96:99], v81 offset:23552
	global_load_lds_dwordx4 v[100:101], off
	v_lshl_add_u64 v[100:101], v[134:135], 0, s[20:21]
	s_mov_b32 m0, s68
	s_addc_u32 s73, s45, 0
	global_load_lds_dwordx4 v[100:101], off
	v_lshl_add_u64 v[100:101], s[72:73], 0, v[68:69]
	s_mov_b32 m0, s53
	v_lshl_add_u64 v[136:137], s[42:43], 0, v[70:71]
	global_load_lds_dwordx4 v[100:101], off
	v_lshl_add_u64 v[100:101], s[72:73], 0, v[64:65]
	s_mov_b32 m0, s54
	v_lshl_add_u64 v[138:139], s[42:43], 0, v[66:67]
	global_load_lds_dwordx4 v[100:101], off
	v_lshl_add_u64 v[100:101], v[136:137], 0, s[20:21]
	s_mov_b32 m0, s52
	s_nop 0
	global_load_lds_dwordx4 v[100:101], off
	v_lshl_add_u64 v[100:101], v[138:139], 0, s[20:21]
	s_mov_b32 m0, s55
	s_nop 0
	global_load_lds_dwordx4 v[100:101], off
	s_waitcnt vmcnt(8)
	s_waitcnt lgkmcnt(0)
	s_setprio 1
	s_barrier
	v_mfma_f32_16x16x32_bf16 v[100:103], v[0:3], v[44:47], 0
	v_mfma_f32_16x16x32_bf16 v[44:47], v[8:11], v[44:47], 0
	v_mfma_f32_16x16x32_bf16 v[100:103], v[4:7], v[52:55], v[100:103]
	v_mfma_f32_16x16x32_bf16 v[44:47], v[12:15], v[52:55], v[44:47]
	v_mfma_f32_16x16x32_bf16 v[52:55], v[0:3], v[56:59], 0
	v_mfma_f32_16x16x32_bf16 v[56:59], v[8:11], v[56:59], 0
	v_mfma_f32_16x16x32_bf16 v[52:55], v[4:7], v[60:63], v[52:55]
	v_mfma_f32_16x16x32_bf16 v[56:59], v[12:15], v[60:63], v[56:59]
	v_mfma_f32_16x16x32_bf16 v[60:63], v[0:3], v[84:87], 0
	v_mfma_f32_16x16x32_bf16 v[0:3], v[0:3], v[92:95], 0
	v_mfma_f32_16x16x32_bf16 v[60:63], v[4:7], v[88:91], v[60:63]
	v_mfma_f32_16x16x32_bf16 v[0:3], v[4:7], v[96:99], v[0:3]
	v_mfma_f32_16x16x32_bf16 v[4:7], v[8:11], v[92:95], 0
	v_mfma_f32_16x16x32_bf16 v[84:87], v[8:11], v[84:87], 0
	v_mfma_f32_16x16x32_bf16 v[4:7], v[12:15], v[96:99], v[4:7]
	v_mfma_f32_16x16x32_bf16 v[84:87], v[12:15], v[88:91], v[84:87]
	s_setprio 0
	s_setprio 1
	s_setprio 0
	s_barrier
	ds_read_b128 v[8:11], v82
	ds_read_b128 v[12:15], v82 offset:1024
	ds_read_b128 v[88:91], v82 offset:2048
	ds_read_b128 v[92:95], v82 offset:3072
	s_add_u32 s72, s42, 0x18100
	s_addc_u32 s73, s43, 0
	s_mov_b32 m0, s56
	v_lshl_add_u64 v[140:141], s[72:73], 0, v[70:71]
	ds_read_b128 v[96:99], v81 offset:32768
	ds_read_b128 v[104:107], v81 offset:33792
	ds_read_b128 v[108:111], v81 offset:34816
	ds_read_b128 v[112:115], v81 offset:35840
	ds_read_b128 v[116:119], v81 offset:36864
	ds_read_b128 v[120:123], v81 offset:37888
	ds_read_b128 v[124:127], v81 offset:38912
	ds_read_b128 v[128:131], v81 offset:39936
	global_load_lds_dwordx4 v[140:141], off
	v_lshl_add_u64 v[140:141], s[72:73], 0, v[66:67]
	s_mov_b32 m0, s57
	s_nop 0
	global_load_lds_dwordx4 v[140:141], off
	s_waitcnt vmcnt(8)
	s_waitcnt lgkmcnt(0)
	s_setprio 1
	s_barrier
	v_mfma_f32_16x16x32_bf16 v[48:51], v[8:11], v[96:99], v[48:51]
	v_mfma_f32_16x16x32_bf16 v[16:19], v[88:91], v[96:99], v[16:19]
	v_mfma_f32_16x16x32_bf16 v[20:23], v[8:11], v[108:111], v[20:23]
	v_mfma_f32_16x16x32_bf16 v[24:27], v[88:91], v[108:111], v[24:27]
	v_mfma_f32_16x16x32_bf16 v[28:31], v[8:11], v[116:119], v[28:31]
	v_mfma_f32_16x16x32_bf16 v[32:35], v[88:91], v[116:119], v[32:35]
	v_mfma_f32_16x16x32_bf16 v[36:39], v[8:11], v[124:127], v[36:39]
	v_mfma_f32_16x16x32_bf16 v[40:43], v[88:91], v[124:127], v[40:43]
	v_mfma_f32_16x16x32_bf16 v[48:51], v[12:15], v[104:107], v[48:51]
	v_mfma_f32_16x16x32_bf16 v[16:19], v[92:95], v[104:107], v[16:19]
	v_mfma_f32_16x16x32_bf16 v[20:23], v[12:15], v[112:115], v[20:23]
	v_mfma_f32_16x16x32_bf16 v[24:27], v[92:95], v[112:115], v[24:27]
	v_mfma_f32_16x16x32_bf16 v[28:31], v[12:15], v[120:123], v[28:31]
	v_mfma_f32_16x16x32_bf16 v[32:35], v[92:95], v[120:123], v[32:35]
	v_mfma_f32_16x16x32_bf16 v[36:39], v[12:15], v[128:131], v[36:39]
	v_mfma_f32_16x16x32_bf16 v[40:43], v[92:95], v[128:131], v[40:43]
	s_setprio 0
	s_setprio 1
	s_setprio 0
	s_barrier
	s_mov_b32 m0, s69
	v_lshl_add_u64 v[132:133], v[132:133], 0, s[22:23]
	s_add_u32 s44, s44, 0x10180
	ds_read_b128 v[96:99], v81 offset:49152
	ds_read_b128 v[104:107], v81 offset:50176
	ds_read_b128 v[108:111], v81 offset:51200
	ds_read_b128 v[112:115], v81 offset:52224
	ds_read_b128 v[116:119], v81 offset:53248
	ds_read_b128 v[120:123], v81 offset:54272
	ds_read_b128 v[124:127], v81 offset:55296
	ds_read_b128 v[128:131], v81 offset:56320
	global_load_lds_dwordx4 v[132:133], off
	v_lshl_add_u64 v[132:133], v[134:135], 0, s[22:23]
	s_mov_b32 m0, s70
	s_addc_u32 s45, s45, 0
	global_load_lds_dwordx4 v[132:133], off
	v_lshl_add_u64 v[132:133], s[44:45], 0, v[68:69]
	s_mov_b32 m0, s60
	s_nop 0
	global_load_lds_dwordx4 v[132:133], off
	v_lshl_add_u64 v[132:133], s[44:45], 0, v[64:65]
	s_mov_b32 m0, s61
	s_nop 0
	global_load_lds_dwordx4 v[132:133], off
	v_lshl_add_u64 v[132:133], v[136:137], 0, s[22:23]
	s_mov_b32 m0, s58
	s_nop 0
	global_load_lds_dwordx4 v[132:133], off
	v_lshl_add_u64 v[132:133], v[138:139], 0, s[22:23]
	s_mov_b32 m0, s59
	s_nop 0
	global_load_lds_dwordx4 v[132:133], off
	s_waitcnt vmcnt(8)
	s_waitcnt lgkmcnt(0)
	s_setprio 1
	s_barrier
	v_mfma_f32_16x16x32_bf16 v[44:47], v[88:91], v[96:99], v[44:47]
	v_mfma_f32_16x16x32_bf16 v[52:55], v[8:11], v[108:111], v[52:55]
	v_mfma_f32_16x16x32_bf16 v[56:59], v[88:91], v[108:111], v[56:59]
	v_mfma_f32_16x16x32_bf16 v[60:63], v[8:11], v[116:119], v[60:63]
	v_mfma_f32_16x16x32_bf16 v[0:3], v[8:11], v[124:127], v[0:3]
	v_mfma_f32_16x16x32_bf16 v[4:7], v[88:91], v[124:127], v[4:7]
	v_mfma_f32_16x16x32_bf16 v[100:103], v[8:11], v[96:99], v[100:103]
	v_mfma_f32_16x16x32_bf16 v[44:47], v[92:95], v[104:107], v[44:47]
	v_mfma_f32_16x16x32_bf16 v[52:55], v[12:15], v[112:115], v[52:55]
	v_mfma_f32_16x16x32_bf16 v[56:59], v[92:95], v[112:115], v[56:59]
	v_mfma_f32_16x16x32_bf16 v[60:63], v[12:15], v[120:123], v[60:63]
	v_mfma_f32_16x16x32_bf16 v[84:87], v[88:91], v[116:119], v[84:87]
	v_mfma_f32_16x16x32_bf16 v[0:3], v[12:15], v[128:131], v[0:3]
	v_mfma_f32_16x16x32_bf16 v[4:7], v[92:95], v[128:131], v[4:7]
	v_mfma_f32_16x16x32_bf16 v[100:103], v[12:15], v[104:107], v[100:103]
	v_mfma_f32_16x16x32_bf16 v[84:87], v[92:95], v[120:123], v[84:87]
	s_setprio 0
	s_setprio 1
	s_setprio 0
	s_barrier
	ds_read_b128 v[8:11], v80
	ds_read_b128 v[12:15], v80 offset:1024
	ds_read_b128 v[88:91], v80 offset:2048
	ds_read_b128 v[92:95], v80 offset:3072
	s_add_u32 s42, s42, 0x18180
	s_addc_u32 s43, s43, 0
	s_mov_b32 m0, s65
	v_lshl_add_u64 v[132:133], s[42:43], 0, v[70:71]
	ds_read_b128 v[96:99], v81
	ds_read_b128 v[104:107], v81 offset:1024
	ds_read_b128 v[108:111], v81 offset:2048
	ds_read_b128 v[112:115], v81 offset:3072
	ds_read_b128 v[116:119], v81 offset:4096
	ds_read_b128 v[120:123], v81 offset:5120
	ds_read_b128 v[124:127], v81 offset:6144
	ds_read_b128 v[128:131], v81 offset:7168
	global_load_lds_dwordx4 v[132:133], off
	v_lshl_add_u64 v[132:133], s[42:43], 0, v[66:67]
	s_mov_b32 m0, s66
	s_nop 0
	global_load_lds_dwordx4 v[132:133], off
	s_waitcnt vmcnt(8)
	s_waitcnt lgkmcnt(0)
	s_setprio 1
	s_barrier
	v_mfma_f32_16x16x32_bf16 v[24:27], v[88:91], v[108:111], v[24:27]
	v_mfma_f32_16x16x32_bf16 v[48:51], v[8:11], v[96:99], v[48:51]
	v_mfma_f32_16x16x32_bf16 v[16:19], v[88:91], v[96:99], v[16:19]
	v_mfma_f32_16x16x32_bf16 v[96:99], v[92:95], v[112:115], v[24:27]
	v_mfma_f32_16x16x32_bf16 v[24:27], v[8:11], v[116:119], v[28:31]
	v_mfma_f32_16x16x32_bf16 v[48:51], v[12:15], v[104:107], v[48:51]
	v_mfma_f32_16x16x32_bf16 v[16:19], v[92:95], v[104:107], v[16:19]
	v_mfma_f32_16x16x32_bf16 v[104:107], v[12:15], v[120:123], v[24:27]
	v_mfma_f32_16x16x32_bf16 v[24:27], v[88:91], v[116:119], v[32:35]
	v_mfma_f32_16x16x32_bf16 v[32:35], v[92:95], v[120:123], v[24:27]
	v_mfma_f32_16x16x32_bf16 v[24:27], v[8:11], v[124:127], v[36:39]
	v_mfma_f32_16x16x32_bf16 v[20:23], v[8:11], v[108:111], v[20:23]
	v_mfma_f32_16x16x32_bf16 v[36:39], v[12:15], v[128:131], v[24:27]
	v_mfma_f32_16x16x32_bf16 v[24:27], v[88:91], v[124:127], v[40:43]
	v_mfma_f32_16x16x32_bf16 v[20:23], v[12:15], v[112:115], v[20:23]
	v_mfma_f32_16x16x32_bf16 v[40:43], v[92:95], v[128:131], v[24:27]
	s_setprio 0
	s_setprio 1
	s_setprio 0
	s_barrier
	s_mov_b32 m0, s67
	v_lshl_add_u64 v[144:145], s[46:47], 0, v[68:69]
	s_add_u32 s42, s46, 0x10000
	ds_read_b128 v[24:27], v81 offset:16384
	ds_read_b128 v[28:31], v81 offset:17408
	ds_read_b128 v[108:111], v81 offset:18432
	ds_read_b128 v[112:115], v81 offset:19456
	ds_read_b128 v[116:119], v81 offset:20480
	ds_read_b128 v[120:123], v81 offset:21504
	ds_read_b128 v[124:127], v81 offset:22528
	ds_read_b128 v[128:131], v81 offset:23552
	global_load_lds_dwordx4 v[144:145], off
	v_lshl_add_u64 v[146:147], s[46:47], 0, v[64:65]
	s_mov_b32 m0, s68
	s_addc_u32 s43, s47, 0
	global_load_lds_dwordx4 v[146:147], off
	v_lshl_add_u64 v[132:133], s[42:43], 0, v[68:69]
	s_mov_b32 m0, s53
	v_lshl_add_u64 v[148:149], s[36:37], 0, v[70:71]
	global_load_lds_dwordx4 v[132:133], off
	v_lshl_add_u64 v[132:133], s[42:43], 0, v[64:65]
	s_mov_b32 m0, s54
	v_lshl_add_u64 v[150:151], s[36:37], 0, v[66:67]
	global_load_lds_dwordx4 v[132:133], off
	s_mov_b32 m0, s52
	s_nop 0
	global_load_lds_dwordx4 v[148:149], off
	s_mov_b32 m0, s55
	s_nop 0
	global_load_lds_dwordx4 v[150:151], off
	s_waitcnt vmcnt(8)
	s_waitcnt lgkmcnt(0)
	s_setprio 1
	s_barrier
	v_mfma_f32_16x16x32_bf16 v[100:103], v[8:11], v[24:27], v[100:103]
	v_mfma_f32_16x16x32_bf16 v[24:27], v[88:91], v[24:27], v[44:47]
	v_mfma_f32_16x16x32_bf16 v[44:47], v[92:95], v[28:31], v[24:27]
	v_mfma_f32_16x16x32_bf16 v[24:27], v[8:11], v[108:111], v[52:55]
	v_mfma_f32_16x16x32_bf16 v[52:55], v[12:15], v[112:115], v[24:27]
	v_mfma_f32_16x16x32_bf16 v[24:27], v[88:91], v[108:111], v[56:59]
	v_mfma_f32_16x16x32_bf16 v[108:111], v[92:95], v[112:115], v[24:27]
	v_mfma_f32_16x16x32_bf16 v[24:27], v[8:11], v[116:119], v[60:63]
	v_mfma_f32_16x16x32_bf16 v[0:3], v[8:11], v[124:127], v[0:3]
	v_mfma_f32_16x16x32_bf16 v[112:115], v[12:15], v[120:123], v[24:27]
	v_mfma_f32_16x16x32_bf16 v[24:27], v[88:91], v[116:119], v[84:87]
	v_mfma_f32_16x16x32_bf16 v[116:119], v[12:15], v[128:131], v[0:3]
	v_mfma_f32_16x16x32_bf16 v[0:3], v[88:91], v[124:127], v[4:7]
	v_mfma_f32_16x16x32_bf16 v[100:103], v[12:15], v[28:31], v[100:103]
	v_mfma_f32_16x16x32_bf16 v[84:87], v[92:95], v[120:123], v[24:27]
	v_mfma_f32_16x16x32_bf16 v[88:91], v[92:95], v[128:131], v[0:3]
	s_setprio 0
	s_setprio 1
	s_setprio 0
	s_barrier
	ds_read_b128 v[92:95], v82
	ds_read_b128 v[120:123], v82 offset:1024
	ds_read_b128 v[124:127], v82 offset:2048
	ds_read_b128 v[128:131], v82 offset:3072
	s_add_u32 s42, s36, 0x18000
	s_addc_u32 s43, s37, 0
	s_mov_b32 m0, s56
	v_lshl_add_u64 v[24:25], s[42:43], 0, v[70:71]
	ds_read_b128 v[0:3], v81 offset:32768
	ds_read_b128 v[4:7], v81 offset:33792
	ds_read_b128 v[8:11], v81 offset:34816
	ds_read_b128 v[12:15], v81 offset:35840
	ds_read_b128 v[56:59], v81 offset:36864
	ds_read_b128 v[60:63], v81 offset:37888
	ds_read_b128 v[132:135], v81 offset:38912
	ds_read_b128 v[136:139], v81 offset:39936
	global_load_lds_dwordx4 v[24:25], off
	v_lshl_add_u64 v[24:25], s[42:43], 0, v[66:67]
	s_mov_b32 m0, s57
	s_nop 0
	global_load_lds_dwordx4 v[24:25], off
	s_waitcnt vmcnt(8)
	s_waitcnt lgkmcnt(0)
	s_setprio 1
	s_barrier
	v_mfma_f32_16x16x32_bf16 v[24:27], v[92:95], v[0:3], v[48:51]
	v_mfma_f32_16x16x32_bf16 v[0:3], v[124:127], v[0:3], v[16:19]
	v_mfma_f32_16x16x32_bf16 v[28:31], v[128:131], v[4:7], v[0:3]
	v_mfma_f32_16x16x32_bf16 v[0:3], v[92:95], v[8:11], v[20:23]
	v_mfma_f32_16x16x32_bf16 v[16:19], v[120:123], v[12:15], v[0:3]
	v_mfma_f32_16x16x32_bf16 v[0:3], v[124:127], v[8:11], v[96:99]
	v_mfma_f32_16x16x32_bf16 v[20:23], v[128:131], v[12:15], v[0:3]
	v_mfma_f32_16x16x32_bf16 v[0:3], v[92:95], v[56:59], v[104:107]
	v_mfma_f32_16x16x32_bf16 v[8:11], v[120:123], v[60:63], v[0:3]
	v_mfma_f32_16x16x32_bf16 v[0:3], v[124:127], v[56:59], v[32:35]
	v_mfma_f32_16x16x32_bf16 v[24:27], v[120:123], v[4:7], v[24:27]
	v_mfma_f32_16x16x32_bf16 v[12:15], v[128:131], v[60:63], v[0:3]
	v_mfma_f32_16x16x32_bf16 v[0:3], v[92:95], v[132:135], v[36:39]
	v_mfma_f32_16x16x32_bf16 v[4:7], v[124:127], v[132:135], v[40:43]
	v_mfma_f32_16x16x32_bf16 v[0:3], v[120:123], v[136:139], v[0:3]
	v_mfma_f32_16x16x32_bf16 v[4:7], v[128:131], v[136:139], v[4:7]
	s_setprio 0
	s_setprio 1
	s_setprio 0
	s_barrier
	s_mov_b32 m0, s69
	v_lshl_add_u64 v[48:49], v[144:145], 0, s[16:17]
	s_add_u32 s42, s46, 0x10080
	ds_read_b128 v[32:35], v81 offset:49152
	ds_read_b128 v[36:39], v81 offset:50176
	ds_read_b128 v[40:43], v81 offset:51200
	ds_read_b128 v[96:99], v81 offset:52224
	ds_read_b128 v[104:107], v81 offset:53248
	ds_read_b128 v[132:135], v81 offset:54272
	ds_read_b128 v[136:139], v81 offset:55296
	ds_read_b128 v[140:143], v81 offset:56320
	global_load_lds_dwordx4 v[48:49], off
	v_lshl_add_u64 v[48:49], v[146:147], 0, s[16:17]
	s_mov_b32 m0, s70
	s_addc_u32 s43, s47, 0
	global_load_lds_dwordx4 v[48:49], off
	v_lshl_add_u64 v[48:49], s[42:43], 0, v[68:69]
	s_mov_b32 m0, s60
	s_nop 0
	global_load_lds_dwordx4 v[48:49], off
	v_lshl_add_u64 v[48:49], s[42:43], 0, v[64:65]
	s_mov_b32 m0, s61
	s_nop 0
	global_load_lds_dwordx4 v[48:49], off
	v_lshl_add_u64 v[48:49], v[148:149], 0, s[16:17]
	s_mov_b32 m0, s58
	s_nop 0
	global_load_lds_dwordx4 v[48:49], off
	v_lshl_add_u64 v[48:49], v[150:151], 0, s[16:17]
	s_mov_b32 m0, s59
	s_nop 0
	global_load_lds_dwordx4 v[48:49], off
	s_waitcnt vmcnt(8)
	s_waitcnt lgkmcnt(0)
	s_setprio 1
	s_barrier
	v_mfma_f32_16x16x32_bf16 v[48:51], v[92:95], v[32:35], v[100:103]
	v_mfma_f32_16x16x32_bf16 v[32:35], v[124:127], v[32:35], v[44:47]
	v_mfma_f32_16x16x32_bf16 v[60:63], v[128:131], v[36:39], v[32:35]
	v_mfma_f32_16x16x32_bf16 v[32:35], v[92:95], v[40:43], v[52:55]
	v_mfma_f32_16x16x32_bf16 v[56:59], v[120:123], v[36:39], v[48:51]
	v_mfma_f32_16x16x32_bf16 v[48:51], v[120:123], v[96:99], v[32:35]
	v_mfma_f32_16x16x32_bf16 v[32:35], v[124:127], v[40:43], v[108:111]
	v_mfma_f32_16x16x32_bf16 v[52:55], v[128:131], v[96:99], v[32:35]
	v_mfma_f32_16x16x32_bf16 v[32:35], v[92:95], v[104:107], v[112:115]
	v_mfma_f32_16x16x32_bf16 v[40:43], v[120:123], v[132:135], v[32:35]
	v_mfma_f32_16x16x32_bf16 v[32:35], v[124:127], v[104:107], v[84:87]
	v_mfma_f32_16x16x32_bf16 v[44:47], v[128:131], v[132:135], v[32:35]
	v_mfma_f32_16x16x32_bf16 v[32:35], v[92:95], v[136:139], v[116:119]
	v_mfma_f32_16x16x32_bf16 v[36:39], v[124:127], v[136:139], v[88:91]
	v_mfma_f32_16x16x32_bf16 v[32:35], v[120:123], v[140:143], v[32:35]
	v_mfma_f32_16x16x32_bf16 v[36:39], v[128:131], v[140:143], v[36:39]
	s_setprio 0
	s_setprio 1
	s_setprio 0
	s_barrier
	s_and_b64 vcc, exec, s[6:7]
	s_cbranch_vccnz .LBB0_975
	s_barrier

.LBB0_1110:
	v_add_u32_e32 v138, s60, v78
	s_lshr_b64 s[38:39], s[38:39], 2
	ds_read_b128 v[80:83], v138
	ds_read_b128 v[84:87], v138 offset:1024
	ds_read_b128 v[88:91], v138 offset:2048
	ds_read_b128 v[92:95], v138 offset:3072
	s_and_b64 s[40:41], s[6:7], exec
	s_cselect_b32 s9, s38, s42
	s_ashr_i64 s[40:41], s[8:9], 15
	s_add_u32 s40, s46, s40
	s_addc_u32 s41, s47, s41
	s_and_b64 s[42:43], s[6:7], exec
	s_cselect_b32 s43, s41, s21
	s_cselect_b32 s42, s40, s20
	s_add_u32 s70, s22, 0x18080
	s_addc_u32 s71, s23, 0
	s_mov_b32 m0, s61
	v_lshl_add_u64 v[128:129], s[70:71], 0, v[70:71]
	ds_read_b128 v[96:99], v79
	ds_read_b128 v[100:103], v79 offset:1024
	ds_read_b128 v[104:107], v79 offset:2048
	ds_read_b128 v[108:111], v79 offset:3072
	ds_read_b128 v[112:115], v79 offset:4096
	ds_read_b128 v[116:119], v79 offset:5120
	ds_read_b128 v[120:123], v79 offset:6144
	ds_read_b128 v[124:127], v79 offset:7168
	global_load_lds_dwordx4 v[128:129], off
	v_lshl_add_u64 v[128:129], s[70:71], 0, v[66:67]
	s_mov_b32 m0, s62
	s_nop 0
	global_load_lds_dwordx4 v[128:129], off
	s_waitcnt vmcnt(8)
	s_waitcnt lgkmcnt(0)
	s_setprio 1
	s_barrier
	v_mfma_f32_16x16x32_bf16 v[60:63], v[80:83], v[96:99], v[60:63]
	v_mfma_f32_16x16x32_bf16 v[56:59], v[88:91], v[96:99], v[56:59]
	v_mfma_f32_16x16x32_bf16 v[52:55], v[80:83], v[104:107], v[52:55]
	v_mfma_f32_16x16x32_bf16 v[48:51], v[88:91], v[104:107], v[48:51]
	v_mfma_f32_16x16x32_bf16 v[44:47], v[80:83], v[112:115], v[44:47]
	v_mfma_f32_16x16x32_bf16 v[40:43], v[88:91], v[112:115], v[40:43]
	v_mfma_f32_16x16x32_bf16 v[36:39], v[80:83], v[120:123], v[36:39]
	v_mfma_f32_16x16x32_bf16 v[32:35], v[88:91], v[120:123], v[32:35]
	v_mfma_f32_16x16x32_bf16 v[60:63], v[84:87], v[100:103], v[60:63]
	v_mfma_f32_16x16x32_bf16 v[56:59], v[92:95], v[100:103], v[56:59]
	v_mfma_f32_16x16x32_bf16 v[52:55], v[84:87], v[108:111], v[52:55]
	v_mfma_f32_16x16x32_bf16 v[48:51], v[92:95], v[108:111], v[48:51]
	v_mfma_f32_16x16x32_bf16 v[44:47], v[84:87], v[116:119], v[44:47]
	v_mfma_f32_16x16x32_bf16 v[40:43], v[92:95], v[116:119], v[40:43]
	v_mfma_f32_16x16x32_bf16 v[36:39], v[84:87], v[124:127], v[36:39]
	v_mfma_f32_16x16x32_bf16 v[32:35], v[92:95], v[124:127], v[32:35]
	s_setprio 0
	s_setprio 1
	s_setprio 0
	s_barrier
	v_lshl_add_u64 v[128:129], s[20:21], 0, v[68:69]
	s_mov_b32 m0, s63
	v_lshl_add_u64 v[130:131], v[128:129], 0, s[16:17]
	ds_read_b128 v[96:99], v79 offset:16384
	ds_read_b128 v[100:103], v79 offset:17408
	ds_read_b128 v[104:107], v79 offset:18432
	ds_read_b128 v[108:111], v79 offset:19456
	ds_read_b128 v[112:115], v79 offset:20480
	ds_read_b128 v[116:119], v79 offset:21504
	ds_read_b128 v[120:123], v79 offset:22528
	ds_read_b128 v[124:127], v79 offset:23552
	global_load_lds_dwordx4 v[130:131], off
	v_lshl_add_u64 v[130:131], s[20:21], 0, v[64:65]
	s_add_u32 s70, s20, 0x10100
	v_lshl_add_u64 v[132:133], v[130:131], 0, s[16:17]
	s_mov_b32 m0, s64
	s_addc_u32 s71, s21, 0
	global_load_lds_dwordx4 v[132:133], off
	v_lshl_add_u64 v[132:133], s[70:71], 0, v[68:69]
	s_mov_b32 m0, s50
	s_nop 0
	global_load_lds_dwordx4 v[132:133], off
	v_lshl_add_u64 v[132:133], s[70:71], 0, v[64:65]
	s_mov_b32 m0, s51
	s_nop 0
	global_load_lds_dwordx4 v[132:133], off
	v_lshl_add_u64 v[132:133], s[22:23], 0, v[70:71]
	v_lshl_add_u64 v[134:135], v[132:133], 0, s[16:17]
	s_mov_b32 m0, s49
	s_nop 0
	global_load_lds_dwordx4 v[134:135], off
	v_lshl_add_u64 v[134:135], s[22:23], 0, v[66:67]
	v_lshl_add_u64 v[136:137], v[134:135], 0, s[16:17]
	s_mov_b32 m0, s52
	s_nop 0
	global_load_lds_dwordx4 v[136:137], off
	s_waitcnt vmcnt(8)
	s_waitcnt lgkmcnt(0)
	s_setprio 1
	s_barrier
	v_mfma_f32_16x16x32_bf16 v[28:31], v[80:83], v[96:99], v[28:31]
	v_mfma_f32_16x16x32_bf16 v[24:27], v[88:91], v[96:99], v[24:27]
	v_mfma_f32_16x16x32_bf16 v[20:23], v[80:83], v[104:107], v[20:23]
	v_mfma_f32_16x16x32_bf16 v[16:19], v[88:91], v[104:107], v[16:19]
	v_mfma_f32_16x16x32_bf16 v[12:15], v[80:83], v[112:115], v[12:15]
	v_mfma_f32_16x16x32_bf16 v[8:11], v[88:91], v[112:115], v[8:11]
	v_mfma_f32_16x16x32_bf16 v[4:7], v[80:83], v[120:123], v[4:7]
	v_mfma_f32_16x16x32_bf16 v[0:3], v[88:91], v[120:123], v[0:3]
	v_mfma_f32_16x16x32_bf16 v[28:31], v[84:87], v[100:103], v[28:31]
	v_mfma_f32_16x16x32_bf16 v[24:27], v[92:95], v[100:103], v[24:27]
	v_mfma_f32_16x16x32_bf16 v[20:23], v[84:87], v[108:111], v[20:23]
	v_mfma_f32_16x16x32_bf16 v[16:19], v[92:95], v[108:111], v[16:19]
	v_mfma_f32_16x16x32_bf16 v[12:15], v[84:87], v[116:119], v[12:15]
	v_mfma_f32_16x16x32_bf16 v[8:11], v[92:95], v[116:119], v[8:11]
	v_mfma_f32_16x16x32_bf16 v[4:7], v[84:87], v[124:127], v[4:7]
	v_mfma_f32_16x16x32_bf16 v[0:3], v[92:95], v[124:127], v[0:3]
	s_setprio 0
	s_setprio 1
	s_setprio 0
	s_barrier
	v_add_u32_e32 v139, s65, v78
	ds_read_b128 v[80:83], v139
	ds_read_b128 v[84:87], v139 offset:1024
	ds_read_b128 v[88:91], v139 offset:2048
	ds_read_b128 v[92:95], v139 offset:3072
	s_add_u32 s70, s22, 0x18100
	s_addc_u32 s71, s23, 0
	s_mov_b32 m0, s53
	v_lshl_add_u64 v[136:137], s[70:71], 0, v[70:71]
	ds_read_b128 v[96:99], v79 offset:32768
	ds_read_b128 v[100:103], v79 offset:33792
	ds_read_b128 v[104:107], v79 offset:34816
	ds_read_b128 v[108:111], v79 offset:35840
	ds_read_b128 v[112:115], v79 offset:36864
	ds_read_b128 v[116:119], v79 offset:37888
	ds_read_b128 v[120:123], v79 offset:38912
	ds_read_b128 v[124:127], v79 offset:39936
	global_load_lds_dwordx4 v[136:137], off
	v_lshl_add_u64 v[136:137], s[70:71], 0, v[66:67]
	s_mov_b32 m0, s54
	s_nop 0
	global_load_lds_dwordx4 v[136:137], off
	s_waitcnt vmcnt(8)
	s_waitcnt lgkmcnt(0)
	s_setprio 1
	s_barrier
	v_mfma_f32_16x16x32_bf16 v[60:63], v[80:83], v[96:99], v[60:63]
	v_mfma_f32_16x16x32_bf16 v[56:59], v[88:91], v[96:99], v[56:59]
	v_mfma_f32_16x16x32_bf16 v[52:55], v[80:83], v[104:107], v[52:55]
	v_mfma_f32_16x16x32_bf16 v[48:51], v[88:91], v[104:107], v[48:51]
	v_mfma_f32_16x16x32_bf16 v[44:47], v[80:83], v[112:115], v[44:47]
	v_mfma_f32_16x16x32_bf16 v[40:43], v[88:91], v[112:115], v[40:43]
	v_mfma_f32_16x16x32_bf16 v[36:39], v[80:83], v[120:123], v[36:39]
	v_mfma_f32_16x16x32_bf16 v[32:35], v[88:91], v[120:123], v[32:35]
	v_mfma_f32_16x16x32_bf16 v[60:63], v[84:87], v[100:103], v[60:63]
	v_mfma_f32_16x16x32_bf16 v[56:59], v[92:95], v[100:103], v[56:59]
	v_mfma_f32_16x16x32_bf16 v[52:55], v[84:87], v[108:111], v[52:55]
	v_mfma_f32_16x16x32_bf16 v[48:51], v[92:95], v[108:111], v[48:51]
	v_mfma_f32_16x16x32_bf16 v[44:47], v[84:87], v[116:119], v[44:47]
	v_mfma_f32_16x16x32_bf16 v[40:43], v[92:95], v[116:119], v[40:43]
	v_mfma_f32_16x16x32_bf16 v[36:39], v[84:87], v[124:127], v[36:39]
	v_mfma_f32_16x16x32_bf16 v[32:35], v[92:95], v[124:127], v[32:35]
	s_setprio 0
	s_setprio 1
	s_setprio 0
	s_barrier
	s_mov_b32 m0, s66
	v_lshl_add_u64 v[128:129], v[128:129], 0, s[18:19]
	s_add_u32 s70, s20, 0x10180
	ds_read_b128 v[96:99], v79 offset:49152
	ds_read_b128 v[100:103], v79 offset:50176
	ds_read_b128 v[104:107], v79 offset:51200
	ds_read_b128 v[108:111], v79 offset:52224
	ds_read_b128 v[112:115], v79 offset:53248
	ds_read_b128 v[116:119], v79 offset:54272
	ds_read_b128 v[120:123], v79 offset:55296
	ds_read_b128 v[124:127], v79 offset:56320
	global_load_lds_dwordx4 v[128:129], off
	v_lshl_add_u64 v[128:129], v[130:131], 0, s[18:19]
	s_mov_b32 m0, s67
	s_addc_u32 s71, s21, 0
	global_load_lds_dwordx4 v[128:129], off
	v_lshl_add_u64 v[128:129], s[70:71], 0, v[68:69]
	s_mov_b32 m0, s58
	s_nop 0
	global_load_lds_dwordx4 v[128:129], off
	v_lshl_add_u64 v[128:129], s[70:71], 0, v[64:65]
	s_mov_b32 m0, s59
	s_nop 0
	global_load_lds_dwordx4 v[128:129], off
	v_lshl_add_u64 v[128:129], v[132:133], 0, s[18:19]
	s_mov_b32 m0, s56
	s_nop 0
	global_load_lds_dwordx4 v[128:129], off
	v_lshl_add_u64 v[128:129], v[134:135], 0, s[18:19]
	s_mov_b32 m0, s57
	s_nop 0
	global_load_lds_dwordx4 v[128:129], off
	s_waitcnt vmcnt(8)
	s_waitcnt lgkmcnt(0)
	s_setprio 1
	s_barrier
	v_mfma_f32_16x16x32_bf16 v[28:31], v[80:83], v[96:99], v[28:31]
	v_mfma_f32_16x16x32_bf16 v[24:27], v[88:91], v[96:99], v[24:27]
	v_mfma_f32_16x16x32_bf16 v[20:23], v[80:83], v[104:107], v[20:23]
	v_mfma_f32_16x16x32_bf16 v[16:19], v[88:91], v[104:107], v[16:19]
	v_mfma_f32_16x16x32_bf16 v[12:15], v[80:83], v[112:115], v[12:15]
	v_mfma_f32_16x16x32_bf16 v[8:11], v[88:91], v[112:115], v[8:11]
	v_mfma_f32_16x16x32_bf16 v[4:7], v[80:83], v[120:123], v[4:7]
	v_mfma_f32_16x16x32_bf16 v[0:3], v[88:91], v[120:123], v[0:3]
	v_mfma_f32_16x16x32_bf16 v[28:31], v[84:87], v[100:103], v[28:31]
	v_mfma_f32_16x16x32_bf16 v[24:27], v[92:95], v[100:103], v[24:27]
	v_mfma_f32_16x16x32_bf16 v[20:23], v[84:87], v[108:111], v[20:23]
	v_mfma_f32_16x16x32_bf16 v[16:19], v[92:95], v[108:111], v[16:19]
	v_mfma_f32_16x16x32_bf16 v[12:15], v[84:87], v[116:119], v[12:15]
	v_mfma_f32_16x16x32_bf16 v[8:11], v[92:95], v[116:119], v[8:11]
	v_mfma_f32_16x16x32_bf16 v[4:7], v[84:87], v[124:127], v[4:7]
	v_mfma_f32_16x16x32_bf16 v[0:3], v[92:95], v[124:127], v[0:3]
	s_setprio 0
	s_setprio 1
	s_setprio 0
	s_barrier
	ds_read_b128 v[80:83], v138
	ds_read_b128 v[84:87], v138 offset:1024
	ds_read_b128 v[88:91], v138 offset:2048
	ds_read_b128 v[92:95], v138 offset:3072
	s_add_u32 s70, s22, 0x18180
	s_addc_u32 s71, s23, 0
	s_mov_b32 m0, s61
	v_lshl_add_u64 v[128:129], s[70:71], 0, v[70:71]
	ds_read_b128 v[96:99], v79
	ds_read_b128 v[100:103], v79 offset:1024
	ds_read_b128 v[104:107], v79 offset:2048
	ds_read_b128 v[108:111], v79 offset:3072
	ds_read_b128 v[112:115], v79 offset:4096
	ds_read_b128 v[116:119], v79 offset:5120
	ds_read_b128 v[120:123], v79 offset:6144
	ds_read_b128 v[124:127], v79 offset:7168
	global_load_lds_dwordx4 v[128:129], off
	v_lshl_add_u64 v[128:129], s[70:71], 0, v[66:67]
	s_mov_b32 m0, s62
	s_nop 0
	global_load_lds_dwordx4 v[128:129], off
	s_waitcnt vmcnt(8)
	s_waitcnt lgkmcnt(0)
	s_setprio 1
	s_barrier
	v_mfma_f32_16x16x32_bf16 v[60:63], v[80:83], v[96:99], v[60:63]
	v_mfma_f32_16x16x32_bf16 v[56:59], v[88:91], v[96:99], v[56:59]
	v_mfma_f32_16x16x32_bf16 v[52:55], v[80:83], v[104:107], v[52:55]
	v_mfma_f32_16x16x32_bf16 v[48:51], v[88:91], v[104:107], v[48:51]
	v_mfma_f32_16x16x32_bf16 v[44:47], v[80:83], v[112:115], v[44:47]
	v_mfma_f32_16x16x32_bf16 v[40:43], v[88:91], v[112:115], v[40:43]
	v_mfma_f32_16x16x32_bf16 v[36:39], v[80:83], v[120:123], v[36:39]
	v_mfma_f32_16x16x32_bf16 v[32:35], v[88:91], v[120:123], v[32:35]
	v_mfma_f32_16x16x32_bf16 v[60:63], v[84:87], v[100:103], v[60:63]
	v_mfma_f32_16x16x32_bf16 v[56:59], v[92:95], v[100:103], v[56:59]
	v_mfma_f32_16x16x32_bf16 v[52:55], v[84:87], v[108:111], v[52:55]
	v_mfma_f32_16x16x32_bf16 v[48:51], v[92:95], v[108:111], v[48:51]
	v_mfma_f32_16x16x32_bf16 v[44:47], v[84:87], v[116:119], v[44:47]
	v_mfma_f32_16x16x32_bf16 v[40:43], v[92:95], v[116:119], v[40:43]
	v_mfma_f32_16x16x32_bf16 v[36:39], v[84:87], v[124:127], v[36:39]
	v_mfma_f32_16x16x32_bf16 v[32:35], v[92:95], v[124:127], v[32:35]
	s_setprio 0
	s_setprio 1
	s_setprio 0
	s_barrier
	s_mov_b32 m0, s63
	v_lshl_add_u64 v[128:129], s[42:43], 0, v[68:69]
	s_add_u32 s70, s42, 0x10000
	ds_read_b128 v[96:99], v79 offset:16384
	ds_read_b128 v[100:103], v79 offset:17408
	ds_read_b128 v[104:107], v79 offset:18432
	ds_read_b128 v[108:111], v79 offset:19456
	ds_read_b128 v[112:115], v79 offset:20480
	ds_read_b128 v[116:119], v79 offset:21504
	ds_read_b128 v[120:123], v79 offset:22528
	ds_read_b128 v[124:127], v79 offset:23552
	global_load_lds_dwordx4 v[128:129], off
	v_lshl_add_u64 v[130:131], s[42:43], 0, v[64:65]
	s_mov_b32 m0, s64
	s_addc_u32 s71, s43, 0
	global_load_lds_dwordx4 v[130:131], off
	v_lshl_add_u64 v[132:133], s[70:71], 0, v[68:69]
	s_mov_b32 m0, s50
	v_lshl_add_u64 v[134:135], s[24:25], 0, v[66:67]
	global_load_lds_dwordx4 v[132:133], off
	v_lshl_add_u64 v[132:133], s[70:71], 0, v[64:65]
	s_mov_b32 m0, s51
	s_nop 0
	global_load_lds_dwordx4 v[132:133], off
	v_lshl_add_u64 v[132:133], s[24:25], 0, v[70:71]
	s_mov_b32 m0, s49
	s_nop 0
	global_load_lds_dwordx4 v[132:133], off
	s_mov_b32 m0, s52
	s_nop 0
	global_load_lds_dwordx4 v[134:135], off
	s_waitcnt vmcnt(8)
	s_waitcnt lgkmcnt(0)
	s_setprio 1
	s_barrier
	v_mfma_f32_16x16x32_bf16 v[28:31], v[80:83], v[96:99], v[28:31]
	v_mfma_f32_16x16x32_bf16 v[24:27], v[88:91], v[96:99], v[24:27]
	v_mfma_f32_16x16x32_bf16 v[20:23], v[80:83], v[104:107], v[20:23]
	v_mfma_f32_16x16x32_bf16 v[16:19], v[88:91], v[104:107], v[16:19]
	v_mfma_f32_16x16x32_bf16 v[12:15], v[80:83], v[112:115], v[12:15]
	v_mfma_f32_16x16x32_bf16 v[8:11], v[88:91], v[112:115], v[8:11]
	v_mfma_f32_16x16x32_bf16 v[4:7], v[80:83], v[120:123], v[4:7]
	v_mfma_f32_16x16x32_bf16 v[0:3], v[88:91], v[120:123], v[0:3]
	v_mfma_f32_16x16x32_bf16 v[28:31], v[84:87], v[100:103], v[28:31]
	v_mfma_f32_16x16x32_bf16 v[24:27], v[92:95], v[100:103], v[24:27]
	v_mfma_f32_16x16x32_bf16 v[20:23], v[84:87], v[108:111], v[20:23]
	v_mfma_f32_16x16x32_bf16 v[16:19], v[92:95], v[108:111], v[16:19]
	v_mfma_f32_16x16x32_bf16 v[12:15], v[84:87], v[116:119], v[12:15]
	v_mfma_f32_16x16x32_bf16 v[8:11], v[92:95], v[116:119], v[8:11]
	v_mfma_f32_16x16x32_bf16 v[4:7], v[84:87], v[124:127], v[4:7]
	v_mfma_f32_16x16x32_bf16 v[0:3], v[92:95], v[124:127], v[0:3]
	s_setprio 0
	s_setprio 1
	s_setprio 0
	s_barrier
	ds_read_b128 v[80:83], v139
	ds_read_b128 v[84:87], v139 offset:1024
	ds_read_b128 v[88:91], v139 offset:2048
	ds_read_b128 v[92:95], v139 offset:3072
	s_add_u32 s70, s24, 0x18000
	s_addc_u32 s71, s25, 0
	s_mov_b32 m0, s53
	v_lshl_add_u64 v[136:137], s[70:71], 0, v[70:71]
	ds_read_b128 v[96:99], v79 offset:32768
	ds_read_b128 v[100:103], v79 offset:33792
	ds_read_b128 v[104:107], v79 offset:34816
	ds_read_b128 v[108:111], v79 offset:35840
	ds_read_b128 v[112:115], v79 offset:36864
	ds_read_b128 v[116:119], v79 offset:37888
	ds_read_b128 v[120:123], v79 offset:38912
	ds_read_b128 v[124:127], v79 offset:39936
	global_load_lds_dwordx4 v[136:137], off
	v_lshl_add_u64 v[136:137], s[70:71], 0, v[66:67]
	s_mov_b32 m0, s54
	s_nop 0
	global_load_lds_dwordx4 v[136:137], off
	s_waitcnt vmcnt(8)
	s_waitcnt lgkmcnt(0)
	s_setprio 1
	s_barrier
	v_mfma_f32_16x16x32_bf16 v[60:63], v[80:83], v[96:99], v[60:63]
	v_mfma_f32_16x16x32_bf16 v[56:59], v[88:91], v[96:99], v[56:59]
	v_mfma_f32_16x16x32_bf16 v[52:55], v[80:83], v[104:107], v[52:55]
	v_mfma_f32_16x16x32_bf16 v[48:51], v[88:91], v[104:107], v[48:51]
	v_mfma_f32_16x16x32_bf16 v[44:47], v[80:83], v[112:115], v[44:47]
	v_mfma_f32_16x16x32_bf16 v[40:43], v[88:91], v[112:115], v[40:43]
	v_mfma_f32_16x16x32_bf16 v[36:39], v[80:83], v[120:123], v[36:39]
	v_mfma_f32_16x16x32_bf16 v[32:35], v[88:91], v[120:123], v[32:35]
	v_mfma_f32_16x16x32_bf16 v[60:63], v[84:87], v[100:103], v[60:63]
	v_mfma_f32_16x16x32_bf16 v[56:59], v[92:95], v[100:103], v[56:59]
	v_mfma_f32_16x16x32_bf16 v[52:55], v[84:87], v[108:111], v[52:55]
	v_mfma_f32_16x16x32_bf16 v[48:51], v[92:95], v[108:111], v[48:51]
	v_mfma_f32_16x16x32_bf16 v[44:47], v[84:87], v[116:119], v[44:47]
	v_mfma_f32_16x16x32_bf16 v[40:43], v[92:95], v[116:119], v[40:43]
	v_mfma_f32_16x16x32_bf16 v[36:39], v[84:87], v[124:127], v[36:39]
	v_mfma_f32_16x16x32_bf16 v[32:35], v[92:95], v[124:127], v[32:35]
	s_setprio 0
	s_setprio 1
	s_setprio 0
	s_barrier
	s_mov_b32 m0, s66
	v_lshl_add_u64 v[128:129], v[128:129], 0, s[12:13]
	s_add_u32 s42, s42, 0x10080
	ds_read_b128 v[96:99], v79 offset:49152
	ds_read_b128 v[100:103], v79 offset:50176
	ds_read_b128 v[104:107], v79 offset:51200
	ds_read_b128 v[108:111], v79 offset:52224
	ds_read_b128 v[112:115], v79 offset:53248
	ds_read_b128 v[116:119], v79 offset:54272
	ds_read_b128 v[120:123], v79 offset:55296
	ds_read_b128 v[124:127], v79 offset:56320
	global_load_lds_dwordx4 v[128:129], off
	v_lshl_add_u64 v[128:129], v[130:131], 0, s[12:13]
	s_mov_b32 m0, s67
	s_addc_u32 s43, s43, 0
	global_load_lds_dwordx4 v[128:129], off
	v_lshl_add_u64 v[128:129], s[42:43], 0, v[68:69]
	s_mov_b32 m0, s58
	s_nop 0
	global_load_lds_dwordx4 v[128:129], off
	v_lshl_add_u64 v[128:129], s[42:43], 0, v[64:65]
	s_mov_b32 m0, s59
	s_nop 0
	global_load_lds_dwordx4 v[128:129], off
	v_lshl_add_u64 v[128:129], v[132:133], 0, s[12:13]
	s_mov_b32 m0, s56
	s_nop 0
	global_load_lds_dwordx4 v[128:129], off
	v_lshl_add_u64 v[128:129], v[134:135], 0, s[12:13]
	s_mov_b32 m0, s57
	s_nop 0
	global_load_lds_dwordx4 v[128:129], off
	s_waitcnt vmcnt(8)
	s_waitcnt lgkmcnt(0)
	s_setprio 1
	s_barrier
	v_mfma_f32_16x16x32_bf16 v[28:31], v[80:83], v[96:99], v[28:31]
	v_mfma_f32_16x16x32_bf16 v[24:27], v[88:91], v[96:99], v[24:27]
	v_mfma_f32_16x16x32_bf16 v[20:23], v[80:83], v[104:107], v[20:23]
	v_mfma_f32_16x16x32_bf16 v[16:19], v[88:91], v[104:107], v[16:19]
	v_mfma_f32_16x16x32_bf16 v[12:15], v[80:83], v[112:115], v[12:15]
	v_mfma_f32_16x16x32_bf16 v[8:11], v[88:91], v[112:115], v[8:11]
	v_mfma_f32_16x16x32_bf16 v[4:7], v[80:83], v[120:123], v[4:7]
	v_mfma_f32_16x16x32_bf16 v[0:3], v[88:91], v[120:123], v[0:3]
	v_mfma_f32_16x16x32_bf16 v[28:31], v[84:87], v[100:103], v[28:31]
	v_mfma_f32_16x16x32_bf16 v[24:27], v[92:95], v[100:103], v[24:27]
	v_mfma_f32_16x16x32_bf16 v[20:23], v[84:87], v[108:111], v[20:23]
	v_mfma_f32_16x16x32_bf16 v[16:19], v[92:95], v[108:111], v[16:19]
	v_mfma_f32_16x16x32_bf16 v[12:15], v[84:87], v[116:119], v[12:15]
	v_mfma_f32_16x16x32_bf16 v[8:11], v[92:95], v[116:119], v[8:11]
	v_mfma_f32_16x16x32_bf16 v[4:7], v[84:87], v[124:127], v[4:7]
	v_mfma_f32_16x16x32_bf16 v[0:3], v[92:95], v[124:127], v[0:3]
	s_setprio 0
	s_setprio 1
	s_setprio 0
	s_barrier
	s_andn2_b64 vcc, exec, s[14:15]
	s_cbranch_vccnz .LBB0_1112
	s_barrier

.LBB0_1146:
	ds_read_b128 v[8:11], v144
	ds_read_b128 v[12:15], v144 offset:1024
	ds_read_b128 v[16:19], v144 offset:2048
	ds_read_b128 v[20:23], v144 offset:3072
	ds_read_b128 v[24:27], v145
	ds_read_b128 v[28:31], v145 offset:1024
	ds_read_b128 v[32:35], v145 offset:2048
	ds_read_b128 v[36:39], v145 offset:3072
	s_add_u32 s66, s44, 0x18080
	s_addc_u32 s67, s45, 0
	s_mov_b32 m0, s64
	v_lshl_add_u64 v[64:65], s[66:67], 0, v[134:135]
	s_add_i32 s43, s53, 0xe000
	ds_read_b128 v[0:3], v141
	ds_read_b128 v[4:7], v141 offset:1024
	ds_read_b128 v[40:43], v141 offset:2048
	ds_read_b128 v[44:47], v141 offset:3072
	ds_read_b128 v[48:51], v141 offset:4096
	ds_read_b128 v[52:55], v141 offset:5120
	ds_read_b128 v[56:59], v141 offset:6144
	ds_read_b128 v[60:63], v141 offset:7168
	global_load_lds_dwordx4 v[64:65], off
	v_lshl_add_u64 v[64:65], s[66:67], 0, v[130:131]
	s_mov_b32 m0, s43
	s_nop 0
	global_load_lds_dwordx4 v[64:65], off
	s_waitcnt vmcnt(8)
	s_waitcnt lgkmcnt(0)
	s_setprio 1
	s_barrier
	v_mfma_f32_16x16x32_bf16 v[64:67], v[8:11], v[0:3], 0
	v_mfma_f32_16x16x32_bf16 v[68:71], v[16:19], v[0:3], 0
	v_mfma_f32_16x16x32_bf16 v[72:75], v[8:11], v[40:43], 0
	v_mfma_f32_16x16x32_bf16 v[76:79], v[16:19], v[40:43], 0
	v_mfma_f32_16x16x32_bf16 v[80:83], v[8:11], v[48:51], 0
	v_mfma_f32_16x16x32_bf16 v[84:87], v[16:19], v[48:51], 0
	v_mfma_f32_16x16x32_bf16 v[88:91], v[8:11], v[56:59], 0
	v_mfma_f32_16x16x32_bf16 v[92:95], v[16:19], v[56:59], 0
	v_mfma_f32_16x16x32_bf16 v[64:67], v[12:15], v[4:7], v[64:67]
	v_mfma_f32_16x16x32_bf16 v[68:71], v[20:23], v[4:7], v[68:71]
	v_mfma_f32_16x16x32_bf16 v[72:75], v[12:15], v[44:47], v[72:75]
	v_mfma_f32_16x16x32_bf16 v[76:79], v[20:23], v[44:47], v[76:79]
	v_mfma_f32_16x16x32_bf16 v[80:83], v[12:15], v[52:55], v[80:83]
	v_mfma_f32_16x16x32_bf16 v[84:87], v[20:23], v[52:55], v[84:87]
	v_mfma_f32_16x16x32_bf16 v[88:91], v[12:15], v[60:63], v[88:91]
	v_mfma_f32_16x16x32_bf16 v[92:95], v[20:23], v[60:63], v[92:95]
	s_setprio 0
	s_setprio 1
	v_mfma_f32_16x16x32_bf16 v[96:99], v[24:27], v[0:3], 0
	v_mfma_f32_16x16x32_bf16 v[0:3], v[32:35], v[0:3], 0
	v_mfma_f32_16x16x32_bf16 v[100:103], v[36:39], v[4:7], v[0:3]
	v_mfma_f32_16x16x32_bf16 v[0:3], v[24:27], v[40:43], 0
	v_mfma_f32_16x16x32_bf16 v[104:107], v[28:31], v[44:47], v[0:3]
	v_mfma_f32_16x16x32_bf16 v[0:3], v[32:35], v[40:43], 0
	v_mfma_f32_16x16x32_bf16 v[40:43], v[36:39], v[44:47], v[0:3]
	v_mfma_f32_16x16x32_bf16 v[0:3], v[24:27], v[48:51], 0
	v_mfma_f32_16x16x32_bf16 v[44:47], v[28:31], v[52:55], v[0:3]
	v_mfma_f32_16x16x32_bf16 v[0:3], v[32:35], v[48:51], 0
	v_mfma_f32_16x16x32_bf16 v[48:51], v[36:39], v[52:55], v[0:3]
	v_mfma_f32_16x16x32_bf16 v[0:3], v[24:27], v[56:59], 0
	v_mfma_f32_16x16x32_bf16 v[52:55], v[28:31], v[60:63], v[0:3]
	v_mfma_f32_16x16x32_bf16 v[0:3], v[32:35], v[56:59], 0
	v_mfma_f32_16x16x32_bf16 v[96:99], v[28:31], v[4:7], v[96:99]
	v_mfma_f32_16x16x32_bf16 v[56:59], v[36:39], v[60:63], v[0:3]
	s_setprio 0
	s_barrier
	s_nop 3
	v_lshl_add_u64 v[0:1], s[46:47], 0, v[132:133]
	s_add_i32 s69, s62, s52
	v_lshl_add_u64 v[2:3], v[0:1], 0, s[22:23]
	s_mov_b32 m0, s69
	s_add_i32 s66, s69, 0x2000
	ds_read_b128 v[60:63], v141 offset:16384
	ds_read_b128 v[108:111], v141 offset:17408
	ds_read_b128 v[112:115], v141 offset:18432
	ds_read_b128 v[116:119], v141 offset:19456
	ds_read_b128 v[120:123], v141 offset:20480
	ds_read_b128 v[124:127], v141 offset:21504
	ds_read_b128 v[146:149], v141 offset:22528
	ds_read_b128 v[150:153], v141 offset:23552
	global_load_lds_dwordx4 v[2:3], off
	v_lshl_add_u64 v[2:3], s[46:47], 0, v[128:129]
	s_add_u32 s70, s46, 0x18100
	v_lshl_add_u64 v[4:5], v[2:3], 0, s[22:23]
	s_mov_b32 m0, s66
	s_addc_u32 s71, s47, 0
	s_add_i32 s67, s63, s52
	global_load_lds_dwordx4 v[4:5], off
	v_lshl_add_u64 v[4:5], s[70:71], 0, v[132:133]
	s_mov_b32 m0, s67
	s_add_i32 s68, s67, 0x2000
	global_load_lds_dwordx4 v[4:5], off
	v_lshl_add_u64 v[4:5], s[70:71], 0, v[128:129]
	s_mov_b32 m0, s68
	s_nop 0
	global_load_lds_dwordx4 v[4:5], off
	v_lshl_add_u64 v[4:5], s[44:45], 0, v[134:135]
	v_lshl_add_u64 v[6:7], v[4:5], 0, s[22:23]
	s_mov_b32 m0, s53
	s_nop 0
	global_load_lds_dwordx4 v[6:7], off
	v_lshl_add_u64 v[6:7], s[44:45], 0, v[130:131]
	v_lshl_add_u64 v[154:155], v[6:7], 0, s[22:23]
	s_mov_b32 m0, s54
	s_nop 0
	global_load_lds_dwordx4 v[154:155], off
	s_waitcnt vmcnt(8)
	s_waitcnt lgkmcnt(0)
	s_setprio 1
	s_barrier
	v_mfma_f32_16x16x32_bf16 v[154:157], v[8:11], v[60:63], 0
	v_mfma_f32_16x16x32_bf16 v[162:165], v[8:11], v[112:115], 0
	v_mfma_f32_16x16x32_bf16 v[170:173], v[8:11], v[120:123], 0
	v_mfma_f32_16x16x32_bf16 v[8:11], v[8:11], v[146:149], 0
	v_mfma_f32_16x16x32_bf16 v[154:157], v[12:15], v[108:111], v[154:157]
	v_mfma_f32_16x16x32_bf16 v[158:161], v[16:19], v[60:63], 0
	v_mfma_f32_16x16x32_bf16 v[162:165], v[12:15], v[116:119], v[162:165]
	v_mfma_f32_16x16x32_bf16 v[166:169], v[16:19], v[112:115], 0
	v_mfma_f32_16x16x32_bf16 v[170:173], v[12:15], v[124:127], v[170:173]
	v_mfma_f32_16x16x32_bf16 v[174:177], v[16:19], v[120:123], 0
	v_mfma_f32_16x16x32_bf16 v[10:13], v[12:15], v[150:153], v[8:11]
	v_mfma_f32_16x16x32_bf16 v[14:17], v[16:19], v[146:149], 0
	v_mfma_f32_16x16x32_bf16 v[14:17], v[20:23], v[150:153], v[14:17]
	v_mfma_f32_16x16x32_bf16 v[158:161], v[20:23], v[108:111], v[158:161]
	v_mfma_f32_16x16x32_bf16 v[166:169], v[20:23], v[116:119], v[166:169]
	v_mfma_f32_16x16x32_bf16 v[174:177], v[20:23], v[124:127], v[174:177]
	s_setprio 0
	s_setprio 1
	v_mfma_f32_16x16x32_bf16 v[18:21], v[24:27], v[60:63], 0
	v_mfma_f32_16x16x32_bf16 v[60:63], v[32:35], v[60:63], 0
	v_mfma_f32_16x16x32_bf16 v[18:21], v[28:31], v[108:111], v[18:21]
	v_mfma_f32_16x16x32_bf16 v[60:63], v[36:39], v[108:111], v[60:63]
	v_mfma_f32_16x16x32_bf16 v[108:111], v[24:27], v[112:115], 0
	v_mfma_f32_16x16x32_bf16 v[112:115], v[32:35], v[112:115], 0
	v_mfma_f32_16x16x32_bf16 v[108:111], v[28:31], v[116:119], v[108:111]
	v_mfma_f32_16x16x32_bf16 v[112:115], v[36:39], v[116:119], v[112:115]
	v_mfma_f32_16x16x32_bf16 v[116:119], v[24:27], v[120:123], 0
	v_mfma_f32_16x16x32_bf16 v[22:25], v[24:27], v[146:149], 0
	v_mfma_f32_16x16x32_bf16 v[116:119], v[28:31], v[124:127], v[116:119]
	v_mfma_f32_16x16x32_bf16 v[120:123], v[32:35], v[120:123], 0
	v_mfma_f32_16x16x32_bf16 v[22:25], v[28:31], v[150:153], v[22:25]
	v_mfma_f32_16x16x32_bf16 v[26:29], v[32:35], v[146:149], 0
	v_mfma_f32_16x16x32_bf16 v[120:123], v[36:39], v[124:127], v[120:123]
	v_mfma_f32_16x16x32_bf16 v[26:29], v[36:39], v[150:153], v[26:29]
	s_setprio 0
	s_barrier
	s_add_i32 s73, 0, 0x18000
	s_add_i32 s72, 0, 0x1c000
	v_add_u32_e32 v8, s73, v140
	v_add_u32_e32 v9, s72, v140
	ds_read_b128 v[30:33], v8
	ds_read_b128 v[34:37], v8 offset:1024
	ds_read_b128 v[124:127], v8 offset:2048
	ds_read_b128 v[146:149], v8 offset:3072
	ds_read_b128 v[150:153], v9
	ds_read_b128 v[178:181], v9 offset:1024
	ds_read_b128 v[182:185], v9 offset:2048
	ds_read_b128 v[186:189], v9 offset:3072
	s_add_u32 s70, s44, 0x18100
	s_addc_u32 s71, s45, 0
	s_mov_b32 m0, s55
	v_lshl_add_u64 v[38:39], s[70:71], 0, v[134:135]
	ds_read_b128 v[190:193], v141 offset:32768
	ds_read_b128 v[194:197], v141 offset:33792
	ds_read_b128 v[198:201], v141 offset:34816
	ds_read_b128 v[202:205], v141 offset:35840
	ds_read_b128 v[210:213], v141 offset:36864
	ds_read_b128 v[214:217], v141 offset:37888
	ds_read_b128 v[218:221], v141 offset:38912
	ds_read_b128 v[222:225], v141 offset:39936
	global_load_lds_dwordx4 v[38:39], off
	v_lshl_add_u64 v[38:39], s[70:71], 0, v[130:131]
	s_mov_b32 m0, s56
	s_nop 0
	global_load_lds_dwordx4 v[38:39], off
	s_waitcnt vmcnt(8)
	s_waitcnt lgkmcnt(0)
	s_setprio 1
	s_barrier
	v_mfma_f32_16x16x32_bf16 v[64:67], v[30:33], v[190:193], v[64:67]
	v_mfma_f32_16x16x32_bf16 v[68:71], v[124:127], v[190:193], v[68:71]
	v_mfma_f32_16x16x32_bf16 v[72:75], v[30:33], v[198:201], v[72:75]
	v_mfma_f32_16x16x32_bf16 v[76:79], v[124:127], v[198:201], v[76:79]
	v_mfma_f32_16x16x32_bf16 v[80:83], v[30:33], v[210:213], v[80:83]
	v_mfma_f32_16x16x32_bf16 v[84:87], v[124:127], v[210:213], v[84:87]
	v_mfma_f32_16x16x32_bf16 v[88:91], v[30:33], v[218:221], v[88:91]
	v_mfma_f32_16x16x32_bf16 v[92:95], v[124:127], v[218:221], v[92:95]
	v_mfma_f32_16x16x32_bf16 v[64:67], v[34:37], v[194:197], v[64:67]
	v_mfma_f32_16x16x32_bf16 v[68:71], v[146:149], v[194:197], v[68:71]
	v_mfma_f32_16x16x32_bf16 v[72:75], v[34:37], v[202:205], v[72:75]
	v_mfma_f32_16x16x32_bf16 v[76:79], v[146:149], v[202:205], v[76:79]
	v_mfma_f32_16x16x32_bf16 v[80:83], v[34:37], v[214:217], v[80:83]
	v_mfma_f32_16x16x32_bf16 v[84:87], v[146:149], v[214:217], v[84:87]
	v_mfma_f32_16x16x32_bf16 v[88:91], v[34:37], v[222:225], v[88:91]
	v_mfma_f32_16x16x32_bf16 v[92:95], v[146:149], v[222:225], v[92:95]
	s_setprio 0
	s_setprio 1
	v_mfma_f32_16x16x32_bf16 v[96:99], v[150:153], v[190:193], v[96:99]
	v_mfma_f32_16x16x32_bf16 v[100:103], v[182:185], v[190:193], v[100:103]
	v_mfma_f32_16x16x32_bf16 v[104:107], v[150:153], v[198:201], v[104:107]
	v_mfma_f32_16x16x32_bf16 v[38:41], v[182:185], v[198:201], v[40:43]
	v_mfma_f32_16x16x32_bf16 v[42:45], v[150:153], v[210:213], v[44:47]
	v_mfma_f32_16x16x32_bf16 v[46:49], v[182:185], v[210:213], v[48:51]
	v_mfma_f32_16x16x32_bf16 v[50:53], v[150:153], v[218:221], v[52:55]
	v_mfma_f32_16x16x32_bf16 v[54:57], v[182:185], v[218:221], v[56:59]
	v_mfma_f32_16x16x32_bf16 v[96:99], v[178:181], v[194:197], v[96:99]
	v_mfma_f32_16x16x32_bf16 v[100:103], v[186:189], v[194:197], v[100:103]
	v_mfma_f32_16x16x32_bf16 v[104:107], v[178:181], v[202:205], v[104:107]
	v_mfma_f32_16x16x32_bf16 v[38:41], v[186:189], v[202:205], v[38:41]
	v_mfma_f32_16x16x32_bf16 v[42:45], v[178:181], v[214:217], v[42:45]
	v_mfma_f32_16x16x32_bf16 v[46:49], v[186:189], v[214:217], v[46:49]
	v_mfma_f32_16x16x32_bf16 v[50:53], v[178:181], v[222:225], v[50:53]
	v_mfma_f32_16x16x32_bf16 v[54:57], v[186:189], v[222:225], v[54:57]
	s_setprio 0
	s_barrier
	s_add_i32 s73, s73, s52
	s_add_i32 s70, s73, 0x2000
	v_lshl_add_u64 v[58:59], v[0:1], 0, s[24:25]
	s_mov_b32 m0, s73
	s_add_u32 s74, s46, 0x18180
	ds_read_b128 v[190:193], v141 offset:49152
	ds_read_b128 v[194:197], v141 offset:50176
	ds_read_b128 v[198:201], v141 offset:51200
	ds_read_b128 v[202:205], v141 offset:52224
	ds_read_b128 v[210:213], v141 offset:53248
	ds_read_b128 v[214:217], v141 offset:54272
	ds_read_b128 v[218:221], v141 offset:55296
	ds_read_b128 v[222:225], v141 offset:56320
	global_load_lds_dwordx4 v[58:59], off
	v_lshl_add_u64 v[58:59], v[2:3], 0, s[24:25]
	s_mov_b32 m0, s70
	s_addc_u32 s75, s47, 0
	s_add_i32 s71, s72, s52
	global_load_lds_dwordx4 v[58:59], off
	v_lshl_add_u64 v[58:59], s[74:75], 0, v[132:133]
	s_mov_b32 m0, s71
	s_add_i32 s72, s71, 0x2000
	global_load_lds_dwordx4 v[58:59], off
	v_lshl_add_u64 v[58:59], s[74:75], 0, v[128:129]
	s_mov_b32 m0, s72
	s_nop 0
	global_load_lds_dwordx4 v[58:59], off
	v_lshl_add_u64 v[58:59], v[4:5], 0, s[24:25]
	s_mov_b32 m0, s57
	s_nop 0
	global_load_lds_dwordx4 v[58:59], off
	v_lshl_add_u64 v[58:59], v[6:7], 0, s[24:25]
	s_mov_b32 m0, s58
	s_nop 0
	global_load_lds_dwordx4 v[58:59], off
	s_waitcnt vmcnt(8)
	s_waitcnt lgkmcnt(0)
	s_setprio 1
	s_barrier
	v_mfma_f32_16x16x32_bf16 v[10:13], v[30:33], v[218:221], v[10:13]
	v_mfma_f32_16x16x32_bf16 v[14:17], v[124:127], v[218:221], v[14:17]
	v_mfma_f32_16x16x32_bf16 v[154:157], v[30:33], v[190:193], v[154:157]
	v_mfma_f32_16x16x32_bf16 v[158:161], v[124:127], v[190:193], v[158:161]
	v_mfma_f32_16x16x32_bf16 v[162:165], v[30:33], v[198:201], v[162:165]
	v_mfma_f32_16x16x32_bf16 v[166:169], v[124:127], v[198:201], v[166:169]
	v_mfma_f32_16x16x32_bf16 v[170:173], v[30:33], v[210:213], v[170:173]
	v_mfma_f32_16x16x32_bf16 v[174:177], v[124:127], v[210:213], v[174:177]
	v_mfma_f32_16x16x32_bf16 v[10:13], v[34:37], v[222:225], v[10:13]
	v_mfma_f32_16x16x32_bf16 v[14:17], v[146:149], v[222:225], v[14:17]
	v_mfma_f32_16x16x32_bf16 v[154:157], v[34:37], v[194:197], v[154:157]
	v_mfma_f32_16x16x32_bf16 v[158:161], v[146:149], v[194:197], v[158:161]
	v_mfma_f32_16x16x32_bf16 v[162:165], v[34:37], v[202:205], v[162:165]
	v_mfma_f32_16x16x32_bf16 v[166:169], v[146:149], v[202:205], v[166:169]
	v_mfma_f32_16x16x32_bf16 v[170:173], v[34:37], v[214:217], v[170:173]
	v_mfma_f32_16x16x32_bf16 v[174:177], v[146:149], v[214:217], v[174:177]
	s_setprio 0
	s_setprio 1
	v_mfma_f32_16x16x32_bf16 v[18:21], v[150:153], v[190:193], v[18:21]
	v_mfma_f32_16x16x32_bf16 v[30:33], v[182:185], v[190:193], v[60:63]
	v_mfma_f32_16x16x32_bf16 v[34:37], v[150:153], v[198:201], v[108:111]
	v_mfma_f32_16x16x32_bf16 v[58:61], v[182:185], v[198:201], v[112:115]
	v_mfma_f32_16x16x32_bf16 v[108:111], v[150:153], v[210:213], v[116:119]
	v_mfma_f32_16x16x32_bf16 v[112:115], v[182:185], v[210:213], v[120:123]
	v_mfma_f32_16x16x32_bf16 v[22:25], v[150:153], v[218:221], v[22:25]
	v_mfma_f32_16x16x32_bf16 v[26:29], v[182:185], v[218:221], v[26:29]
	v_mfma_f32_16x16x32_bf16 v[18:21], v[178:181], v[194:197], v[18:21]
	v_mfma_f32_16x16x32_bf16 v[30:33], v[186:189], v[194:197], v[30:33]
	v_mfma_f32_16x16x32_bf16 v[34:37], v[178:181], v[202:205], v[34:37]
	v_mfma_f32_16x16x32_bf16 v[58:61], v[186:189], v[202:205], v[58:61]
	v_mfma_f32_16x16x32_bf16 v[108:111], v[178:181], v[214:217], v[108:111]
	v_mfma_f32_16x16x32_bf16 v[112:115], v[186:189], v[214:217], v[112:115]
	v_mfma_f32_16x16x32_bf16 v[22:25], v[178:181], v[222:225], v[22:25]
	v_mfma_f32_16x16x32_bf16 v[26:29], v[186:189], v[222:225], v[26:29]
	s_setprio 0
	s_barrier
	ds_read_b128 v[116:119], v144
	ds_read_b128 v[120:123], v144 offset:1024
	ds_read_b128 v[124:127], v144 offset:2048
	ds_read_b128 v[146:149], v144 offset:3072
	ds_read_b128 v[150:153], v145
	ds_read_b128 v[178:181], v145 offset:1024
	ds_read_b128 v[182:185], v145 offset:2048
	ds_read_b128 v[186:189], v145 offset:3072
	s_add_u32 s74, s44, 0x18180
	s_addc_u32 s75, s45, 0
	s_mov_b32 m0, s64
	v_lshl_add_u64 v[62:63], s[74:75], 0, v[134:135]
	ds_read_b128 v[190:193], v141
	ds_read_b128 v[194:197], v141 offset:1024
	ds_read_b128 v[198:201], v141 offset:2048
	ds_read_b128 v[202:205], v141 offset:3072
	ds_read_b128 v[210:213], v141 offset:4096
	ds_read_b128 v[214:217], v141 offset:5120
	ds_read_b128 v[218:221], v141 offset:6144
	ds_read_b128 v[222:225], v141 offset:7168
	global_load_lds_dwordx4 v[62:63], off
	v_lshl_add_u64 v[62:63], s[74:75], 0, v[130:131]
	s_mov_b32 m0, s43
	s_nop 0
	global_load_lds_dwordx4 v[62:63], off
	s_waitcnt vmcnt(8)
	s_waitcnt lgkmcnt(0)
	s_setprio 1
	s_barrier
	v_mfma_f32_16x16x32_bf16 v[62:65], v[116:119], v[190:193], v[64:67]
	v_mfma_f32_16x16x32_bf16 v[66:69], v[124:127], v[190:193], v[68:71]
	v_mfma_f32_16x16x32_bf16 v[70:73], v[116:119], v[198:201], v[72:75]
	v_mfma_f32_16x16x32_bf16 v[74:77], v[124:127], v[198:201], v[76:79]
	v_mfma_f32_16x16x32_bf16 v[78:81], v[116:119], v[210:213], v[80:83]
	v_mfma_f32_16x16x32_bf16 v[82:85], v[124:127], v[210:213], v[84:87]
	v_mfma_f32_16x16x32_bf16 v[86:89], v[116:119], v[218:221], v[88:91]
	v_mfma_f32_16x16x32_bf16 v[90:93], v[124:127], v[218:221], v[92:95]
	v_mfma_f32_16x16x32_bf16 v[62:65], v[120:123], v[194:197], v[62:65]
	v_mfma_f32_16x16x32_bf16 v[66:69], v[146:149], v[194:197], v[66:69]
	v_mfma_f32_16x16x32_bf16 v[70:73], v[120:123], v[202:205], v[70:73]
	v_mfma_f32_16x16x32_bf16 v[74:77], v[146:149], v[202:205], v[74:77]
	v_mfma_f32_16x16x32_bf16 v[78:81], v[120:123], v[214:217], v[78:81]
	v_mfma_f32_16x16x32_bf16 v[82:85], v[146:149], v[214:217], v[82:85]
	v_mfma_f32_16x16x32_bf16 v[86:89], v[120:123], v[222:225], v[86:89]
	v_mfma_f32_16x16x32_bf16 v[90:93], v[146:149], v[222:225], v[90:93]
	s_setprio 0
	s_setprio 1
	v_mfma_f32_16x16x32_bf16 v[94:97], v[150:153], v[190:193], v[96:99]
	v_mfma_f32_16x16x32_bf16 v[98:101], v[182:185], v[190:193], v[100:103]
	v_mfma_f32_16x16x32_bf16 v[102:105], v[150:153], v[198:201], v[104:107]
	v_mfma_f32_16x16x32_bf16 v[38:41], v[182:185], v[198:201], v[38:41]
	v_mfma_f32_16x16x32_bf16 v[42:45], v[150:153], v[210:213], v[42:45]
	v_mfma_f32_16x16x32_bf16 v[46:49], v[182:185], v[210:213], v[46:49]
	v_mfma_f32_16x16x32_bf16 v[50:53], v[150:153], v[218:221], v[50:53]
	v_mfma_f32_16x16x32_bf16 v[54:57], v[182:185], v[218:221], v[54:57]
	v_mfma_f32_16x16x32_bf16 v[94:97], v[178:181], v[194:197], v[94:97]
	v_mfma_f32_16x16x32_bf16 v[98:101], v[186:189], v[194:197], v[98:101]
	v_mfma_f32_16x16x32_bf16 v[102:105], v[178:181], v[202:205], v[102:105]
	v_mfma_f32_16x16x32_bf16 v[38:41], v[186:189], v[202:205], v[38:41]
	v_mfma_f32_16x16x32_bf16 v[42:45], v[178:181], v[214:217], v[42:45]
	v_mfma_f32_16x16x32_bf16 v[46:49], v[186:189], v[214:217], v[46:49]
	v_mfma_f32_16x16x32_bf16 v[50:53], v[178:181], v[222:225], v[50:53]
	v_mfma_f32_16x16x32_bf16 v[54:57], v[186:189], v[222:225], v[54:57]
	s_setprio 0
	s_barrier
	s_mov_b32 m0, s69
	v_lshl_add_u64 v[106:107], v[0:1], 0, s[36:37]
	s_add_u32 s74, s46, 0x18200
	ds_read_b128 v[190:193], v141 offset:16384
	ds_read_b128 v[194:197], v141 offset:17408
	ds_read_b128 v[198:201], v141 offset:18432
	ds_read_b128 v[202:205], v141 offset:19456
	ds_read_b128 v[210:213], v141 offset:20480
	ds_read_b128 v[214:217], v141 offset:21504
	ds_read_b128 v[218:221], v141 offset:22528
	ds_read_b128 v[222:225], v141 offset:23552
	global_load_lds_dwordx4 v[106:107], off
	v_lshl_add_u64 v[106:107], v[2:3], 0, s[36:37]
	s_mov_b32 m0, s66
	s_addc_u32 s75, s47, 0
	global_load_lds_dwordx4 v[106:107], off
	v_lshl_add_u64 v[106:107], s[74:75], 0, v[132:133]
	s_mov_b32 m0, s67
	s_nop 0
	global_load_lds_dwordx4 v[106:107], off
	v_lshl_add_u64 v[106:107], s[74:75], 0, v[128:129]
	s_mov_b32 m0, s68
	s_nop 0
	global_load_lds_dwordx4 v[106:107], off
	v_lshl_add_u64 v[106:107], v[4:5], 0, s[36:37]
	s_mov_b32 m0, s53
	s_nop 0
	global_load_lds_dwordx4 v[106:107], off
	v_lshl_add_u64 v[106:107], v[6:7], 0, s[36:37]
	s_mov_b32 m0, s54
	s_nop 0
	global_load_lds_dwordx4 v[106:107], off
	s_waitcnt vmcnt(8)
	s_waitcnt lgkmcnt(0)
	s_setprio 1
	s_barrier
	v_mfma_f32_16x16x32_bf16 v[10:13], v[116:119], v[218:221], v[10:13]
	v_mfma_f32_16x16x32_bf16 v[14:17], v[124:127], v[218:221], v[14:17]
	v_mfma_f32_16x16x32_bf16 v[154:157], v[116:119], v[190:193], v[154:157]
	v_mfma_f32_16x16x32_bf16 v[158:161], v[124:127], v[190:193], v[158:161]
	v_mfma_f32_16x16x32_bf16 v[162:165], v[116:119], v[198:201], v[162:165]
	v_mfma_f32_16x16x32_bf16 v[166:169], v[124:127], v[198:201], v[166:169]
	v_mfma_f32_16x16x32_bf16 v[170:173], v[116:119], v[210:213], v[170:173]
	v_mfma_f32_16x16x32_bf16 v[174:177], v[124:127], v[210:213], v[174:177]
	v_mfma_f32_16x16x32_bf16 v[10:13], v[120:123], v[222:225], v[10:13]
	v_mfma_f32_16x16x32_bf16 v[14:17], v[146:149], v[222:225], v[14:17]
	v_mfma_f32_16x16x32_bf16 v[154:157], v[120:123], v[194:197], v[154:157]
	v_mfma_f32_16x16x32_bf16 v[158:161], v[146:149], v[194:197], v[158:161]
	v_mfma_f32_16x16x32_bf16 v[162:165], v[120:123], v[202:205], v[162:165]
	v_mfma_f32_16x16x32_bf16 v[166:169], v[146:149], v[202:205], v[166:169]
	v_mfma_f32_16x16x32_bf16 v[170:173], v[120:123], v[214:217], v[170:173]
	v_mfma_f32_16x16x32_bf16 v[174:177], v[146:149], v[214:217], v[174:177]
	s_setprio 0
	s_setprio 1
	v_mfma_f32_16x16x32_bf16 v[18:21], v[150:153], v[190:193], v[18:21]
	v_mfma_f32_16x16x32_bf16 v[30:33], v[182:185], v[190:193], v[30:33]
	v_mfma_f32_16x16x32_bf16 v[34:37], v[150:153], v[198:201], v[34:37]
	v_mfma_f32_16x16x32_bf16 v[58:61], v[182:185], v[198:201], v[58:61]
	v_mfma_f32_16x16x32_bf16 v[106:109], v[150:153], v[210:213], v[108:111]
	v_mfma_f32_16x16x32_bf16 v[110:113], v[182:185], v[210:213], v[112:115]
	v_mfma_f32_16x16x32_bf16 v[22:25], v[150:153], v[218:221], v[22:25]
	v_mfma_f32_16x16x32_bf16 v[26:29], v[182:185], v[218:221], v[26:29]
	v_mfma_f32_16x16x32_bf16 v[18:21], v[178:181], v[194:197], v[18:21]
	v_mfma_f32_16x16x32_bf16 v[30:33], v[186:189], v[194:197], v[30:33]
	v_mfma_f32_16x16x32_bf16 v[34:37], v[178:181], v[202:205], v[34:37]
	v_mfma_f32_16x16x32_bf16 v[58:61], v[186:189], v[202:205], v[58:61]
	v_mfma_f32_16x16x32_bf16 v[106:109], v[178:181], v[214:217], v[106:109]
	v_mfma_f32_16x16x32_bf16 v[110:113], v[186:189], v[214:217], v[110:113]
	v_mfma_f32_16x16x32_bf16 v[22:25], v[178:181], v[222:225], v[22:25]
	v_mfma_f32_16x16x32_bf16 v[26:29], v[186:189], v[222:225], v[26:29]
	s_setprio 0
	s_barrier
	ds_read_b128 v[114:117], v8
	ds_read_b128 v[118:121], v8 offset:1024
	ds_read_b128 v[122:125], v8 offset:2048
	ds_read_b128 v[146:149], v8 offset:3072
	ds_read_b128 v[150:153], v9
	ds_read_b128 v[178:181], v9 offset:1024
	ds_read_b128 v[182:185], v9 offset:2048
	ds_read_b128 v[186:189], v9 offset:3072
	s_add_u32 s74, s44, 0x18200
	s_addc_u32 s75, s45, 0
	s_mov_b32 m0, s55
	v_lshl_add_u64 v[126:127], s[74:75], 0, v[134:135]
	ds_read_b128 v[190:193], v141 offset:32768
	ds_read_b128 v[194:197], v141 offset:33792
	ds_read_b128 v[198:201], v141 offset:34816
	ds_read_b128 v[202:205], v141 offset:35840
	ds_read_b128 v[210:213], v141 offset:36864
	ds_read_b128 v[214:217], v141 offset:37888
	ds_read_b128 v[218:221], v141 offset:38912
	ds_read_b128 v[222:225], v141 offset:39936
	global_load_lds_dwordx4 v[126:127], off
	v_lshl_add_u64 v[126:127], s[74:75], 0, v[130:131]
	s_mov_b32 m0, s56
	s_nop 0
	global_load_lds_dwordx4 v[126:127], off
	s_waitcnt vmcnt(8)
	s_waitcnt lgkmcnt(0)
	s_setprio 1
	s_barrier
	v_mfma_f32_16x16x32_bf16 v[62:65], v[114:117], v[190:193], v[62:65]
	v_mfma_f32_16x16x32_bf16 v[66:69], v[122:125], v[190:193], v[66:69]
	v_mfma_f32_16x16x32_bf16 v[70:73], v[114:117], v[198:201], v[70:73]
	v_mfma_f32_16x16x32_bf16 v[74:77], v[122:125], v[198:201], v[74:77]
	v_mfma_f32_16x16x32_bf16 v[78:81], v[114:117], v[210:213], v[78:81]
	v_mfma_f32_16x16x32_bf16 v[82:85], v[122:125], v[210:213], v[82:85]
	v_mfma_f32_16x16x32_bf16 v[86:89], v[114:117], v[218:221], v[86:89]
	v_mfma_f32_16x16x32_bf16 v[90:93], v[122:125], v[218:221], v[90:93]
	v_mfma_f32_16x16x32_bf16 v[62:65], v[118:121], v[194:197], v[62:65]
	v_mfma_f32_16x16x32_bf16 v[66:69], v[146:149], v[194:197], v[66:69]
	v_mfma_f32_16x16x32_bf16 v[70:73], v[118:121], v[202:205], v[70:73]
	v_mfma_f32_16x16x32_bf16 v[74:77], v[146:149], v[202:205], v[74:77]
	v_mfma_f32_16x16x32_bf16 v[78:81], v[118:121], v[214:217], v[78:81]
	v_mfma_f32_16x16x32_bf16 v[82:85], v[146:149], v[214:217], v[82:85]
	v_mfma_f32_16x16x32_bf16 v[86:89], v[118:121], v[222:225], v[86:89]
	v_mfma_f32_16x16x32_bf16 v[90:93], v[146:149], v[222:225], v[90:93]
	s_setprio 0
	s_setprio 1
	v_mfma_f32_16x16x32_bf16 v[94:97], v[150:153], v[190:193], v[94:97]
	v_mfma_f32_16x16x32_bf16 v[98:101], v[182:185], v[190:193], v[98:101]
	v_mfma_f32_16x16x32_bf16 v[102:105], v[150:153], v[198:201], v[102:105]
	v_mfma_f32_16x16x32_bf16 v[38:41], v[182:185], v[198:201], v[38:41]
	v_mfma_f32_16x16x32_bf16 v[42:45], v[150:153], v[210:213], v[42:45]
	v_mfma_f32_16x16x32_bf16 v[46:49], v[182:185], v[210:213], v[46:49]
	v_mfma_f32_16x16x32_bf16 v[50:53], v[150:153], v[218:221], v[50:53]
	v_mfma_f32_16x16x32_bf16 v[54:57], v[182:185], v[218:221], v[54:57]
	v_mfma_f32_16x16x32_bf16 v[94:97], v[178:181], v[194:197], v[94:97]
	v_mfma_f32_16x16x32_bf16 v[98:101], v[186:189], v[194:197], v[98:101]
	v_mfma_f32_16x16x32_bf16 v[102:105], v[178:181], v[202:205], v[102:105]
	v_mfma_f32_16x16x32_bf16 v[38:41], v[186:189], v[202:205], v[38:41]
	v_mfma_f32_16x16x32_bf16 v[42:45], v[178:181], v[214:217], v[42:45]
	v_mfma_f32_16x16x32_bf16 v[46:49], v[186:189], v[214:217], v[46:49]
	v_mfma_f32_16x16x32_bf16 v[50:53], v[178:181], v[222:225], v[50:53]
	v_mfma_f32_16x16x32_bf16 v[54:57], v[186:189], v[222:225], v[54:57]
	s_setprio 0
	s_barrier
	s_mov_b32 m0, s73
	v_lshl_add_u64 v[0:1], v[0:1], 0, s[38:39]
	s_add_u32 s46, s46, 0x18280
	ds_read_b128 v[190:193], v141 offset:49152
	ds_read_b128 v[194:197], v141 offset:50176
	ds_read_b128 v[198:201], v141 offset:51200
	ds_read_b128 v[202:205], v141 offset:52224
	ds_read_b128 v[210:213], v141 offset:53248
	ds_read_b128 v[214:217], v141 offset:54272
	ds_read_b128 v[218:221], v141 offset:55296
	ds_read_b128 v[222:225], v141 offset:56320
	global_load_lds_dwordx4 v[0:1], off
	v_lshl_add_u64 v[0:1], v[2:3], 0, s[38:39]
	s_mov_b32 m0, s70
	s_addc_u32 s47, s47, 0
	global_load_lds_dwordx4 v[0:1], off
	v_lshl_add_u64 v[0:1], s[46:47], 0, v[132:133]
	s_mov_b32 m0, s71
	s_nop 0
	global_load_lds_dwordx4 v[0:1], off
	v_lshl_add_u64 v[0:1], s[46:47], 0, v[128:129]
	s_mov_b32 m0, s72
	s_nop 0
	global_load_lds_dwordx4 v[0:1], off
	v_lshl_add_u64 v[0:1], v[4:5], 0, s[38:39]
	s_mov_b32 m0, s57
	s_nop 0
	global_load_lds_dwordx4 v[0:1], off
	v_lshl_add_u64 v[0:1], v[6:7], 0, s[38:39]
	s_mov_b32 m0, s58
	s_nop 0
	global_load_lds_dwordx4 v[0:1], off
	s_waitcnt vmcnt(8)
	s_waitcnt lgkmcnt(0)
	s_setprio 1
	s_barrier
	v_mfma_f32_16x16x32_bf16 v[0:3], v[114:117], v[190:193], v[154:157]
	v_mfma_f32_16x16x32_bf16 v[4:7], v[122:125], v[190:193], v[158:161]
	v_mfma_f32_16x16x32_bf16 v[10:13], v[114:117], v[218:221], v[10:13]
	v_mfma_f32_16x16x32_bf16 v[14:17], v[122:125], v[218:221], v[14:17]
	v_mfma_f32_16x16x32_bf16 v[0:3], v[118:121], v[194:197], v[0:3]
	v_mfma_f32_16x16x32_bf16 v[4:7], v[146:149], v[194:197], v[4:7]
	v_mfma_f32_16x16x32_bf16 v[154:157], v[114:117], v[198:201], v[162:165]
	v_mfma_f32_16x16x32_bf16 v[158:161], v[122:125], v[198:201], v[166:169]
	v_mfma_f32_16x16x32_bf16 v[162:165], v[114:117], v[210:213], v[170:173]
	v_mfma_f32_16x16x32_bf16 v[166:169], v[122:125], v[210:213], v[174:177]
	v_mfma_f32_16x16x32_bf16 v[10:13], v[118:121], v[222:225], v[10:13]
	v_mfma_f32_16x16x32_bf16 v[14:17], v[146:149], v[222:225], v[14:17]
	v_mfma_f32_16x16x32_bf16 v[154:157], v[118:121], v[202:205], v[154:157]
	v_mfma_f32_16x16x32_bf16 v[158:161], v[146:149], v[202:205], v[158:161]
	v_mfma_f32_16x16x32_bf16 v[162:165], v[118:121], v[214:217], v[162:165]
	v_mfma_f32_16x16x32_bf16 v[166:169], v[146:149], v[214:217], v[166:169]
	s_setprio 0
	s_setprio 1
	v_mfma_f32_16x16x32_bf16 v[18:21], v[150:153], v[190:193], v[18:21]
	v_mfma_f32_16x16x32_bf16 v[30:33], v[182:185], v[190:193], v[30:33]
	v_mfma_f32_16x16x32_bf16 v[34:37], v[150:153], v[198:201], v[34:37]
	v_mfma_f32_16x16x32_bf16 v[58:61], v[182:185], v[198:201], v[58:61]
	v_mfma_f32_16x16x32_bf16 v[106:109], v[150:153], v[210:213], v[106:109]
	v_mfma_f32_16x16x32_bf16 v[110:113], v[182:185], v[210:213], v[110:113]
	v_mfma_f32_16x16x32_bf16 v[22:25], v[150:153], v[218:221], v[22:25]
	v_mfma_f32_16x16x32_bf16 v[26:29], v[182:185], v[218:221], v[26:29]
	v_mfma_f32_16x16x32_bf16 v[18:21], v[178:181], v[194:197], v[18:21]
	v_mfma_f32_16x16x32_bf16 v[30:33], v[186:189], v[194:197], v[30:33]
	v_mfma_f32_16x16x32_bf16 v[34:37], v[178:181], v[202:205], v[34:37]
	v_mfma_f32_16x16x32_bf16 v[58:61], v[186:189], v[202:205], v[58:61]
	v_mfma_f32_16x16x32_bf16 v[106:109], v[178:181], v[214:217], v[106:109]
	v_mfma_f32_16x16x32_bf16 v[110:113], v[186:189], v[214:217], v[110:113]
	v_mfma_f32_16x16x32_bf16 v[22:25], v[178:181], v[222:225], v[22:25]
	v_mfma_f32_16x16x32_bf16 v[26:29], v[186:189], v[222:225], v[26:29]
	s_setprio 0
	s_barrier
	ds_read_b128 v[114:117], v144
	ds_read_b128 v[118:121], v144 offset:1024
	ds_read_b128 v[122:125], v144 offset:2048
	ds_read_b128 v[146:149], v144 offset:3072
	ds_read_b128 v[150:153], v145
	ds_read_b128 v[170:173], v145 offset:1024
	ds_read_b128 v[174:177], v145 offset:2048
	ds_read_b128 v[178:181], v145 offset:3072
	s_add_u32 s44, s44, 0x18280
	s_addc_u32 s45, s45, 0
	s_mov_b32 m0, s64
	v_lshl_add_u64 v[126:127], s[44:45], 0, v[134:135]
	ds_read_b128 v[182:185], v141
	ds_read_b128 v[186:189], v141 offset:1024
	ds_read_b128 v[190:193], v141 offset:2048
	ds_read_b128 v[194:197], v141 offset:3072
	ds_read_b128 v[198:201], v141 offset:4096
	ds_read_b128 v[202:205], v141 offset:5120
	ds_read_b128 v[210:213], v141 offset:6144
	ds_read_b128 v[214:217], v141 offset:7168
	global_load_lds_dwordx4 v[126:127], off
	v_lshl_add_u64 v[126:127], s[44:45], 0, v[130:131]
	s_mov_b32 m0, s43
	s_nop 0
	global_load_lds_dwordx4 v[126:127], off
	s_waitcnt vmcnt(8)
	s_waitcnt lgkmcnt(0)
	s_setprio 1
	s_barrier
	v_mfma_f32_16x16x32_bf16 v[62:65], v[114:117], v[182:185], v[62:65]
	v_mfma_f32_16x16x32_bf16 v[66:69], v[122:125], v[182:185], v[66:69]
	v_mfma_f32_16x16x32_bf16 v[70:73], v[114:117], v[190:193], v[70:73]
	v_mfma_f32_16x16x32_bf16 v[74:77], v[122:125], v[190:193], v[74:77]
	v_mfma_f32_16x16x32_bf16 v[78:81], v[114:117], v[198:201], v[78:81]
	v_mfma_f32_16x16x32_bf16 v[82:85], v[122:125], v[198:201], v[82:85]
	v_mfma_f32_16x16x32_bf16 v[86:89], v[114:117], v[210:213], v[86:89]
	v_mfma_f32_16x16x32_bf16 v[62:65], v[118:121], v[186:189], v[62:65]
	v_mfma_f32_16x16x32_bf16 v[66:69], v[146:149], v[186:189], v[66:69]
	v_mfma_f32_16x16x32_bf16 v[70:73], v[118:121], v[194:197], v[70:73]
	v_mfma_f32_16x16x32_bf16 v[74:77], v[146:149], v[194:197], v[74:77]
	v_mfma_f32_16x16x32_bf16 v[78:81], v[118:121], v[202:205], v[78:81]
	v_mfma_f32_16x16x32_bf16 v[82:85], v[146:149], v[202:205], v[82:85]
	v_mfma_f32_16x16x32_bf16 v[218:221], v[118:121], v[214:217], v[86:89]
	v_mfma_f32_16x16x32_bf16 v[86:89], v[122:125], v[210:213], v[90:93]
	v_mfma_f32_16x16x32_bf16 v[222:225], v[146:149], v[214:217], v[86:89]
	s_setprio 0
	s_setprio 1
	v_mfma_f32_16x16x32_bf16 v[86:89], v[150:153], v[182:185], v[94:97]
	v_mfma_f32_16x16x32_bf16 v[226:229], v[170:173], v[186:189], v[86:89]
	v_mfma_f32_16x16x32_bf16 v[86:89], v[174:177], v[182:185], v[98:101]
	v_mfma_f32_16x16x32_bf16 v[96:99], v[178:181], v[186:189], v[86:89]
	v_mfma_f32_16x16x32_bf16 v[86:89], v[150:153], v[190:193], v[102:105]
	v_mfma_f32_16x16x32_bf16 v[38:41], v[174:177], v[190:193], v[38:41]
	v_mfma_f32_16x16x32_bf16 v[42:45], v[150:153], v[198:201], v[42:45]
	v_mfma_f32_16x16x32_bf16 v[46:49], v[174:177], v[198:201], v[46:49]
	v_mfma_f32_16x16x32_bf16 v[50:53], v[150:153], v[210:213], v[50:53]
	v_mfma_f32_16x16x32_bf16 v[54:57], v[174:177], v[210:213], v[54:57]
	v_mfma_f32_16x16x32_bf16 v[100:103], v[170:173], v[194:197], v[86:89]
	v_mfma_f32_16x16x32_bf16 v[38:41], v[178:181], v[194:197], v[38:41]
	v_mfma_f32_16x16x32_bf16 v[42:45], v[170:173], v[202:205], v[42:45]
	v_mfma_f32_16x16x32_bf16 v[46:49], v[178:181], v[202:205], v[46:49]
	v_mfma_f32_16x16x32_bf16 v[50:53], v[170:173], v[214:217], v[50:53]
	v_mfma_f32_16x16x32_bf16 v[54:57], v[178:181], v[214:217], v[54:57]
	s_setprio 0
	s_barrier
	s_mov_b32 m0, s69
	v_lshl_add_u64 v[206:207], s[6:7], 0, v[132:133]
	s_add_u32 s44, s6, 0x18000
	ds_read_b128 v[86:89], v141 offset:16384
	ds_read_b128 v[90:93], v141 offset:17408
	ds_read_b128 v[182:185], v141 offset:18432
	ds_read_b128 v[186:189], v141 offset:19456
	ds_read_b128 v[190:193], v141 offset:20480
	ds_read_b128 v[194:197], v141 offset:21504
	ds_read_b128 v[198:201], v141 offset:22528
	ds_read_b128 v[202:205], v141 offset:23552
	global_load_lds_dwordx4 v[206:207], off
	v_lshl_add_u64 v[136:137], s[6:7], 0, v[128:129]
	s_mov_b32 m0, s66
	s_addc_u32 s45, s7, 0
	global_load_lds_dwordx4 v[136:137], off
	v_lshl_add_u64 v[94:95], s[44:45], 0, v[132:133]
	s_mov_b32 m0, s67
	v_lshl_add_u64 v[138:139], s[40:41], 0, v[134:135]
	global_load_lds_dwordx4 v[94:95], off
	v_lshl_add_u64 v[94:95], s[44:45], 0, v[128:129]
	s_mov_b32 m0, s68
	v_lshl_add_u64 v[142:143], s[40:41], 0, v[130:131]
	global_load_lds_dwordx4 v[94:95], off
	s_mov_b32 m0, s53
	s_nop 0
	global_load_lds_dwordx4 v[138:139], off
	s_mov_b32 m0, s54
	s_nop 0
	global_load_lds_dwordx4 v[142:143], off
	s_waitcnt vmcnt(8)
	s_waitcnt lgkmcnt(0)
	s_setprio 1
	s_barrier
	v_mfma_f32_16x16x32_bf16 v[0:3], v[114:117], v[86:89], v[0:3]
	v_mfma_f32_16x16x32_bf16 v[4:7], v[122:125], v[86:89], v[4:7]
	v_mfma_f32_16x16x32_bf16 v[10:13], v[114:117], v[198:201], v[10:13]
	v_mfma_f32_16x16x32_bf16 v[14:17], v[122:125], v[198:201], v[14:17]
	v_mfma_f32_16x16x32_bf16 v[0:3], v[118:121], v[90:93], v[0:3]
	v_mfma_f32_16x16x32_bf16 v[4:7], v[146:149], v[90:93], v[4:7]
	v_mfma_f32_16x16x32_bf16 v[154:157], v[114:117], v[182:185], v[154:157]
	v_mfma_f32_16x16x32_bf16 v[158:161], v[122:125], v[182:185], v[158:161]
	v_mfma_f32_16x16x32_bf16 v[162:165], v[114:117], v[190:193], v[162:165]
	v_mfma_f32_16x16x32_bf16 v[166:169], v[122:125], v[190:193], v[166:169]
	v_mfma_f32_16x16x32_bf16 v[10:13], v[118:121], v[202:205], v[10:13]
	v_mfma_f32_16x16x32_bf16 v[14:17], v[146:149], v[202:205], v[14:17]
	v_mfma_f32_16x16x32_bf16 v[154:157], v[118:121], v[186:189], v[154:157]
	v_mfma_f32_16x16x32_bf16 v[158:161], v[146:149], v[186:189], v[158:161]
	v_mfma_f32_16x16x32_bf16 v[162:165], v[118:121], v[194:197], v[162:165]
	v_mfma_f32_16x16x32_bf16 v[166:169], v[146:149], v[194:197], v[166:169]
	s_setprio 0
	s_setprio 1
	v_mfma_f32_16x16x32_bf16 v[30:33], v[174:177], v[86:89], v[30:33]
	v_mfma_f32_16x16x32_bf16 v[58:61], v[174:177], v[182:185], v[58:61]
	v_mfma_f32_16x16x32_bf16 v[18:21], v[150:153], v[86:89], v[18:21]
	v_mfma_f32_16x16x32_bf16 v[146:149], v[178:181], v[90:93], v[30:33]
	v_mfma_f32_16x16x32_bf16 v[30:33], v[150:153], v[182:185], v[34:37]
	v_mfma_f32_16x16x32_bf16 v[182:185], v[178:181], v[186:189], v[58:61]
	v_mfma_f32_16x16x32_bf16 v[58:61], v[150:153], v[190:193], v[106:109]
	v_mfma_f32_16x16x32_bf16 v[22:25], v[150:153], v[198:201], v[22:25]
	v_mfma_f32_16x16x32_bf16 v[18:21], v[170:173], v[90:93], v[18:21]
	v_mfma_f32_16x16x32_bf16 v[32:35], v[170:173], v[186:189], v[30:33]
	v_mfma_f32_16x16x32_bf16 v[186:189], v[170:173], v[194:197], v[58:61]
	v_mfma_f32_16x16x32_bf16 v[58:61], v[174:177], v[190:193], v[110:113]
	v_mfma_f32_16x16x32_bf16 v[150:153], v[170:173], v[202:205], v[22:25]
	v_mfma_f32_16x16x32_bf16 v[22:25], v[174:177], v[198:201], v[26:29]
	v_mfma_f32_16x16x32_bf16 v[190:193], v[178:181], v[194:197], v[58:61]
	v_mfma_f32_16x16x32_bf16 v[170:173], v[178:181], v[202:205], v[22:25]
	s_setprio 0
	s_barrier
	ds_read_b128 v[174:177], v8
	ds_read_b128 v[178:181], v8 offset:1024
	ds_read_b128 v[194:197], v8 offset:2048
	ds_read_b128 v[198:201], v8 offset:3072
	ds_read_b128 v[202:205], v9
	ds_read_b128 v[210:213], v9 offset:1024
	ds_read_b128 v[214:217], v9 offset:2048
	ds_read_b128 v[230:233], v9 offset:3072
	s_add_u32 s44, s40, 0x18000
	s_addc_u32 s45, s41, 0
	s_mov_b32 m0, s55
	v_lshl_add_u64 v[8:9], s[44:45], 0, v[134:135]
	ds_read_b128 v[22:25], v141 offset:32768
	ds_read_b128 v[26:29], v141 offset:33792
	ds_read_b128 v[58:61], v141 offset:34816
	ds_read_b128 v[234:237], v141 offset:35840
	ds_read_b128 v[238:241], v141 offset:36864
	ds_read_b128 v[242:245], v141 offset:37888
	ds_read_b128 v[246:249], v141 offset:38912
	ds_read_b128 v[250:253], v141 offset:39936
	global_load_lds_dwordx4 v[8:9], off
	v_lshl_add_u64 v[8:9], s[44:45], 0, v[130:131]
	s_mov_b32 m0, s56
	s_nop 0
	global_load_lds_dwordx4 v[8:9], off
	s_waitcnt vmcnt(8)
	s_waitcnt lgkmcnt(0)
	s_setprio 1
	s_barrier
	v_mfma_f32_16x16x32_bf16 v[62:65], v[174:177], v[22:25], v[62:65]
	v_mfma_f32_16x16x32_bf16 v[120:123], v[178:181], v[26:29], v[62:65]
	v_mfma_f32_16x16x32_bf16 v[62:65], v[194:197], v[22:25], v[66:69]
	v_mfma_f32_16x16x32_bf16 v[124:127], v[198:201], v[26:29], v[62:65]
	v_mfma_f32_16x16x32_bf16 v[62:65], v[174:177], v[58:61], v[70:73]
	v_mfma_f32_16x16x32_bf16 v[104:107], v[178:181], v[234:237], v[62:65]
	v_mfma_f32_16x16x32_bf16 v[62:65], v[194:197], v[58:61], v[74:77]
	v_mfma_f32_16x16x32_bf16 v[108:111], v[198:201], v[234:237], v[62:65]
	v_mfma_f32_16x16x32_bf16 v[62:65], v[174:177], v[238:241], v[78:81]
	v_mfma_f32_16x16x32_bf16 v[88:91], v[178:181], v[242:245], v[62:65]
	v_mfma_f32_16x16x32_bf16 v[62:65], v[194:197], v[238:241], v[82:85]
	v_mfma_f32_16x16x32_bf16 v[92:95], v[198:201], v[242:245], v[62:65]
	v_mfma_f32_16x16x32_bf16 v[62:65], v[174:177], v[246:249], v[218:221]
	v_mfma_f32_16x16x32_bf16 v[72:75], v[178:181], v[250:253], v[62:65]
	v_mfma_f32_16x16x32_bf16 v[62:65], v[194:197], v[246:249], v[222:225]
	v_mfma_f32_16x16x32_bf16 v[76:79], v[198:201], v[250:253], v[62:65]
	s_setprio 0
	s_setprio 1
	v_mfma_f32_16x16x32_bf16 v[62:65], v[202:205], v[22:25], v[226:229]
	v_mfma_f32_16x16x32_bf16 v[22:25], v[214:217], v[22:25], v[96:99]
	v_mfma_f32_16x16x32_bf16 v[116:119], v[230:233], v[26:29], v[22:25]
	v_mfma_f32_16x16x32_bf16 v[22:25], v[202:205], v[58:61], v[100:103]
	v_mfma_f32_16x16x32_bf16 v[96:99], v[210:213], v[234:237], v[22:25]
	v_mfma_f32_16x16x32_bf16 v[22:25], v[214:217], v[58:61], v[38:41]
	v_mfma_f32_16x16x32_bf16 v[100:103], v[230:233], v[234:237], v[22:25]
	v_mfma_f32_16x16x32_bf16 v[22:25], v[202:205], v[238:241], v[42:45]
	v_mfma_f32_16x16x32_bf16 v[80:83], v[210:213], v[242:245], v[22:25]
	v_mfma_f32_16x16x32_bf16 v[22:25], v[214:217], v[238:241], v[46:49]
	v_mfma_f32_16x16x32_bf16 v[84:87], v[230:233], v[242:245], v[22:25]
	v_mfma_f32_16x16x32_bf16 v[22:25], v[202:205], v[246:249], v[50:53]
	v_mfma_f32_16x16x32_bf16 v[112:115], v[210:213], v[26:29], v[62:65]
	v_mfma_f32_16x16x32_bf16 v[64:67], v[210:213], v[250:253], v[22:25]
	v_mfma_f32_16x16x32_bf16 v[22:25], v[214:217], v[246:249], v[54:57]
	v_mfma_f32_16x16x32_bf16 v[68:71], v[230:233], v[250:253], v[22:25]
	s_setprio 0
	s_barrier
	s_mov_b32 m0, s73
	v_lshl_add_u64 v[8:9], v[206:207], 0, s[16:17]
	s_add_u32 s44, s6, 0x18080
	ds_read_b128 v[36:39], v141 offset:49152
	ds_read_b128 v[52:55], v141 offset:50176
	ds_read_b128 v[218:221], v141 offset:51200
	ds_read_b128 v[222:225], v141 offset:52224
	ds_read_b128 v[226:229], v141 offset:53248
	ds_read_b128 v[234:237], v141 offset:54272
	ds_read_b128 v[238:241], v141 offset:55296
	ds_read_b128 v[242:245], v141 offset:56320
	global_load_lds_dwordx4 v[8:9], off
	v_lshl_add_u64 v[8:9], v[136:137], 0, s[16:17]
	s_mov_b32 m0, s70
	s_addc_u32 s45, s7, 0
	global_load_lds_dwordx4 v[8:9], off
	v_lshl_add_u64 v[8:9], s[44:45], 0, v[132:133]
	s_mov_b32 m0, s71
	s_nop 0
	global_load_lds_dwordx4 v[8:9], off
	v_lshl_add_u64 v[8:9], s[44:45], 0, v[128:129]
	s_mov_b32 m0, s72
	s_nop 0
	global_load_lds_dwordx4 v[8:9], off
	v_lshl_add_u64 v[8:9], v[138:139], 0, s[16:17]
	s_mov_b32 m0, s57
	s_nop 0
	global_load_lds_dwordx4 v[8:9], off
	v_lshl_add_u64 v[8:9], v[142:143], 0, s[16:17]
	s_mov_b32 m0, s58
	s_nop 0
	global_load_lds_dwordx4 v[8:9], off
	s_waitcnt vmcnt(8)
	s_waitcnt lgkmcnt(0)
	s_setprio 1
	s_barrier
	v_mfma_f32_16x16x32_bf16 v[0:3], v[174:177], v[36:39], v[0:3]
	v_mfma_f32_16x16x32_bf16 v[56:59], v[178:181], v[52:55], v[0:3]
	v_mfma_f32_16x16x32_bf16 v[0:3], v[194:197], v[36:39], v[4:7]
	v_mfma_f32_16x16x32_bf16 v[60:63], v[198:201], v[52:55], v[0:3]
	v_mfma_f32_16x16x32_bf16 v[0:3], v[174:177], v[218:221], v[154:157]
	v_mfma_f32_16x16x32_bf16 v[40:43], v[178:181], v[222:225], v[0:3]
	v_mfma_f32_16x16x32_bf16 v[0:3], v[194:197], v[218:221], v[158:161]
	v_mfma_f32_16x16x32_bf16 v[44:47], v[198:201], v[222:225], v[0:3]
	v_mfma_f32_16x16x32_bf16 v[0:3], v[174:177], v[226:229], v[162:165]
	v_mfma_f32_16x16x32_bf16 v[24:27], v[178:181], v[234:237], v[0:3]
	v_mfma_f32_16x16x32_bf16 v[0:3], v[194:197], v[226:229], v[166:169]
	v_mfma_f32_16x16x32_bf16 v[28:31], v[198:201], v[234:237], v[0:3]
	v_mfma_f32_16x16x32_bf16 v[0:3], v[174:177], v[238:241], v[10:13]
	v_mfma_f32_16x16x32_bf16 v[8:11], v[178:181], v[242:245], v[0:3]
	v_mfma_f32_16x16x32_bf16 v[0:3], v[194:197], v[238:241], v[14:17]
	v_mfma_f32_16x16x32_bf16 v[12:15], v[198:201], v[242:245], v[0:3]
	s_setprio 0
	s_setprio 1
	v_mfma_f32_16x16x32_bf16 v[0:3], v[202:205], v[36:39], v[18:21]
	v_mfma_f32_16x16x32_bf16 v[48:51], v[210:213], v[52:55], v[0:3]
	v_mfma_f32_16x16x32_bf16 v[0:3], v[214:217], v[36:39], v[146:149]
	v_mfma_f32_16x16x32_bf16 v[52:55], v[230:233], v[52:55], v[0:3]
	v_mfma_f32_16x16x32_bf16 v[0:3], v[202:205], v[218:221], v[32:35]
	v_mfma_f32_16x16x32_bf16 v[32:35], v[210:213], v[222:225], v[0:3]
	v_mfma_f32_16x16x32_bf16 v[0:3], v[214:217], v[218:221], v[182:185]
	v_mfma_f32_16x16x32_bf16 v[36:39], v[230:233], v[222:225], v[0:3]
	v_mfma_f32_16x16x32_bf16 v[0:3], v[202:205], v[226:229], v[186:189]
	v_mfma_f32_16x16x32_bf16 v[16:19], v[210:213], v[234:237], v[0:3]
	v_mfma_f32_16x16x32_bf16 v[0:3], v[214:217], v[226:229], v[190:193]
	v_mfma_f32_16x16x32_bf16 v[20:23], v[230:233], v[234:237], v[0:3]
	v_mfma_f32_16x16x32_bf16 v[0:3], v[202:205], v[238:241], v[150:153]
	v_mfma_f32_16x16x32_bf16 v[4:7], v[214:217], v[238:241], v[170:173]
	v_mfma_f32_16x16x32_bf16 v[0:3], v[210:213], v[242:245], v[0:3]
	v_mfma_f32_16x16x32_bf16 v[4:7], v[230:233], v[242:245], v[4:7]
	s_setprio 0
	s_barrier
	s_andn2_b64 vcc, exec, s[18:19]
	s_cbranch_vccnz .LBB0_1148
	s_barrier

.LBB0_1227:
	ds_read_b128 v[144:147], v151
	ds_read_b128 v[154:157], v151 offset:1024
	ds_read_b128 v[158:161], v151 offset:2048
	ds_read_b128 v[162:165], v151 offset:3072
	ds_read_b128 v[166:169], v152
	ds_read_b128 v[170:173], v152 offset:1024
	ds_read_b128 v[174:177], v152 offset:2048
	ds_read_b128 v[178:181], v152 offset:3072
	s_add_u32 s44, s42, 0xfffc0080
	s_addc_u32 s45, s43, -1
	s_cmp_eq_u32 s67, 12
	s_cselect_b32 s47, s23, s45
	s_cselect_b32 s46, s39, s44
	s_cselect_b32 s45, s21, s66
	s_cselect_b32 s44, s64, s65
	v_lshl_add_u64 v[206:207], s[42:43], 0, v[136:137]
	s_add_i32 m0, s41, 0xc000
	ds_read_b128 v[182:185], v153
	ds_read_b128 v[186:189], v153 offset:1024
	ds_read_b128 v[190:193], v153 offset:2048
	ds_read_b128 v[194:197], v153 offset:3072
	ds_read_b128 v[198:201], v153 offset:4096
	ds_read_b128 v[202:205], v153 offset:5120
	ds_read_b128 v[210:213], v153 offset:6144
	ds_read_b128 v[214:217], v153 offset:7168
	global_load_lds_dwordx4 v[206:207], off
	v_lshl_add_u64 v[206:207], s[42:43], 0, v[138:139]
	s_add_i32 m0, s41, 0xe000
	s_nop 0
	global_load_lds_dwordx4 v[206:207], off
	s_waitcnt vmcnt(8)
	s_waitcnt lgkmcnt(0)
	s_setprio 1
	s_barrier
	v_mfma_f32_16x16x32_bf16 v[120:123], v[144:147], v[182:185], v[120:123]
	v_mfma_f32_16x16x32_bf16 v[112:115], v[158:161], v[182:185], v[112:115]
	v_mfma_f32_16x16x32_bf16 v[104:107], v[144:147], v[190:193], v[104:107]
	v_mfma_f32_16x16x32_bf16 v[96:99], v[158:161], v[190:193], v[96:99]
	v_mfma_f32_16x16x32_bf16 v[88:91], v[144:147], v[198:201], v[88:91]
	v_mfma_f32_16x16x32_bf16 v[80:83], v[158:161], v[198:201], v[80:83]
	v_mfma_f32_16x16x32_bf16 v[72:75], v[144:147], v[210:213], v[72:75]
	v_mfma_f32_16x16x32_bf16 v[64:67], v[158:161], v[210:213], v[64:67]
	v_mfma_f32_16x16x32_bf16 v[120:123], v[154:157], v[186:189], v[120:123]
	v_mfma_f32_16x16x32_bf16 v[112:115], v[162:165], v[186:189], v[112:115]
	v_mfma_f32_16x16x32_bf16 v[104:107], v[154:157], v[194:197], v[104:107]
	v_mfma_f32_16x16x32_bf16 v[96:99], v[162:165], v[194:197], v[96:99]
	v_mfma_f32_16x16x32_bf16 v[88:91], v[154:157], v[202:205], v[88:91]
	v_mfma_f32_16x16x32_bf16 v[80:83], v[162:165], v[202:205], v[80:83]
	v_mfma_f32_16x16x32_bf16 v[72:75], v[154:157], v[214:217], v[72:75]
	v_mfma_f32_16x16x32_bf16 v[64:67], v[162:165], v[214:217], v[64:67]
	s_setprio 0
	s_setprio 1
	v_mfma_f32_16x16x32_bf16 v[124:127], v[166:169], v[182:185], v[124:127]
	v_mfma_f32_16x16x32_bf16 v[116:119], v[174:177], v[182:185], v[116:119]
	v_mfma_f32_16x16x32_bf16 v[108:111], v[166:169], v[190:193], v[108:111]
	v_mfma_f32_16x16x32_bf16 v[100:103], v[174:177], v[190:193], v[100:103]
	v_mfma_f32_16x16x32_bf16 v[92:95], v[166:169], v[198:201], v[92:95]
	v_mfma_f32_16x16x32_bf16 v[84:87], v[174:177], v[198:201], v[84:87]
	v_mfma_f32_16x16x32_bf16 v[76:79], v[166:169], v[210:213], v[76:79]
	v_mfma_f32_16x16x32_bf16 v[68:71], v[174:177], v[210:213], v[68:71]
	v_mfma_f32_16x16x32_bf16 v[124:127], v[170:173], v[186:189], v[124:127]
	v_mfma_f32_16x16x32_bf16 v[116:119], v[178:181], v[186:189], v[116:119]
	v_mfma_f32_16x16x32_bf16 v[108:111], v[170:173], v[194:197], v[108:111]
	v_mfma_f32_16x16x32_bf16 v[100:103], v[178:181], v[194:197], v[100:103]
	v_mfma_f32_16x16x32_bf16 v[92:95], v[170:173], v[202:205], v[92:95]
	v_mfma_f32_16x16x32_bf16 v[84:87], v[178:181], v[202:205], v[84:87]
	v_mfma_f32_16x16x32_bf16 v[76:79], v[170:173], v[214:217], v[76:79]
	v_mfma_f32_16x16x32_bf16 v[68:71], v[178:181], v[214:217], v[68:71]
	s_setprio 0
	s_barrier
	s_add_i32 s68, s62, s52
	v_lshl_add_u64 v[206:207], s[44:45], 0, v[130:131]
	s_mov_b32 m0, s68
	ds_read_b128 v[182:185], v153 offset:16384
	ds_read_b128 v[186:189], v153 offset:17408
	ds_read_b128 v[190:193], v153 offset:18432
	ds_read_b128 v[194:197], v153 offset:19456
	ds_read_b128 v[198:201], v153 offset:20480
	ds_read_b128 v[202:205], v153 offset:21504
	ds_read_b128 v[210:213], v153 offset:22528
	ds_read_b128 v[214:217], v153 offset:23552
	global_load_lds_dwordx4 v[206:207], off
	s_add_i32 m0, s68, 0x2000
	s_add_u32 s68, s44, 0x40000
	v_lshl_add_u64 v[218:219], s[44:45], 0, v[134:135]
	s_addc_u32 s69, s45, 0
	s_add_i32 s70, s63, s52
	global_load_lds_dwordx4 v[218:219], off
	v_lshl_add_u64 v[220:221], s[68:69], 0, v[130:131]
	s_mov_b32 m0, s70
	v_lshl_add_u64 v[222:223], s[46:47], 0, v[132:133]
	global_load_lds_dwordx4 v[220:221], off
	v_lshl_add_u64 v[220:221], s[68:69], 0, v[134:135]
	s_add_i32 m0, s70, 0x2000
	s_nop 0
	global_load_lds_dwordx4 v[220:221], off
	v_lshl_add_u64 v[220:221], s[46:47], 0, v[128:129]
	s_mov_b32 m0, s41
	s_nop 0
	global_load_lds_dwordx4 v[220:221], off
	s_mov_b32 m0, s53
	s_nop 0
	global_load_lds_dwordx4 v[222:223], off
	s_waitcnt vmcnt(8)
	s_waitcnt lgkmcnt(0)
	s_setprio 1
	s_barrier
	v_mfma_f32_16x16x32_bf16 v[56:59], v[144:147], v[182:185], v[56:59]
	v_mfma_f32_16x16x32_bf16 v[48:51], v[158:161], v[182:185], v[48:51]
	v_mfma_f32_16x16x32_bf16 v[40:43], v[144:147], v[190:193], v[40:43]
	v_mfma_f32_16x16x32_bf16 v[32:35], v[158:161], v[190:193], v[32:35]
	v_mfma_f32_16x16x32_bf16 v[24:27], v[144:147], v[198:201], v[24:27]
	v_mfma_f32_16x16x32_bf16 v[16:19], v[158:161], v[198:201], v[16:19]
	v_mfma_f32_16x16x32_bf16 v[8:11], v[144:147], v[210:213], v[8:11]
	v_mfma_f32_16x16x32_bf16 v[0:3], v[158:161], v[210:213], v[0:3]
	v_mfma_f32_16x16x32_bf16 v[56:59], v[154:157], v[186:189], v[56:59]
	v_mfma_f32_16x16x32_bf16 v[48:51], v[162:165], v[186:189], v[48:51]
	v_mfma_f32_16x16x32_bf16 v[40:43], v[154:157], v[194:197], v[40:43]
	v_mfma_f32_16x16x32_bf16 v[32:35], v[162:165], v[194:197], v[32:35]
	v_mfma_f32_16x16x32_bf16 v[24:27], v[154:157], v[202:205], v[24:27]
	v_mfma_f32_16x16x32_bf16 v[16:19], v[162:165], v[202:205], v[16:19]
	v_mfma_f32_16x16x32_bf16 v[8:11], v[154:157], v[214:217], v[8:11]
	v_mfma_f32_16x16x32_bf16 v[0:3], v[162:165], v[214:217], v[0:3]
	s_setprio 0
	s_setprio 1
	v_mfma_f32_16x16x32_bf16 v[60:63], v[166:169], v[182:185], v[60:63]
	v_mfma_f32_16x16x32_bf16 v[52:55], v[174:177], v[182:185], v[52:55]
	v_mfma_f32_16x16x32_bf16 v[44:47], v[166:169], v[190:193], v[44:47]
	v_mfma_f32_16x16x32_bf16 v[36:39], v[174:177], v[190:193], v[36:39]
	v_mfma_f32_16x16x32_bf16 v[28:31], v[166:169], v[198:201], v[28:31]
	v_mfma_f32_16x16x32_bf16 v[20:23], v[174:177], v[198:201], v[20:23]
	v_mfma_f32_16x16x32_bf16 v[12:15], v[166:169], v[210:213], v[12:15]
	v_mfma_f32_16x16x32_bf16 v[4:7], v[174:177], v[210:213], v[4:7]
	v_mfma_f32_16x16x32_bf16 v[60:63], v[170:173], v[186:189], v[60:63]
	v_mfma_f32_16x16x32_bf16 v[52:55], v[178:181], v[186:189], v[52:55]
	v_mfma_f32_16x16x32_bf16 v[44:47], v[170:173], v[194:197], v[44:47]
	v_mfma_f32_16x16x32_bf16 v[36:39], v[178:181], v[194:197], v[36:39]
	v_mfma_f32_16x16x32_bf16 v[28:31], v[170:173], v[202:205], v[28:31]
	v_mfma_f32_16x16x32_bf16 v[20:23], v[178:181], v[202:205], v[20:23]
	v_mfma_f32_16x16x32_bf16 v[12:15], v[170:173], v[214:217], v[12:15]
	v_mfma_f32_16x16x32_bf16 v[4:7], v[178:181], v[214:217], v[4:7]
	s_setprio 0
	s_barrier
	s_add_i32 s68, 0, 0x18000
	s_add_i32 s69, 0, 0x1c000
	v_add_u32_e32 v162, s68, v149
	v_add_u32_e32 v178, s69, v149
	ds_read_b128 v[144:147], v162
	ds_read_b128 v[154:157], v162 offset:1024
	ds_read_b128 v[158:161], v162 offset:2048
	ds_read_b128 v[162:165], v162 offset:3072
	ds_read_b128 v[166:169], v178
	ds_read_b128 v[170:173], v178 offset:1024
	ds_read_b128 v[174:177], v178 offset:2048
	ds_read_b128 v[178:181], v178 offset:3072
	s_add_u32 s46, s46, 0x40000
	s_addc_u32 s47, s47, 0
	s_mov_b32 m0, s54
	v_lshl_add_u64 v[224:225], s[46:47], 0, v[128:129]
	ds_read_b128 v[182:185], v153 offset:32768
	ds_read_b128 v[186:189], v153 offset:33792
	ds_read_b128 v[190:193], v153 offset:34816
	ds_read_b128 v[194:197], v153 offset:35840
	ds_read_b128 v[198:201], v153 offset:36864
	ds_read_b128 v[202:205], v153 offset:37888
	ds_read_b128 v[210:213], v153 offset:38912
	ds_read_b128 v[214:217], v153 offset:39936
	global_load_lds_dwordx4 v[224:225], off
	v_lshl_add_u64 v[224:225], s[46:47], 0, v[132:133]
	s_mov_b32 m0, s55
	s_nop 0
	global_load_lds_dwordx4 v[224:225], off
	s_waitcnt vmcnt(8)
	s_waitcnt lgkmcnt(0)
	s_setprio 1
	s_barrier
	v_mfma_f32_16x16x32_bf16 v[120:123], v[144:147], v[182:185], v[120:123]
	v_mfma_f32_16x16x32_bf16 v[112:115], v[158:161], v[182:185], v[112:115]
	v_mfma_f32_16x16x32_bf16 v[104:107], v[144:147], v[190:193], v[104:107]
	v_mfma_f32_16x16x32_bf16 v[96:99], v[158:161], v[190:193], v[96:99]
	v_mfma_f32_16x16x32_bf16 v[88:91], v[144:147], v[198:201], v[88:91]
	v_mfma_f32_16x16x32_bf16 v[80:83], v[158:161], v[198:201], v[80:83]
	v_mfma_f32_16x16x32_bf16 v[72:75], v[144:147], v[210:213], v[72:75]
	v_mfma_f32_16x16x32_bf16 v[64:67], v[158:161], v[210:213], v[64:67]
	v_mfma_f32_16x16x32_bf16 v[120:123], v[154:157], v[186:189], v[120:123]
	v_mfma_f32_16x16x32_bf16 v[112:115], v[162:165], v[186:189], v[112:115]
	v_mfma_f32_16x16x32_bf16 v[104:107], v[154:157], v[194:197], v[104:107]
	v_mfma_f32_16x16x32_bf16 v[96:99], v[162:165], v[194:197], v[96:99]
	v_mfma_f32_16x16x32_bf16 v[88:91], v[154:157], v[202:205], v[88:91]
	v_mfma_f32_16x16x32_bf16 v[80:83], v[162:165], v[202:205], v[80:83]
	v_mfma_f32_16x16x32_bf16 v[72:75], v[154:157], v[214:217], v[72:75]
	v_mfma_f32_16x16x32_bf16 v[64:67], v[162:165], v[214:217], v[64:67]
	s_setprio 0
	s_setprio 1
	v_mfma_f32_16x16x32_bf16 v[124:127], v[166:169], v[182:185], v[124:127]
	v_mfma_f32_16x16x32_bf16 v[116:119], v[174:177], v[182:185], v[116:119]
	v_mfma_f32_16x16x32_bf16 v[108:111], v[166:169], v[190:193], v[108:111]
	v_mfma_f32_16x16x32_bf16 v[100:103], v[174:177], v[190:193], v[100:103]
	v_mfma_f32_16x16x32_bf16 v[92:95], v[166:169], v[198:201], v[92:95]
	v_mfma_f32_16x16x32_bf16 v[84:87], v[174:177], v[198:201], v[84:87]
	v_mfma_f32_16x16x32_bf16 v[76:79], v[166:169], v[210:213], v[76:79]
	v_mfma_f32_16x16x32_bf16 v[68:71], v[174:177], v[210:213], v[68:71]
	v_mfma_f32_16x16x32_bf16 v[124:127], v[170:173], v[186:189], v[124:127]
	v_mfma_f32_16x16x32_bf16 v[116:119], v[178:181], v[186:189], v[116:119]
	v_mfma_f32_16x16x32_bf16 v[108:111], v[170:173], v[194:197], v[108:111]
	v_mfma_f32_16x16x32_bf16 v[100:103], v[178:181], v[194:197], v[100:103]
	v_mfma_f32_16x16x32_bf16 v[92:95], v[170:173], v[202:205], v[92:95]
	v_mfma_f32_16x16x32_bf16 v[84:87], v[178:181], v[202:205], v[84:87]
	v_mfma_f32_16x16x32_bf16 v[76:79], v[170:173], v[214:217], v[76:79]
	v_mfma_f32_16x16x32_bf16 v[68:71], v[178:181], v[214:217], v[68:71]
	s_setprio 0
	s_barrier
	s_add_i32 s46, s68, s52
	v_lshl_add_u64 v[206:207], v[206:207], 0, s[16:17]
	s_mov_b32 m0, s46
	ds_read_b128 v[182:185], v153 offset:49152
	ds_read_b128 v[186:189], v153 offset:50176
	ds_read_b128 v[190:193], v153 offset:51200
	ds_read_b128 v[194:197], v153 offset:52224
	ds_read_b128 v[198:201], v153 offset:53248
	ds_read_b128 v[202:205], v153 offset:54272
	ds_read_b128 v[210:213], v153 offset:55296
	ds_read_b128 v[214:217], v153 offset:56320
	global_load_lds_dwordx4 v[206:207], off
	s_add_i32 m0, s46, 0x2000
	s_add_u32 s44, s44, 0x40080
	v_lshl_add_u64 v[206:207], v[218:219], 0, s[16:17]
	s_addc_u32 s45, s45, 0
	s_add_i32 s46, s69, s52
	global_load_lds_dwordx4 v[206:207], off
	v_lshl_add_u64 v[206:207], s[44:45], 0, v[130:131]
	s_mov_b32 m0, s46
	s_nop 0
	global_load_lds_dwordx4 v[206:207], off
	v_lshl_add_u64 v[206:207], s[44:45], 0, v[134:135]
	s_add_i32 m0, s46, 0x2000
	s_nop 0
	global_load_lds_dwordx4 v[206:207], off
	v_lshl_add_u64 v[206:207], v[220:221], 0, s[16:17]
	s_mov_b32 m0, s57
	s_nop 0
	global_load_lds_dwordx4 v[206:207], off
	v_lshl_add_u64 v[206:207], v[222:223], 0, s[16:17]
	s_mov_b32 m0, s58
	s_nop 0
	global_load_lds_dwordx4 v[206:207], off
	s_waitcnt vmcnt(8)
	s_waitcnt lgkmcnt(0)
	s_setprio 1
	s_barrier
	v_mfma_f32_16x16x32_bf16 v[56:59], v[144:147], v[182:185], v[56:59]
	v_mfma_f32_16x16x32_bf16 v[48:51], v[158:161], v[182:185], v[48:51]
	v_mfma_f32_16x16x32_bf16 v[40:43], v[144:147], v[190:193], v[40:43]
	v_mfma_f32_16x16x32_bf16 v[32:35], v[158:161], v[190:193], v[32:35]
	v_mfma_f32_16x16x32_bf16 v[24:27], v[144:147], v[198:201], v[24:27]
	v_mfma_f32_16x16x32_bf16 v[16:19], v[158:161], v[198:201], v[16:19]
	v_mfma_f32_16x16x32_bf16 v[8:11], v[144:147], v[210:213], v[8:11]
	v_mfma_f32_16x16x32_bf16 v[0:3], v[158:161], v[210:213], v[0:3]
	v_mfma_f32_16x16x32_bf16 v[56:59], v[154:157], v[186:189], v[56:59]
	v_mfma_f32_16x16x32_bf16 v[48:51], v[162:165], v[186:189], v[48:51]
	v_mfma_f32_16x16x32_bf16 v[40:43], v[154:157], v[194:197], v[40:43]
	v_mfma_f32_16x16x32_bf16 v[32:35], v[162:165], v[194:197], v[32:35]
	v_mfma_f32_16x16x32_bf16 v[24:27], v[154:157], v[202:205], v[24:27]
	v_mfma_f32_16x16x32_bf16 v[16:19], v[162:165], v[202:205], v[16:19]
	v_mfma_f32_16x16x32_bf16 v[8:11], v[154:157], v[214:217], v[8:11]
	v_mfma_f32_16x16x32_bf16 v[0:3], v[162:165], v[214:217], v[0:3]
	s_setprio 0
	s_setprio 1
	v_mfma_f32_16x16x32_bf16 v[60:63], v[166:169], v[182:185], v[60:63]
	v_mfma_f32_16x16x32_bf16 v[52:55], v[174:177], v[182:185], v[52:55]
	v_mfma_f32_16x16x32_bf16 v[44:47], v[166:169], v[190:193], v[44:47]
	v_mfma_f32_16x16x32_bf16 v[36:39], v[174:177], v[190:193], v[36:39]
	v_mfma_f32_16x16x32_bf16 v[28:31], v[166:169], v[198:201], v[28:31]
	v_mfma_f32_16x16x32_bf16 v[20:23], v[174:177], v[198:201], v[20:23]
	v_mfma_f32_16x16x32_bf16 v[12:15], v[166:169], v[210:213], v[12:15]
	v_mfma_f32_16x16x32_bf16 v[4:7], v[174:177], v[210:213], v[4:7]
	v_mfma_f32_16x16x32_bf16 v[60:63], v[170:173], v[186:189], v[60:63]
	v_mfma_f32_16x16x32_bf16 v[52:55], v[178:181], v[186:189], v[52:55]
	v_mfma_f32_16x16x32_bf16 v[44:47], v[170:173], v[194:197], v[44:47]
	v_mfma_f32_16x16x32_bf16 v[36:39], v[178:181], v[194:197], v[36:39]
	v_mfma_f32_16x16x32_bf16 v[28:31], v[170:173], v[202:205], v[28:31]
	v_mfma_f32_16x16x32_bf16 v[20:23], v[178:181], v[202:205], v[20:23]
	v_mfma_f32_16x16x32_bf16 v[12:15], v[170:173], v[214:217], v[12:15]
	v_mfma_f32_16x16x32_bf16 v[4:7], v[178:181], v[214:217], v[4:7]
	s_setprio 0
	s_barrier
	s_add_i32 s67, s67, 2
	s_add_u32 s42, s42, 0x100
	s_addc_u32 s43, s43, 0
	s_add_u32 s65, s65, 0x100
	s_addc_u32 s66, s66, 0
	s_cmp_gt_u32 s67, 13
	s_cbranch_scc0 .LBB0_1227
	s_and_b64 vcc, exec, s[18:19]
	s_cbranch_vccz .LBB0_1230
	s_barrier

.LBB0_1322:
	ds_read_b128 v[152:155], v149
	ds_read_b128 v[156:159], v149 offset:1024
	ds_read_b128 v[160:163], v149 offset:2048
	ds_read_b128 v[164:167], v149 offset:3072
	ds_read_b128 v[168:171], v150
	ds_read_b128 v[172:175], v150 offset:1024
	ds_read_b128 v[176:179], v150 offset:2048
	ds_read_b128 v[180:183], v150 offset:3072
	s_add_u32 s46, s44, 0xfffc0080
	s_addc_u32 s47, s45, -1
	s_cmp_eq_u32 s75, 12
	s_cselect_b32 s49, s37, s47
	s_cselect_b32 s48, s71, s46
	s_cselect_b32 s47, s25, s74
	s_cselect_b32 s46, s72, s73
	v_lshl_add_u64 v[144:145], s[44:45], 0, v[136:137]
	s_add_i32 m0, s43, 0xc000
	ds_read_b128 v[184:187], v151
	ds_read_b128 v[188:191], v151 offset:1024
	ds_read_b128 v[192:195], v151 offset:2048
	ds_read_b128 v[196:199], v151 offset:3072
	ds_read_b128 v[200:203], v151 offset:4096
	ds_read_b128 v[204:207], v151 offset:5120
	ds_read_b128 v[210:213], v151 offset:6144
	ds_read_b128 v[214:217], v151 offset:7168
	global_load_lds_dwordx4 v[144:145], off
	v_lshl_add_u64 v[144:145], s[44:45], 0, v[138:139]
	s_add_i32 m0, s43, 0xe000
	s_nop 0
	global_load_lds_dwordx4 v[144:145], off
	s_waitcnt vmcnt(8)
	s_waitcnt lgkmcnt(0)
	s_setprio 1
	s_barrier
	v_mfma_f32_16x16x32_bf16 v[124:127], v[152:155], v[184:187], v[124:127]
	v_mfma_f32_16x16x32_bf16 v[120:123], v[160:163], v[184:187], v[120:123]
	v_mfma_f32_16x16x32_bf16 v[108:111], v[152:155], v[192:195], v[108:111]
	v_mfma_f32_16x16x32_bf16 v[104:107], v[160:163], v[192:195], v[104:107]
	v_mfma_f32_16x16x32_bf16 v[92:95], v[152:155], v[200:203], v[92:95]
	v_mfma_f32_16x16x32_bf16 v[88:91], v[160:163], v[200:203], v[88:91]
	v_mfma_f32_16x16x32_bf16 v[76:79], v[152:155], v[210:213], v[76:79]
	v_mfma_f32_16x16x32_bf16 v[72:75], v[160:163], v[210:213], v[72:75]
	v_mfma_f32_16x16x32_bf16 v[124:127], v[156:159], v[188:191], v[124:127]
	v_mfma_f32_16x16x32_bf16 v[120:123], v[164:167], v[188:191], v[120:123]
	v_mfma_f32_16x16x32_bf16 v[108:111], v[156:159], v[196:199], v[108:111]
	v_mfma_f32_16x16x32_bf16 v[104:107], v[164:167], v[196:199], v[104:107]
	v_mfma_f32_16x16x32_bf16 v[92:95], v[156:159], v[204:207], v[92:95]
	v_mfma_f32_16x16x32_bf16 v[88:91], v[164:167], v[204:207], v[88:91]
	v_mfma_f32_16x16x32_bf16 v[76:79], v[156:159], v[214:217], v[76:79]
	v_mfma_f32_16x16x32_bf16 v[72:75], v[164:167], v[214:217], v[72:75]
	s_setprio 0
	s_setprio 1
	v_mfma_f32_16x16x32_bf16 v[116:119], v[168:171], v[184:187], v[116:119]
	v_mfma_f32_16x16x32_bf16 v[112:115], v[176:179], v[184:187], v[112:115]
	v_mfma_f32_16x16x32_bf16 v[100:103], v[168:171], v[192:195], v[100:103]
	v_mfma_f32_16x16x32_bf16 v[96:99], v[176:179], v[192:195], v[96:99]
	v_mfma_f32_16x16x32_bf16 v[84:87], v[168:171], v[200:203], v[84:87]
	v_mfma_f32_16x16x32_bf16 v[80:83], v[176:179], v[200:203], v[80:83]
	v_mfma_f32_16x16x32_bf16 v[68:71], v[168:171], v[210:213], v[68:71]
	v_mfma_f32_16x16x32_bf16 v[64:67], v[176:179], v[210:213], v[64:67]
	v_mfma_f32_16x16x32_bf16 v[116:119], v[172:175], v[188:191], v[116:119]
	v_mfma_f32_16x16x32_bf16 v[112:115], v[180:183], v[188:191], v[112:115]
	v_mfma_f32_16x16x32_bf16 v[100:103], v[172:175], v[196:199], v[100:103]
	v_mfma_f32_16x16x32_bf16 v[96:99], v[180:183], v[196:199], v[96:99]
	v_mfma_f32_16x16x32_bf16 v[84:87], v[172:175], v[204:207], v[84:87]
	v_mfma_f32_16x16x32_bf16 v[80:83], v[180:183], v[204:207], v[80:83]
	v_mfma_f32_16x16x32_bf16 v[68:71], v[172:175], v[214:217], v[68:71]
	v_mfma_f32_16x16x32_bf16 v[64:67], v[180:183], v[214:217], v[64:67]
	s_setprio 0
	s_barrier
	s_add_i32 s76, s64, s55
	v_lshl_add_u64 v[144:145], s[46:47], 0, v[130:131]
	s_mov_b32 m0, s76
	ds_read_b128 v[184:187], v151 offset:16384
	ds_read_b128 v[188:191], v151 offset:17408
	ds_read_b128 v[192:195], v151 offset:18432
	ds_read_b128 v[196:199], v151 offset:19456
	ds_read_b128 v[200:203], v151 offset:20480
	ds_read_b128 v[204:207], v151 offset:21504
	ds_read_b128 v[210:213], v151 offset:22528
	ds_read_b128 v[214:217], v151 offset:23552
	global_load_lds_dwordx4 v[144:145], off
	s_add_i32 m0, s76, 0x2000
	s_add_u32 s76, s46, 0x40000
	v_lshl_add_u64 v[218:219], s[46:47], 0, v[134:135]
	s_addc_u32 s77, s47, 0
	s_add_i32 s78, s65, s55
	global_load_lds_dwordx4 v[218:219], off
	v_lshl_add_u64 v[220:221], s[76:77], 0, v[130:131]
	s_mov_b32 m0, s78
	v_lshl_add_u64 v[222:223], s[48:49], 0, v[132:133]
	global_load_lds_dwordx4 v[220:221], off
	v_lshl_add_u64 v[220:221], s[76:77], 0, v[134:135]
	s_add_i32 m0, s78, 0x2000
	s_nop 0
	global_load_lds_dwordx4 v[220:221], off
	v_lshl_add_u64 v[220:221], s[48:49], 0, v[128:129]
	s_mov_b32 m0, s43
	s_nop 0
	global_load_lds_dwordx4 v[220:221], off
	s_mov_b32 m0, s56
	s_nop 0
	global_load_lds_dwordx4 v[222:223], off
	s_waitcnt vmcnt(8)
	s_waitcnt lgkmcnt(0)
	s_setprio 1
	s_barrier
	v_mfma_f32_16x16x32_bf16 v[60:63], v[152:155], v[184:187], v[60:63]
	v_mfma_f32_16x16x32_bf16 v[56:59], v[160:163], v[184:187], v[56:59]
	v_mfma_f32_16x16x32_bf16 v[44:47], v[152:155], v[192:195], v[44:47]
	v_mfma_f32_16x16x32_bf16 v[40:43], v[160:163], v[192:195], v[40:43]
	v_mfma_f32_16x16x32_bf16 v[28:31], v[152:155], v[200:203], v[28:31]
	v_mfma_f32_16x16x32_bf16 v[24:27], v[160:163], v[200:203], v[24:27]
	v_mfma_f32_16x16x32_bf16 v[12:15], v[152:155], v[210:213], v[12:15]
	v_mfma_f32_16x16x32_bf16 v[8:11], v[160:163], v[210:213], v[8:11]
	v_mfma_f32_16x16x32_bf16 v[60:63], v[156:159], v[188:191], v[60:63]
	v_mfma_f32_16x16x32_bf16 v[56:59], v[164:167], v[188:191], v[56:59]
	v_mfma_f32_16x16x32_bf16 v[44:47], v[156:159], v[196:199], v[44:47]
	v_mfma_f32_16x16x32_bf16 v[40:43], v[164:167], v[196:199], v[40:43]
	v_mfma_f32_16x16x32_bf16 v[28:31], v[156:159], v[204:207], v[28:31]
	v_mfma_f32_16x16x32_bf16 v[24:27], v[164:167], v[204:207], v[24:27]
	v_mfma_f32_16x16x32_bf16 v[12:15], v[156:159], v[214:217], v[12:15]
	v_mfma_f32_16x16x32_bf16 v[8:11], v[164:167], v[214:217], v[8:11]
	s_setprio 0
	s_setprio 1
	v_mfma_f32_16x16x32_bf16 v[52:55], v[168:171], v[184:187], v[52:55]
	v_mfma_f32_16x16x32_bf16 v[48:51], v[176:179], v[184:187], v[48:51]
	v_mfma_f32_16x16x32_bf16 v[36:39], v[168:171], v[192:195], v[36:39]
	v_mfma_f32_16x16x32_bf16 v[32:35], v[176:179], v[192:195], v[32:35]
	v_mfma_f32_16x16x32_bf16 v[20:23], v[168:171], v[200:203], v[20:23]
	v_mfma_f32_16x16x32_bf16 v[16:19], v[176:179], v[200:203], v[16:19]
	v_mfma_f32_16x16x32_bf16 v[4:7], v[168:171], v[210:213], v[4:7]
	v_mfma_f32_16x16x32_bf16 v[0:3], v[176:179], v[210:213], v[0:3]
	v_mfma_f32_16x16x32_bf16 v[52:55], v[172:175], v[188:191], v[52:55]
	v_mfma_f32_16x16x32_bf16 v[48:51], v[180:183], v[188:191], v[48:51]
	v_mfma_f32_16x16x32_bf16 v[36:39], v[172:175], v[196:199], v[36:39]
	v_mfma_f32_16x16x32_bf16 v[32:35], v[180:183], v[196:199], v[32:35]
	v_mfma_f32_16x16x32_bf16 v[20:23], v[172:175], v[204:207], v[20:23]
	v_mfma_f32_16x16x32_bf16 v[16:19], v[180:183], v[204:207], v[16:19]
	v_mfma_f32_16x16x32_bf16 v[4:7], v[172:175], v[214:217], v[4:7]
	v_mfma_f32_16x16x32_bf16 v[0:3], v[180:183], v[214:217], v[0:3]
	s_setprio 0
	s_barrier
	s_add_i32 s76, 0, 0x18000
	s_add_i32 s77, 0, 0x1c000
	v_add_u32_e32 v164, s76, v147
	v_add_u32_e32 v180, s77, v147
	ds_read_b128 v[152:155], v164
	ds_read_b128 v[156:159], v164 offset:1024
	ds_read_b128 v[160:163], v164 offset:2048
	ds_read_b128 v[164:167], v164 offset:3072
	ds_read_b128 v[168:171], v180
	ds_read_b128 v[172:175], v180 offset:1024
	ds_read_b128 v[176:179], v180 offset:2048
	ds_read_b128 v[180:183], v180 offset:3072
	s_add_u32 s48, s48, 0x40000
	s_addc_u32 s49, s49, 0
	s_mov_b32 m0, s57
	v_lshl_add_u64 v[224:225], s[48:49], 0, v[128:129]
	ds_read_b128 v[184:187], v151 offset:32768
	ds_read_b128 v[188:191], v151 offset:33792
	ds_read_b128 v[192:195], v151 offset:34816
	ds_read_b128 v[196:199], v151 offset:35840
	ds_read_b128 v[200:203], v151 offset:36864
	ds_read_b128 v[204:207], v151 offset:37888
	ds_read_b128 v[210:213], v151 offset:38912
	ds_read_b128 v[214:217], v151 offset:39936
	global_load_lds_dwordx4 v[224:225], off
	v_lshl_add_u64 v[224:225], s[48:49], 0, v[132:133]
	s_mov_b32 m0, s58
	s_nop 0
	global_load_lds_dwordx4 v[224:225], off
	s_waitcnt vmcnt(8)
	s_waitcnt lgkmcnt(0)
	s_setprio 1
	s_barrier
	v_mfma_f32_16x16x32_bf16 v[124:127], v[152:155], v[184:187], v[124:127]
	v_mfma_f32_16x16x32_bf16 v[120:123], v[160:163], v[184:187], v[120:123]
	v_mfma_f32_16x16x32_bf16 v[108:111], v[152:155], v[192:195], v[108:111]
	v_mfma_f32_16x16x32_bf16 v[104:107], v[160:163], v[192:195], v[104:107]
	v_mfma_f32_16x16x32_bf16 v[92:95], v[152:155], v[200:203], v[92:95]
	v_mfma_f32_16x16x32_bf16 v[88:91], v[160:163], v[200:203], v[88:91]
	v_mfma_f32_16x16x32_bf16 v[76:79], v[152:155], v[210:213], v[76:79]
	v_mfma_f32_16x16x32_bf16 v[72:75], v[160:163], v[210:213], v[72:75]
	v_mfma_f32_16x16x32_bf16 v[124:127], v[156:159], v[188:191], v[124:127]
	v_mfma_f32_16x16x32_bf16 v[120:123], v[164:167], v[188:191], v[120:123]
	v_mfma_f32_16x16x32_bf16 v[108:111], v[156:159], v[196:199], v[108:111]
	v_mfma_f32_16x16x32_bf16 v[104:107], v[164:167], v[196:199], v[104:107]
	v_mfma_f32_16x16x32_bf16 v[92:95], v[156:159], v[204:207], v[92:95]
	v_mfma_f32_16x16x32_bf16 v[88:91], v[164:167], v[204:207], v[88:91]
	v_mfma_f32_16x16x32_bf16 v[76:79], v[156:159], v[214:217], v[76:79]
	v_mfma_f32_16x16x32_bf16 v[72:75], v[164:167], v[214:217], v[72:75]
	s_setprio 0
	s_setprio 1
	v_mfma_f32_16x16x32_bf16 v[116:119], v[168:171], v[184:187], v[116:119]
	v_mfma_f32_16x16x32_bf16 v[112:115], v[176:179], v[184:187], v[112:115]
	v_mfma_f32_16x16x32_bf16 v[100:103], v[168:171], v[192:195], v[100:103]
	v_mfma_f32_16x16x32_bf16 v[96:99], v[176:179], v[192:195], v[96:99]
	v_mfma_f32_16x16x32_bf16 v[84:87], v[168:171], v[200:203], v[84:87]
	v_mfma_f32_16x16x32_bf16 v[80:83], v[176:179], v[200:203], v[80:83]
	v_mfma_f32_16x16x32_bf16 v[68:71], v[168:171], v[210:213], v[68:71]
	v_mfma_f32_16x16x32_bf16 v[64:67], v[176:179], v[210:213], v[64:67]
	v_mfma_f32_16x16x32_bf16 v[116:119], v[172:175], v[188:191], v[116:119]
	v_mfma_f32_16x16x32_bf16 v[112:115], v[180:183], v[188:191], v[112:115]
	v_mfma_f32_16x16x32_bf16 v[100:103], v[172:175], v[196:199], v[100:103]
	v_mfma_f32_16x16x32_bf16 v[96:99], v[180:183], v[196:199], v[96:99]
	v_mfma_f32_16x16x32_bf16 v[84:87], v[172:175], v[204:207], v[84:87]
	v_mfma_f32_16x16x32_bf16 v[80:83], v[180:183], v[204:207], v[80:83]
	v_mfma_f32_16x16x32_bf16 v[68:71], v[172:175], v[214:217], v[68:71]
	v_mfma_f32_16x16x32_bf16 v[64:67], v[180:183], v[214:217], v[64:67]
	s_setprio 0
	s_barrier
	s_add_i32 s48, s76, s55
	v_lshl_add_u64 v[144:145], v[144:145], 0, s[12:13]
	s_mov_b32 m0, s48
	ds_read_b128 v[184:187], v151 offset:49152
	ds_read_b128 v[188:191], v151 offset:50176
	ds_read_b128 v[192:195], v151 offset:51200
	ds_read_b128 v[196:199], v151 offset:52224
	ds_read_b128 v[200:203], v151 offset:53248
	ds_read_b128 v[204:207], v151 offset:54272
	ds_read_b128 v[210:213], v151 offset:55296
	ds_read_b128 v[214:217], v151 offset:56320
	global_load_lds_dwordx4 v[144:145], off
	s_add_i32 m0, s48, 0x2000
	s_add_u32 s46, s46, 0x40080
	v_lshl_add_u64 v[144:145], v[218:219], 0, s[12:13]
	s_addc_u32 s47, s47, 0
	s_add_i32 s48, s77, s55
	global_load_lds_dwordx4 v[144:145], off
	v_lshl_add_u64 v[144:145], s[46:47], 0, v[130:131]
	s_mov_b32 m0, s48
	s_nop 0
	global_load_lds_dwordx4 v[144:145], off
	v_lshl_add_u64 v[144:145], s[46:47], 0, v[134:135]
	s_add_i32 m0, s48, 0x2000
	s_nop 0
	global_load_lds_dwordx4 v[144:145], off
	v_lshl_add_u64 v[144:145], v[220:221], 0, s[12:13]
	s_mov_b32 m0, s60
	s_nop 0
	global_load_lds_dwordx4 v[144:145], off
	v_lshl_add_u64 v[144:145], v[222:223], 0, s[12:13]
	s_mov_b32 m0, s61
	s_nop 0
	global_load_lds_dwordx4 v[144:145], off
	s_waitcnt vmcnt(8)
	s_waitcnt lgkmcnt(0)
	s_setprio 1
	s_barrier
	v_mfma_f32_16x16x32_bf16 v[60:63], v[152:155], v[184:187], v[60:63]
	v_mfma_f32_16x16x32_bf16 v[56:59], v[160:163], v[184:187], v[56:59]
	v_mfma_f32_16x16x32_bf16 v[44:47], v[152:155], v[192:195], v[44:47]
	v_mfma_f32_16x16x32_bf16 v[40:43], v[160:163], v[192:195], v[40:43]
	v_mfma_f32_16x16x32_bf16 v[28:31], v[152:155], v[200:203], v[28:31]
	v_mfma_f32_16x16x32_bf16 v[24:27], v[160:163], v[200:203], v[24:27]
	v_mfma_f32_16x16x32_bf16 v[12:15], v[152:155], v[210:213], v[12:15]
	v_mfma_f32_16x16x32_bf16 v[8:11], v[160:163], v[210:213], v[8:11]
	v_mfma_f32_16x16x32_bf16 v[60:63], v[156:159], v[188:191], v[60:63]
	v_mfma_f32_16x16x32_bf16 v[56:59], v[164:167], v[188:191], v[56:59]
	v_mfma_f32_16x16x32_bf16 v[44:47], v[156:159], v[196:199], v[44:47]
	v_mfma_f32_16x16x32_bf16 v[40:43], v[164:167], v[196:199], v[40:43]
	v_mfma_f32_16x16x32_bf16 v[28:31], v[156:159], v[204:207], v[28:31]
	v_mfma_f32_16x16x32_bf16 v[24:27], v[164:167], v[204:207], v[24:27]
	v_mfma_f32_16x16x32_bf16 v[12:15], v[156:159], v[214:217], v[12:15]
	v_mfma_f32_16x16x32_bf16 v[8:11], v[164:167], v[214:217], v[8:11]
	s_setprio 0
	s_setprio 1
	v_mfma_f32_16x16x32_bf16 v[52:55], v[168:171], v[184:187], v[52:55]
	v_mfma_f32_16x16x32_bf16 v[48:51], v[176:179], v[184:187], v[48:51]
	v_mfma_f32_16x16x32_bf16 v[36:39], v[168:171], v[192:195], v[36:39]
	v_mfma_f32_16x16x32_bf16 v[32:35], v[176:179], v[192:195], v[32:35]
	v_mfma_f32_16x16x32_bf16 v[20:23], v[168:171], v[200:203], v[20:23]
	v_mfma_f32_16x16x32_bf16 v[16:19], v[176:179], v[200:203], v[16:19]
	v_mfma_f32_16x16x32_bf16 v[4:7], v[168:171], v[210:213], v[4:7]
	v_mfma_f32_16x16x32_bf16 v[0:3], v[176:179], v[210:213], v[0:3]
	v_mfma_f32_16x16x32_bf16 v[52:55], v[172:175], v[188:191], v[52:55]
	v_mfma_f32_16x16x32_bf16 v[48:51], v[180:183], v[188:191], v[48:51]
	v_mfma_f32_16x16x32_bf16 v[36:39], v[172:175], v[196:199], v[36:39]
	v_mfma_f32_16x16x32_bf16 v[32:35], v[180:183], v[196:199], v[32:35]
	v_mfma_f32_16x16x32_bf16 v[20:23], v[172:175], v[204:207], v[20:23]
	v_mfma_f32_16x16x32_bf16 v[16:19], v[180:183], v[204:207], v[16:19]
	v_mfma_f32_16x16x32_bf16 v[4:7], v[172:175], v[214:217], v[4:7]
	v_mfma_f32_16x16x32_bf16 v[0:3], v[180:183], v[214:217], v[0:3]
	s_setprio 0
	s_barrier
	s_add_i32 s75, s75, 2
	s_add_u32 s44, s44, 0x100
	s_addc_u32 s45, s45, 0
	s_add_u32 s73, s73, 0x100
	s_addc_u32 s74, s74, 0
	s_cmp_gt_u32 s75, 13
	s_cbranch_scc0 .LBB0_1322
	s_and_b64 vcc, exec, s[14:15]
	s_cbranch_vccz .LBB0_1325
	s_barrier

.LBB0_1402:
	ds_read_b128 v[144:147], v155
	ds_read_b128 v[148:151], v155 offset:1024
	ds_read_b128 v[160:163], v155 offset:2048
	ds_read_b128 v[164:167], v155 offset:3072
	ds_read_b128 v[168:171], v156
	ds_read_b128 v[172:175], v156 offset:1024
	ds_read_b128 v[176:179], v156 offset:2048
	ds_read_b128 v[180:183], v156 offset:3072
	s_add_u32 s42, s40, 0xfff00080
	s_addc_u32 s43, s41, -1
	s_cmp_eq_u32 s63, 60
	s_cselect_b32 s45, s31, s43
	s_cselect_b32 s44, s59, s42
	s_cselect_b32 s43, s27, s62
	s_cselect_b32 s42, s60, s61
	v_lshl_add_u64 v[216:217], s[40:41], 0, v[136:137]
	s_add_i32 m0, s39, 0xc000
	ds_read_b128 v[184:187], v157
	ds_read_b128 v[188:191], v157 offset:1024
	ds_read_b128 v[192:195], v157 offset:2048
	ds_read_b128 v[196:199], v157 offset:3072
	ds_read_b128 v[200:203], v157 offset:4096
	ds_read_b128 v[204:207], v157 offset:5120
	ds_read_b128 v[208:211], v157 offset:6144
	ds_read_b128 v[212:215], v157 offset:7168
	global_load_lds_dwordx4 v[216:217], off
	v_lshl_add_u64 v[216:217], s[40:41], 0, v[138:139]
	s_add_i32 m0, s39, 0xe000
	s_nop 0
	global_load_lds_dwordx4 v[216:217], off
	s_waitcnt vmcnt(8)
	s_waitcnt lgkmcnt(0)
	s_setprio 1
	s_barrier
	v_mfma_f32_16x16x32_bf16 v[120:123], v[144:147], v[184:187], v[120:123]
	v_mfma_f32_16x16x32_bf16 v[124:127], v[160:163], v[184:187], v[124:127]
	v_mfma_f32_16x16x32_bf16 v[104:107], v[144:147], v[192:195], v[104:107]
	v_mfma_f32_16x16x32_bf16 v[108:111], v[160:163], v[192:195], v[108:111]
	v_mfma_f32_16x16x32_bf16 v[88:91], v[144:147], v[200:203], v[88:91]
	v_mfma_f32_16x16x32_bf16 v[92:95], v[160:163], v[200:203], v[92:95]
	v_mfma_f32_16x16x32_bf16 v[72:75], v[144:147], v[208:211], v[72:75]
	v_mfma_f32_16x16x32_bf16 v[76:79], v[160:163], v[208:211], v[76:79]
	v_mfma_f32_16x16x32_bf16 v[120:123], v[148:151], v[188:191], v[120:123]
	v_mfma_f32_16x16x32_bf16 v[124:127], v[164:167], v[188:191], v[124:127]
	v_mfma_f32_16x16x32_bf16 v[104:107], v[148:151], v[196:199], v[104:107]
	v_mfma_f32_16x16x32_bf16 v[108:111], v[164:167], v[196:199], v[108:111]
	v_mfma_f32_16x16x32_bf16 v[88:91], v[148:151], v[204:207], v[88:91]
	v_mfma_f32_16x16x32_bf16 v[92:95], v[164:167], v[204:207], v[92:95]
	v_mfma_f32_16x16x32_bf16 v[72:75], v[148:151], v[212:215], v[72:75]
	v_mfma_f32_16x16x32_bf16 v[76:79], v[164:167], v[212:215], v[76:79]
	s_setprio 0
	s_setprio 1
	v_mfma_f32_16x16x32_bf16 v[116:119], v[168:171], v[184:187], v[116:119]
	v_mfma_f32_16x16x32_bf16 v[112:115], v[176:179], v[184:187], v[112:115]
	v_mfma_f32_16x16x32_bf16 v[100:103], v[168:171], v[192:195], v[100:103]
	v_mfma_f32_16x16x32_bf16 v[96:99], v[176:179], v[192:195], v[96:99]
	v_mfma_f32_16x16x32_bf16 v[84:87], v[168:171], v[200:203], v[84:87]
	v_mfma_f32_16x16x32_bf16 v[80:83], v[176:179], v[200:203], v[80:83]
	v_mfma_f32_16x16x32_bf16 v[68:71], v[168:171], v[208:211], v[68:71]
	v_mfma_f32_16x16x32_bf16 v[64:67], v[176:179], v[208:211], v[64:67]
	v_mfma_f32_16x16x32_bf16 v[116:119], v[172:175], v[188:191], v[116:119]
	v_mfma_f32_16x16x32_bf16 v[112:115], v[180:183], v[188:191], v[112:115]
	v_mfma_f32_16x16x32_bf16 v[100:103], v[172:175], v[196:199], v[100:103]
	v_mfma_f32_16x16x32_bf16 v[96:99], v[180:183], v[196:199], v[96:99]
	v_mfma_f32_16x16x32_bf16 v[84:87], v[172:175], v[204:207], v[84:87]
	v_mfma_f32_16x16x32_bf16 v[80:83], v[180:183], v[204:207], v[80:83]
	v_mfma_f32_16x16x32_bf16 v[68:71], v[172:175], v[212:215], v[68:71]
	v_mfma_f32_16x16x32_bf16 v[64:67], v[180:183], v[212:215], v[64:67]
	s_setprio 0
	s_barrier
	s_add_i32 s64, s56, s48
	v_lshl_add_u64 v[216:217], s[42:43], 0, v[130:131]
	s_mov_b32 m0, s64
	ds_read_b128 v[184:187], v157 offset:16384
	ds_read_b128 v[188:191], v157 offset:17408
	ds_read_b128 v[192:195], v157 offset:18432
	ds_read_b128 v[196:199], v157 offset:19456
	ds_read_b128 v[200:203], v157 offset:20480
	ds_read_b128 v[204:207], v157 offset:21504
	ds_read_b128 v[208:211], v157 offset:22528
	ds_read_b128 v[212:215], v157 offset:23552
	global_load_lds_dwordx4 v[216:217], off
	s_add_i32 m0, s64, 0x2000
	s_add_u32 s64, s42, 0x100000
	v_lshl_add_u64 v[218:219], s[42:43], 0, v[134:135]
	s_addc_u32 s65, s43, 0
	s_add_i32 s66, s57, s48
	global_load_lds_dwordx4 v[218:219], off
	v_lshl_add_u64 v[220:221], s[64:65], 0, v[130:131]
	s_mov_b32 m0, s66
	v_lshl_add_u64 v[222:223], s[44:45], 0, v[132:133]
	global_load_lds_dwordx4 v[220:221], off
	v_lshl_add_u64 v[220:221], s[64:65], 0, v[134:135]
	s_add_i32 m0, s66, 0x2000
	s_nop 0
	global_load_lds_dwordx4 v[220:221], off
	v_lshl_add_u64 v[220:221], s[44:45], 0, v[128:129]
	s_mov_b32 m0, s39
	s_nop 0
	global_load_lds_dwordx4 v[220:221], off
	s_mov_b32 m0, s49
	s_nop 0
	global_load_lds_dwordx4 v[222:223], off
	s_waitcnt vmcnt(8)
	s_waitcnt lgkmcnt(0)
	s_setprio 1
	s_barrier
	v_mfma_f32_16x16x32_bf16 v[56:59], v[144:147], v[184:187], v[56:59]
	v_mfma_f32_16x16x32_bf16 v[60:63], v[160:163], v[184:187], v[60:63]
	v_mfma_f32_16x16x32_bf16 v[40:43], v[144:147], v[192:195], v[40:43]
	v_mfma_f32_16x16x32_bf16 v[44:47], v[160:163], v[192:195], v[44:47]
	v_mfma_f32_16x16x32_bf16 v[24:27], v[144:147], v[200:203], v[24:27]
	v_mfma_f32_16x16x32_bf16 v[28:31], v[160:163], v[200:203], v[28:31]
	v_mfma_f32_16x16x32_bf16 v[8:11], v[144:147], v[208:211], v[8:11]
	v_mfma_f32_16x16x32_bf16 v[12:15], v[160:163], v[208:211], v[12:15]
	v_mfma_f32_16x16x32_bf16 v[56:59], v[148:151], v[188:191], v[56:59]
	v_mfma_f32_16x16x32_bf16 v[60:63], v[164:167], v[188:191], v[60:63]
	v_mfma_f32_16x16x32_bf16 v[40:43], v[148:151], v[196:199], v[40:43]
	v_mfma_f32_16x16x32_bf16 v[44:47], v[164:167], v[196:199], v[44:47]
	v_mfma_f32_16x16x32_bf16 v[24:27], v[148:151], v[204:207], v[24:27]
	v_mfma_f32_16x16x32_bf16 v[28:31], v[164:167], v[204:207], v[28:31]
	v_mfma_f32_16x16x32_bf16 v[8:11], v[148:151], v[212:215], v[8:11]
	v_mfma_f32_16x16x32_bf16 v[12:15], v[164:167], v[212:215], v[12:15]
	s_setprio 0
	s_setprio 1
	v_mfma_f32_16x16x32_bf16 v[52:55], v[168:171], v[184:187], v[52:55]
	v_mfma_f32_16x16x32_bf16 v[48:51], v[176:179], v[184:187], v[48:51]
	v_mfma_f32_16x16x32_bf16 v[36:39], v[168:171], v[192:195], v[36:39]
	v_mfma_f32_16x16x32_bf16 v[32:35], v[176:179], v[192:195], v[32:35]
	v_mfma_f32_16x16x32_bf16 v[20:23], v[168:171], v[200:203], v[20:23]
	v_mfma_f32_16x16x32_bf16 v[16:19], v[176:179], v[200:203], v[16:19]
	v_mfma_f32_16x16x32_bf16 v[4:7], v[168:171], v[208:211], v[4:7]
	v_mfma_f32_16x16x32_bf16 v[0:3], v[176:179], v[208:211], v[0:3]
	v_mfma_f32_16x16x32_bf16 v[52:55], v[172:175], v[188:191], v[52:55]
	v_mfma_f32_16x16x32_bf16 v[48:51], v[180:183], v[188:191], v[48:51]
	v_mfma_f32_16x16x32_bf16 v[36:39], v[172:175], v[196:199], v[36:39]
	v_mfma_f32_16x16x32_bf16 v[32:35], v[180:183], v[196:199], v[32:35]
	v_mfma_f32_16x16x32_bf16 v[20:23], v[172:175], v[204:207], v[20:23]
	v_mfma_f32_16x16x32_bf16 v[16:19], v[180:183], v[204:207], v[16:19]
	v_mfma_f32_16x16x32_bf16 v[4:7], v[172:175], v[212:215], v[4:7]
	v_mfma_f32_16x16x32_bf16 v[0:3], v[180:183], v[212:215], v[0:3]
	s_setprio 0
	s_barrier
	s_add_i32 s64, 0, 0x18000
	v_add_u32_e32 v159, s64, v153
	s_add_i32 s65, 0, 0x1c000
	ds_read_b128 v[144:147], v159
	ds_read_b128 v[148:151], v159 offset:1024
	ds_read_b128 v[160:163], v159 offset:2048
	ds_read_b128 v[164:167], v159 offset:3072
	v_add_u32_e32 v159, s65, v153
	ds_read_b128 v[168:171], v159
	ds_read_b128 v[172:175], v159 offset:1024
	ds_read_b128 v[176:179], v159 offset:2048
	ds_read_b128 v[180:183], v159 offset:3072
	s_add_u32 s44, s44, 0x100000
	s_addc_u32 s45, s45, 0
	s_mov_b32 m0, s50
	v_lshl_add_u64 v[224:225], s[44:45], 0, v[128:129]
	ds_read_b128 v[184:187], v157 offset:32768
	ds_read_b128 v[188:191], v157 offset:33792
	ds_read_b128 v[192:195], v157 offset:34816
	ds_read_b128 v[196:199], v157 offset:35840
	ds_read_b128 v[200:203], v157 offset:36864
	ds_read_b128 v[204:207], v157 offset:37888
	ds_read_b128 v[208:211], v157 offset:38912
	ds_read_b128 v[212:215], v157 offset:39936
	global_load_lds_dwordx4 v[224:225], off
	v_lshl_add_u64 v[224:225], s[44:45], 0, v[132:133]
	s_mov_b32 m0, s51
	s_nop 0
	global_load_lds_dwordx4 v[224:225], off
	s_waitcnt vmcnt(8)
	s_waitcnt lgkmcnt(0)
	s_setprio 1
	s_barrier
	v_mfma_f32_16x16x32_bf16 v[120:123], v[144:147], v[184:187], v[120:123]
	v_mfma_f32_16x16x32_bf16 v[124:127], v[160:163], v[184:187], v[124:127]
	v_mfma_f32_16x16x32_bf16 v[104:107], v[144:147], v[192:195], v[104:107]
	v_mfma_f32_16x16x32_bf16 v[108:111], v[160:163], v[192:195], v[108:111]
	v_mfma_f32_16x16x32_bf16 v[88:91], v[144:147], v[200:203], v[88:91]
	v_mfma_f32_16x16x32_bf16 v[92:95], v[160:163], v[200:203], v[92:95]
	v_mfma_f32_16x16x32_bf16 v[72:75], v[144:147], v[208:211], v[72:75]
	v_mfma_f32_16x16x32_bf16 v[76:79], v[160:163], v[208:211], v[76:79]
	v_mfma_f32_16x16x32_bf16 v[120:123], v[148:151], v[188:191], v[120:123]
	v_mfma_f32_16x16x32_bf16 v[124:127], v[164:167], v[188:191], v[124:127]
	v_mfma_f32_16x16x32_bf16 v[104:107], v[148:151], v[196:199], v[104:107]
	v_mfma_f32_16x16x32_bf16 v[108:111], v[164:167], v[196:199], v[108:111]
	v_mfma_f32_16x16x32_bf16 v[88:91], v[148:151], v[204:207], v[88:91]
	v_mfma_f32_16x16x32_bf16 v[92:95], v[164:167], v[204:207], v[92:95]
	v_mfma_f32_16x16x32_bf16 v[72:75], v[148:151], v[212:215], v[72:75]
	v_mfma_f32_16x16x32_bf16 v[76:79], v[164:167], v[212:215], v[76:79]
	s_setprio 0
	s_setprio 1
	v_mfma_f32_16x16x32_bf16 v[116:119], v[168:171], v[184:187], v[116:119]
	v_mfma_f32_16x16x32_bf16 v[112:115], v[176:179], v[184:187], v[112:115]
	v_mfma_f32_16x16x32_bf16 v[100:103], v[168:171], v[192:195], v[100:103]
	v_mfma_f32_16x16x32_bf16 v[96:99], v[176:179], v[192:195], v[96:99]
	v_mfma_f32_16x16x32_bf16 v[84:87], v[168:171], v[200:203], v[84:87]
	v_mfma_f32_16x16x32_bf16 v[80:83], v[176:179], v[200:203], v[80:83]
	v_mfma_f32_16x16x32_bf16 v[68:71], v[168:171], v[208:211], v[68:71]
	v_mfma_f32_16x16x32_bf16 v[64:67], v[176:179], v[208:211], v[64:67]
	v_mfma_f32_16x16x32_bf16 v[116:119], v[172:175], v[188:191], v[116:119]
	v_mfma_f32_16x16x32_bf16 v[112:115], v[180:183], v[188:191], v[112:115]
	v_mfma_f32_16x16x32_bf16 v[100:103], v[172:175], v[196:199], v[100:103]
	v_mfma_f32_16x16x32_bf16 v[96:99], v[180:183], v[196:199], v[96:99]
	v_mfma_f32_16x16x32_bf16 v[84:87], v[172:175], v[204:207], v[84:87]
	v_mfma_f32_16x16x32_bf16 v[80:83], v[180:183], v[204:207], v[80:83]
	v_mfma_f32_16x16x32_bf16 v[68:71], v[172:175], v[212:215], v[68:71]
	v_mfma_f32_16x16x32_bf16 v[64:67], v[180:183], v[212:215], v[64:67]
	s_setprio 0
	s_barrier
	s_add_i32 s44, s64, s48
	v_lshl_add_u64 v[216:217], v[216:217], 0, s[12:13]
	s_mov_b32 m0, s44
	ds_read_b128 v[184:187], v157 offset:49152
	ds_read_b128 v[188:191], v157 offset:50176
	ds_read_b128 v[192:195], v157 offset:51200
	ds_read_b128 v[196:199], v157 offset:52224
	ds_read_b128 v[200:203], v157 offset:53248
	ds_read_b128 v[204:207], v157 offset:54272
	ds_read_b128 v[208:211], v157 offset:55296
	ds_read_b128 v[212:215], v157 offset:56320
	global_load_lds_dwordx4 v[216:217], off
	s_add_i32 m0, s44, 0x2000
	s_add_u32 s42, s42, 0x100080
	v_lshl_add_u64 v[216:217], v[218:219], 0, s[12:13]
	s_addc_u32 s43, s43, 0
	s_add_i32 s44, s65, s48
	global_load_lds_dwordx4 v[216:217], off
	v_lshl_add_u64 v[216:217], s[42:43], 0, v[130:131]
	s_mov_b32 m0, s44
	s_nop 0
	global_load_lds_dwordx4 v[216:217], off
	v_lshl_add_u64 v[216:217], s[42:43], 0, v[134:135]
	s_add_i32 m0, s44, 0x2000
	s_nop 0
	global_load_lds_dwordx4 v[216:217], off
	v_lshl_add_u64 v[216:217], v[220:221], 0, s[12:13]
	s_mov_b32 m0, s53
	s_nop 0
	global_load_lds_dwordx4 v[216:217], off
	v_lshl_add_u64 v[216:217], v[222:223], 0, s[12:13]
	s_mov_b32 m0, s54
	s_nop 0
	global_load_lds_dwordx4 v[216:217], off
	s_waitcnt vmcnt(8)
	s_waitcnt lgkmcnt(0)
	s_setprio 1
	s_barrier
	v_mfma_f32_16x16x32_bf16 v[56:59], v[144:147], v[184:187], v[56:59]
	v_mfma_f32_16x16x32_bf16 v[60:63], v[160:163], v[184:187], v[60:63]
	v_mfma_f32_16x16x32_bf16 v[40:43], v[144:147], v[192:195], v[40:43]
	v_mfma_f32_16x16x32_bf16 v[44:47], v[160:163], v[192:195], v[44:47]
	v_mfma_f32_16x16x32_bf16 v[24:27], v[144:147], v[200:203], v[24:27]
	v_mfma_f32_16x16x32_bf16 v[28:31], v[160:163], v[200:203], v[28:31]
	v_mfma_f32_16x16x32_bf16 v[8:11], v[144:147], v[208:211], v[8:11]
	v_mfma_f32_16x16x32_bf16 v[12:15], v[160:163], v[208:211], v[12:15]
	v_mfma_f32_16x16x32_bf16 v[56:59], v[148:151], v[188:191], v[56:59]
	v_mfma_f32_16x16x32_bf16 v[60:63], v[164:167], v[188:191], v[60:63]
	v_mfma_f32_16x16x32_bf16 v[40:43], v[148:151], v[196:199], v[40:43]
	v_mfma_f32_16x16x32_bf16 v[44:47], v[164:167], v[196:199], v[44:47]
	v_mfma_f32_16x16x32_bf16 v[24:27], v[148:151], v[204:207], v[24:27]
	v_mfma_f32_16x16x32_bf16 v[28:31], v[164:167], v[204:207], v[28:31]
	v_mfma_f32_16x16x32_bf16 v[8:11], v[148:151], v[212:215], v[8:11]
	v_mfma_f32_16x16x32_bf16 v[12:15], v[164:167], v[212:215], v[12:15]
	s_setprio 0
	s_setprio 1
	v_mfma_f32_16x16x32_bf16 v[52:55], v[168:171], v[184:187], v[52:55]
	v_mfma_f32_16x16x32_bf16 v[48:51], v[176:179], v[184:187], v[48:51]
	v_mfma_f32_16x16x32_bf16 v[36:39], v[168:171], v[192:195], v[36:39]
	v_mfma_f32_16x16x32_bf16 v[32:35], v[176:179], v[192:195], v[32:35]
	v_mfma_f32_16x16x32_bf16 v[20:23], v[168:171], v[200:203], v[20:23]
	v_mfma_f32_16x16x32_bf16 v[16:19], v[176:179], v[200:203], v[16:19]
	v_mfma_f32_16x16x32_bf16 v[4:7], v[168:171], v[208:211], v[4:7]
	v_mfma_f32_16x16x32_bf16 v[0:3], v[176:179], v[208:211], v[0:3]
	v_mfma_f32_16x16x32_bf16 v[52:55], v[172:175], v[188:191], v[52:55]
	v_mfma_f32_16x16x32_bf16 v[48:51], v[180:183], v[188:191], v[48:51]
	v_mfma_f32_16x16x32_bf16 v[36:39], v[172:175], v[196:199], v[36:39]
	v_mfma_f32_16x16x32_bf16 v[32:35], v[180:183], v[196:199], v[32:35]
	v_mfma_f32_16x16x32_bf16 v[20:23], v[172:175], v[204:207], v[20:23]
	v_mfma_f32_16x16x32_bf16 v[16:19], v[180:183], v[204:207], v[16:19]
	v_mfma_f32_16x16x32_bf16 v[4:7], v[172:175], v[212:215], v[4:7]
	v_mfma_f32_16x16x32_bf16 v[0:3], v[180:183], v[212:215], v[0:3]
	s_setprio 0
	s_barrier
	s_add_i32 s63, s63, 2
	s_add_u32 s40, s40, 0x100
	s_addc_u32 s41, s41, 0
	s_add_u32 s61, s61, 0x100
	s_addc_u32 s62, s62, 0
	s_cmp_gt_u32 s63, 61
	s_cbranch_scc0 .LBB0_1402
	s_and_b64 vcc, exec, s[16:17]
	s_cbranch_vccz .LBB0_1405
	s_barrier
